# M-split of the 16-unit tail round in out-proj (P12,P20) and GLU (P19) GEMM phases: WG pairs share a tile, skip other half MMA blocks, exec-masked stores
# baseline (speedup 1.0000x reference)
; #define PG8_STAGE(bufoff, gbase, voff) do { _Pragma("unroll") for (int _i = 0; _i < 2; ++_i) \
;         __builtin_amdgcn_global_load_lds((const unsigned*)((const char*)(gbase) + (voff)[_i]), (PG8_LAS unsigned*)(lds + (bufoff) + ldsw + _i * 8192), 16, 0, 0); } while (0)
; #define PG8_WAIT_V(n) asm volatile("s_waitcnt vmcnt(" #n ")" ::: "memory")
; #define PG8_BAR __builtin_amdgcn_s_barrier()
;     __device__ __forceinline__ bf16* R(int i) const { return (bf16*)(ws + OFF_R0 + (size_t)i * RSZ); }
; template <class Epi, class Sched, bool ALIGN_EPI = false, bool SP2 = false>
; __device__ __forceinline__ void gemm_phase(PG8_LAS unsigned char* lds, const Gemm g, const Sched& S, const Epi& E) {
;     const int tid = threadIdx.x, wid = __builtin_amdgcn_readfirstlane(tid >> 6), lane = tid & 63, wr = wid >> 2, wc = wid & 3, fr = lane & 15, fq = lane >> 4;
;     const int K = g.K, nt = K / BK;
;     unsigned voffA[2], voffB[2];
; #pragma unroll
;     for (int i = 0; i < 2; ++i) { int R, C; stage_rc(tid * 16 + i * 8192, R, C); const int Rb = Epi::PERM ? ((R & ~31) + perm32(R & 31)) : R;
;         voffA[i] = (unsigned)(R * K + C) * 2u; voffB[i] = (unsigned)(Rb * K + C) * 2u; }
;     const size_t kstep = (size_t)(BK * 2);
;     const size_t hstep = (size_t)HALF * K * 2;
;     const size_t tstep = 2 * hstep;
;     const unsigned ldsw = (unsigned)wid * 1024u;
;     const int aoff = lds_byte(wr * 64 + fr, fq * 8), boff = lds_byte(wc * 32 + fr, fq * 8);
;     ...
;     Unit cur, nxt; int ui = 0;
;     if (!S.next(0, cur)) return;
;     f32x4 acc[2][2][4][2];
; #pragma unroll
;     for (int a = 0; a < 2; ++a)
; #pragma unroll
;         for (int b = 0; b < 2; ++b)
; #pragma unroll
;             for (int m = 0; m < 4; ++m)
; #pragma unroll
;                 for (int n = 0; n < 2; ++n) acc[a][b][m][n] = (f32x4){0.f, 0.f, 0.f, 0.f};
;     bf16x8 At[4][2], B0[2][2], B1[2][2];
;     const char* cA = (const char*)g.A + (size_t)cur.pm * tstep; const char* cB = (const char*)g.Bt + (size_t)cur.pn * tstep;
;     S.a_ready(cur);
;     if constexpr (SP2) {
;         PG8_STAGE(PG8_SB(0, 0), cB, voffB); PG8_STAGE(PG8_SB(0, 1), cB + hstep, voffB); PG8_STAGE(PG8_SA(0, 0), cA, voffA); PG8_STAGE(PG8_SA(0, 1), cA + hstep, voffA);
;         if (wr == 1) PG8_BAR;
;         PG8_WAIT_V(2); PG8_BAR;
.LBB0_1256:
	s_mov_b32 s92, 2
	s_mov_b64 s[88:89], -1
	s_mov_b64 s[90:91], -1
	s_cmp_lt_i32 s34, 13
	s_cselect_b64 s[6:7], -1, 0
	s_cmp_gt_i32 s35, 12
	s_cselect_b64 s[8:9], -1, 0
	s_and_b64 s[6:7], s[6:7], s[8:9]
	s_andn2_b64 vcc, exec, s[6:7]
	s_cbranch_vccnz .LBB0_1278
	s_lshl_b32 s3, s2, 5
	s_and_b32 s3, s3, 0xe0
	s_ashr_i32 s6, s2, 3
	s_add_i32 s3, s3, s6
	s_cmpk_eq_i32 s30, 0x100
	s_cselect_b32 s3, s3, s2
	s_cmpk_gt_i32 s30, 0x110
	s_cselect_b32 s6, s2, s3
	s_movk_i32 s7, 0xe0
	v_readfirstlane_b32 s14, v128
	s_cmpk_gt_i32 s6, 0x10f
	v_lshlrev_b32_e32 v129, 2, v128
	s_cbranch_scc1 .LBB0_1273
	v_lshrrev_b32_e32 v0, 5, v128
	v_lshrrev_b32_e32 v2, 1, v128
	v_and_b32_e32 v0, 4, v0
	v_bfe_u32 v1, v128, 2, 2
	v_and_b32_e32 v11, 24, v2
	v_or3_b32 v0, v0, v1, v11
	v_lshlrev_b32_e32 v1, 4, v128
	v_add_u32_e32 v8, 0x2000, v1
	v_lshrrev_b32_e32 v2, 7, v8
	v_and_b32_e32 v4, 32, v128
	v_and_or_b32 v3, v2, s7, v0
	v_bitop3_b32 v9, v1, v4, 48 bitop3:0x6c
	v_and_b32_e32 v10, 64, v128
	v_bfe_u32 v12, v128, 2, 4
	s_movk_i32 s7, 0xf0
	s_add_u32 s52, s26, 0xbc00000
	v_or_b32_e32 v1, v9, v10
	v_and_or_b32 v2, v2, s7, v12
	s_addc_u32 s53, s27, 0
	v_lshl_or_b32 v138, v2, 11, v1
	v_lshrrev_b32_e32 v2, 3, v128
	s_movk_i32 s7, 0x60
	s_add_u32 s54, s26, 0xfa00000
	v_and_or_b32 v0, v2, s7, v0
	s_movk_i32 s7, 0x70
	s_addc_u32 s55, s27, 0
	v_lshl_or_b32 v140, v0, 11, v1
	v_and_or_b32 v0, v2, s7, v12
	s_ashr_i32 s7, s6, 31
	s_lshr_b32 s7, s7, 30
	s_add_i32 s7, s6, s7
	s_ashr_i32 s42, s7, 2
	s_and_b32 s7, s7, -4
	s_sub_i32 s44, s6, s7
	s_lshr_b32 s10, s14, 6
	s_ashr_i32 s43, s42, 31
	s_ashr_i32 s45, s44, 31
	s_lshr_b32 s15, s14, 8
	s_lshl_b32 s56, s10, 10
	s_lshl_b64 s[6:7], s[42:43], 19
	s_lshl_b64 s[8:9], s[44:45], 19
	s_add_u32 s48, s54, s8
	s_addc_u32 s49, s55, s9
	s_add_i32 s43, s56, 0
	s_add_i32 m0, s43, 0x10000
	v_lshl_or_b32 v136, v3, 11, v1
	global_load_lds_dwordx4 v140, s[48:49]
	s_add_i32 m0, s43, 0x12000
	s_add_u32 s8, s48, 0x40000
	global_load_lds_dwordx4 v136, s[48:49]
	s_addc_u32 s9, s49, 0
	s_add_i32 m0, s43, 0x14000
	v_lshl_or_b32 v142, v0, 11, v1
	global_load_lds_dwordx4 v140, s[8:9]
	s_add_i32 m0, s43, 0x16000
	s_add_u32 s46, s52, s6
	s_addc_u32 s47, s53, s7
	s_add_i32 s45, s43, 0x2000
	global_load_lds_dwordx4 v136, s[8:9]
	s_mov_b32 m0, s43
	s_add_u32 s6, s46, 0x40000
	global_load_lds_dwordx4 v142, s[46:47]
	s_mov_b32 m0, s45
	s_addc_u32 s7, s47, 0
	s_add_i32 s57, s43, 0x4000
	global_load_lds_dwordx4 v138, s[46:47]
	s_mov_b32 m0, s57
	s_add_i32 s58, s43, 0x6000
	global_load_lds_dwordx4 v142, s[6:7]
	s_mov_b32 m0, s58
	v_mov_b32_e32 v141, 0
	global_load_lds_dwordx4 v138, s[6:7]
	v_mov_b32_e32 v137, v141
	v_mov_b32_e32 v143, v141
	v_mov_b32_e32 v139, v141
	s_cmp_eq_u32 s15, 1
	s_mov_b32 s59, 0
	v_lshl_add_u64 v[6:7], s[48:49], 0, v[140:141]
	v_lshl_add_u64 v[4:5], s[48:49], 0, v[136:137]
	v_lshl_add_u64 v[0:1], s[46:47], 0, v[142:143]
	s_cselect_b64 s[6:7], -1, 0
	s_cmp_lg_u32 s15, 1
	v_lshl_add_u64 v[2:3], s[46:47], 0, v[138:139]
	s_cbranch_scc1 .LBB0_1260
	s_barrier

;     __device__ __forceinline__ bool next(int i, Unit& u) const {
;         const int L = i * G + (((i + 1) * G <= n) ? c : cp); if (L >= n) return false;
;         if (mode == 0) { u.pm = L / nN; u.pn = L - u.pm * nN; }
; template <class Epi, class Sched, bool ALIGN_EPI = false, bool SP2 = false>
; __device__ __forceinline__ void gemm_phase(PG8_LAS unsigned char* lds, const Gemm g, const Sched& S, const Epi& E) {
;     ...
;         const bool has_next = S.next(ui + 1, nxt);
;         const char* nA = has_next ? (const char*)g.A + (size_t)nxt.pm * tstep : cA; const char* nB = has_next ? (const char*)g.Bt + (size_t)nxt.pn * tstep : cB;
.LBB0_1262:
	s_mov_b32 s92, s93
	s_cmp_lg_u32 s92, 1
	s_cselect_b64 s[88:89], -1, 0
	s_cmp_lg_u32 s92, 0
	s_cselect_b64 s[90:91], -1, 0
	s_andn2_b64 vcc, exec, s[22:23]
	s_mov_b32 s44, s18
	s_mov_b32 s42, s16
	s_mov_b64 s[48:49], s[24:25]
	s_mov_b64 s[46:47], s[20:21]
	s_cbranch_vccz .LBB0_1272
.LBB0_1263:
	s_add_i32 s59, s59, 1
	s_mul_i32 s17, s59, s30
	s_add_i32 s19, s17, s30
	s_cmpk_gt_i32 s19, 0x110
	s_cselect_b32 s93, 1, 0
	s_cselect_b32 s19, s2, s3
	s_add_i32 s17, s19, s17
	s_cmp_eq_u32 s93, 0
	s_mov_b32 s93, 2
	s_cbranch_scc1 .Lms9_a
	s_lshr_b32 s94, s2, 4
	s_lshl_b32 s94, s94, 3
	s_and_b32 s95, s2, 7
	s_or_b32 s94, s94, s95
	s_sub_i32 s95, s17, s2
	s_add_i32 s17, s95, s94
	s_bfe_u32 s93, s2, 0x10003
.Lms9_a:
	s_cmpk_lt_i32 s17, 0x110
	s_cselect_b64 s[22:23], -1, 0
	s_cmpk_gt_i32 s17, 0x10f
	s_cbranch_scc1 .LBB0_1265
	s_ashr_i32 s16, s17, 31
	s_lshr_b32 s16, s16, 30
	s_add_i32 s18, s17, s16
	s_ashr_i32 s16, s18, 2
	s_and_b32 s18, s18, -4
	s_sub_i32 s18, s17, s18

; #define PG8_STAGE(bufoff, gbase, voff) do { _Pragma("unroll") for (int _i = 0; _i < 2; ++_i) \
;         __builtin_amdgcn_global_load_lds((const unsigned*)((const char*)(gbase) + (voff)[_i]), (PG8_LAS unsigned*)(lds + (bufoff) + ldsw + _i * 8192), 16, 0, 0); } while (0)
; #define PG8_LDA(dst, b, h) do { _Pragma("unroll") for (int m = 0; m < 4; ++m) _Pragma("unroll") for (int k = 0; k < 2; ++k) dst[m][k] = *(const PG8_LAS bf16x8*)(lds + PG8_SA(b, h) + aoff + m * 2048 + k * 1024); } while (0)
; #define PG8_LDB(dst, b, h) do { _Pragma("unroll") for (int n = 0; n < 2; ++n) _Pragma("unroll") for (int k = 0; k < 2; ++k) dst[n][k] = *(const PG8_LAS bf16x8*)(lds + PG8_SB(b, h) + boff + n * 2048 + k * 1024); } while (0)
; #define PG8_MMA(ai, bj, At, Bt) do { __builtin_amdgcn_s_setprio(1); _Pragma("unroll") for (int m = 0; m < 4; ++m) _Pragma("unroll") for (int n = 0; n < 2; ++n) _Pragma("unroll") for (int k = 0; k < 2; ++k) \
;         acc[ai][bj][m][n] = __builtin_amdgcn_mfma_f32_16x16x32_bf16(Bt[n][k], At[m][k], acc[ai][bj][m][n], 0, 0, 0); __builtin_amdgcn_s_setprio(0); } while (0)
; #define PG8_WAIT_V(n) asm volatile("s_waitcnt vmcnt(" #n ")" ::: "memory")
; #define PG8_WAIT_L(n) asm volatile("s_waitcnt lgkmcnt(" #n ")" ::: "memory")
; #define PG8_BAR __builtin_amdgcn_s_barrier()
; #define PG8_SCHED __builtin_amdgcn_sched_barrier(0)
; template <class Epi, class Sched, bool ALIGN_EPI = false, bool SP2 = false>
; __device__ __forceinline__ void gemm_phase(PG8_LAS unsigned char* lds, const Gemm g, const Sched& S, const Epi& E) {
;     ...
;             PG8_LDB(B0, 0, 0); PG8_LDB(B1, 0, 1); PG8_SCHED; PG8_LDA(At, 0, 0); PG8_STAGE(PG8_SA(1, 1), a1 + hstep, voffA);
;             PG8_WAIT_V(8); PG8_WAIT_L(0); PG8_BAR; PG8_MMA(0, 0, At, B0); PG8_MMA(0, 1, At, B1); PG8_BAR; PG8_SCHED;
.LBB0_1266:
	ds_read_b128 v[148:151], v160
	ds_read_b128 v[164:167], v160 offset:1024
	ds_read_b128 v[168:171], v160 offset:2048
	ds_read_b128 v[172:175], v160 offset:3072
	ds_read_b128 v[176:179], v161
	ds_read_b128 v[180:183], v161 offset:1024
	ds_read_b128 v[184:187], v161 offset:2048
	ds_read_b128 v[188:191], v161 offset:3072
	s_add_u32 s48, s46, 0xfffc0080
	s_addc_u32 s49, s47, -1
	s_cmp_eq_u32 s74, 12
	s_cselect_b32 s51, s17, s49
	s_cselect_b32 s50, s70, s48
	s_cselect_b32 s49, s19, s73
	s_cselect_b32 s48, s71, s72
	s_mov_b32 m0, s69
	v_lshl_add_u64 v[224:225], s[46:47], 0, v[144:145]
	ds_read_b128 v[192:195], v162
	ds_read_b128 v[196:199], v162 offset:1024
	ds_read_b128 v[200:203], v162 offset:2048
	ds_read_b128 v[204:207], v162 offset:3072
	ds_read_b128 v[208:211], v162 offset:4096
	ds_read_b128 v[212:215], v162 offset:5120
	ds_read_b128 v[216:219], v162 offset:6144
	ds_read_b128 v[220:223], v162 offset:7168
	global_load_lds_dwordx4 v[224:225], off
	v_lshl_add_u64 v[224:225], s[46:47], 0, v[146:147]
	s_add_i32 m0, s43, 0xe000
	s_nop 0
	global_load_lds_dwordx4 v[224:225], off
	s_waitcnt vmcnt(8)
	s_waitcnt lgkmcnt(0)
	s_barrier
	s_setprio 1
	s_waitcnt lgkmcnt(0)
	s_cmp_eq_u32 s92, 1
	s_cbranch_scc1 .Lms9_b0
	v_mfma_f32_16x16x32_bf16 v[124:127], v[148:151], v[192:195], v[124:127]
	v_mfma_f32_16x16x32_bf16 v[120:123], v[168:171], v[192:195], v[120:123]
	v_mfma_f32_16x16x32_bf16 v[116:119], v[148:151], v[200:203], v[116:119]
	v_mfma_f32_16x16x32_bf16 v[104:107], v[168:171], v[200:203], v[104:107]
	v_mfma_f32_16x16x32_bf16 v[100:103], v[148:151], v[208:211], v[100:103]
	v_mfma_f32_16x16x32_bf16 v[88:91], v[168:171], v[208:211], v[88:91]
	v_mfma_f32_16x16x32_bf16 v[84:87], v[148:151], v[216:219], v[84:87]
	v_mfma_f32_16x16x32_bf16 v[72:75], v[168:171], v[216:219], v[72:75]
	v_mfma_f32_16x16x32_bf16 v[124:127], v[164:167], v[196:199], v[124:127]
	v_mfma_f32_16x16x32_bf16 v[120:123], v[172:175], v[196:199], v[120:123]
	v_mfma_f32_16x16x32_bf16 v[116:119], v[164:167], v[204:207], v[116:119]
	v_mfma_f32_16x16x32_bf16 v[104:107], v[172:175], v[204:207], v[104:107]
	v_mfma_f32_16x16x32_bf16 v[100:103], v[164:167], v[212:215], v[100:103]
	v_mfma_f32_16x16x32_bf16 v[88:91], v[172:175], v[212:215], v[88:91]
	v_mfma_f32_16x16x32_bf16 v[84:87], v[164:167], v[220:223], v[84:87]
	v_mfma_f32_16x16x32_bf16 v[72:75], v[172:175], v[220:223], v[72:75]
.Lms9_b0:
	s_setprio 0
	s_setprio 1
	s_cmp_eq_u32 s92, 1
	s_cbranch_scc1 .Lms9_b1
	v_mfma_f32_16x16x32_bf16 v[112:115], v[176:179], v[192:195], v[112:115]
	v_mfma_f32_16x16x32_bf16 v[108:111], v[184:187], v[192:195], v[108:111]
	v_mfma_f32_16x16x32_bf16 v[96:99], v[176:179], v[200:203], v[96:99]
	v_mfma_f32_16x16x32_bf16 v[92:95], v[184:187], v[200:203], v[92:95]
	v_mfma_f32_16x16x32_bf16 v[80:83], v[176:179], v[208:211], v[80:83]
	v_mfma_f32_16x16x32_bf16 v[76:79], v[184:187], v[208:211], v[76:79]
	v_mfma_f32_16x16x32_bf16 v[68:71], v[176:179], v[216:219], v[68:71]
	v_mfma_f32_16x16x32_bf16 v[64:67], v[184:187], v[216:219], v[64:67]
	v_mfma_f32_16x16x32_bf16 v[112:115], v[180:183], v[196:199], v[112:115]
	v_mfma_f32_16x16x32_bf16 v[108:111], v[188:191], v[196:199], v[108:111]
	v_mfma_f32_16x16x32_bf16 v[96:99], v[180:183], v[204:207], v[96:99]
	v_mfma_f32_16x16x32_bf16 v[92:95], v[188:191], v[204:207], v[92:95]
	v_mfma_f32_16x16x32_bf16 v[80:83], v[180:183], v[212:215], v[80:83]
	v_mfma_f32_16x16x32_bf16 v[76:79], v[188:191], v[212:215], v[76:79]
	v_mfma_f32_16x16x32_bf16 v[68:71], v[180:183], v[220:223], v[68:71]
	v_mfma_f32_16x16x32_bf16 v[64:67], v[188:191], v[220:223], v[64:67]
; #define PG8_STAGE(bufoff, gbase, voff) do { _Pragma("unroll") for (int _i = 0; _i < 2; ++_i) \
;         __builtin_amdgcn_global_load_lds((const unsigned*)((const char*)(gbase) + (voff)[_i]), (PG8_LAS unsigned*)(lds + (bufoff) + ldsw + _i * 8192), 16, 0, 0); } while (0)
; #define PG8_LDA(dst, b, h) do { _Pragma("unroll") for (int m = 0; m < 4; ++m) _Pragma("unroll") for (int k = 0; k < 2; ++k) dst[m][k] = *(const PG8_LAS bf16x8*)(lds + PG8_SA(b, h) + aoff + m * 2048 + k * 1024); } while (0)
; #define PG8_LDB(dst, b, h) do { _Pragma("unroll") for (int n = 0; n < 2; ++n) _Pragma("unroll") for (int k = 0; k < 2; ++k) dst[n][k] = *(const PG8_LAS bf16x8*)(lds + PG8_SB(b, h) + boff + n * 2048 + k * 1024); } while (0)
; #define PG8_MMA(ai, bj, At, Bt) do { __builtin_amdgcn_s_setprio(1); _Pragma("unroll") for (int m = 0; m < 4; ++m) _Pragma("unroll") for (int n = 0; n < 2; ++n) _Pragma("unroll") for (int k = 0; k < 2; ++k) \
;         acc[ai][bj][m][n] = __builtin_amdgcn_mfma_f32_16x16x32_bf16(Bt[n][k], At[m][k], acc[ai][bj][m][n], 0, 0, 0); __builtin_amdgcn_s_setprio(0); } while (0)
; #define PG8_WAIT_V(n) asm volatile("s_waitcnt vmcnt(" #n ")" ::: "memory")
; #define PG8_WAIT_L(n) asm volatile("s_waitcnt lgkmcnt(" #n ")" ::: "memory")
; #define PG8_BAR __builtin_amdgcn_s_barrier()
; #define PG8_SCHED __builtin_amdgcn_sched_barrier(0)
; template <class Epi, class Sched, bool ALIGN_EPI = false, bool SP2 = false>
; __device__ __forceinline__ void gemm_phase(PG8_LAS unsigned char* lds, const Gemm g, const Sched& S, const Epi& E) {
;     ...
;             PG8_LDA(At, 0, 1); PG8_STAGE(PG8_SB(0, 0), b2, voffB); PG8_STAGE(PG8_SB(0, 1), b2 + hstep, voffB); PG8_STAGE(PG8_SA(0, 0), a2, voffA);
;             PG8_WAIT_V(8); PG8_WAIT_L(0); PG8_BAR; PG8_MMA(1, 0, At, B0); PG8_MMA(1, 1, At, B1); PG8_BAR; PG8_SCHED;
;             PG8_LDB(B0, 1, 0); PG8_LDB(B1, 1, 1); PG8_SCHED; PG8_LDA(At, 1, 0); PG8_STAGE(PG8_SA(0, 1), a2 + hstep, voffA);
;             PG8_WAIT_V(8); PG8_WAIT_L(0); PG8_BAR; PG8_MMA(0, 0, At, B0); PG8_MMA(0, 1, At, B1); PG8_BAR; PG8_SCHED;
.Lms9_b1:
	s_setprio 0
	s_barrier
	s_add_i32 s75, s64, s56
	v_lshl_add_u64 v[224:225], s[48:49], 0, v[140:141]
	s_mov_b32 m0, s75
	ds_read_b128 v[192:195], v162 offset:16384
	ds_read_b128 v[196:199], v162 offset:17408
	ds_read_b128 v[200:203], v162 offset:18432
	ds_read_b128 v[204:207], v162 offset:19456
	ds_read_b128 v[208:211], v162 offset:20480
	ds_read_b128 v[212:215], v162 offset:21504
	ds_read_b128 v[216:219], v162 offset:22528
	ds_read_b128 v[220:223], v162 offset:23552
	global_load_lds_dwordx4 v[224:225], off
	s_add_i32 m0, s75, 0x2000
	s_add_u32 s76, s48, 0x40000
	v_lshl_add_u64 v[226:227], s[48:49], 0, v[136:137]
	s_addc_u32 s77, s49, 0
	s_add_i32 s75, s65, s56
	global_load_lds_dwordx4 v[226:227], off
	v_lshl_add_u64 v[228:229], s[76:77], 0, v[140:141]
	s_mov_b32 m0, s75
	v_lshl_add_u64 v[230:231], s[50:51], 0, v[138:139]
	global_load_lds_dwordx4 v[228:229], off
	v_lshl_add_u64 v[228:229], s[76:77], 0, v[136:137]
	s_add_i32 m0, s75, 0x2000
	s_nop 0
	global_load_lds_dwordx4 v[228:229], off
	v_lshl_add_u64 v[228:229], s[50:51], 0, v[142:143]
	s_mov_b32 m0, s43
	s_nop 0
	global_load_lds_dwordx4 v[228:229], off
	s_mov_b32 m0, s45
	s_nop 0
	global_load_lds_dwordx4 v[230:231], off
	s_waitcnt vmcnt(8)
	s_waitcnt lgkmcnt(0)
	s_barrier
	s_setprio 1
	s_waitcnt lgkmcnt(0)
	s_cmp_eq_u32 s92, 0
	s_cbranch_scc1 .Lms9_b2
	v_mfma_f32_16x16x32_bf16 v[60:63], v[148:151], v[192:195], v[60:63]
	v_mfma_f32_16x16x32_bf16 v[56:59], v[168:171], v[192:195], v[56:59]
	v_mfma_f32_16x16x32_bf16 v[52:55], v[148:151], v[200:203], v[52:55]
	v_mfma_f32_16x16x32_bf16 v[40:43], v[168:171], v[200:203], v[40:43]
	v_mfma_f32_16x16x32_bf16 v[36:39], v[148:151], v[208:211], v[36:39]
	v_mfma_f32_16x16x32_bf16 v[24:27], v[168:171], v[208:211], v[24:27]
	v_mfma_f32_16x16x32_bf16 v[20:23], v[148:151], v[216:219], v[20:23]
	v_mfma_f32_16x16x32_bf16 v[8:11], v[168:171], v[216:219], v[8:11]
	v_mfma_f32_16x16x32_bf16 v[60:63], v[164:167], v[196:199], v[60:63]
	v_mfma_f32_16x16x32_bf16 v[56:59], v[172:175], v[196:199], v[56:59]
	v_mfma_f32_16x16x32_bf16 v[52:55], v[164:167], v[204:207], v[52:55]
	v_mfma_f32_16x16x32_bf16 v[40:43], v[172:175], v[204:207], v[40:43]
	v_mfma_f32_16x16x32_bf16 v[36:39], v[164:167], v[212:215], v[36:39]
	v_mfma_f32_16x16x32_bf16 v[24:27], v[172:175], v[212:215], v[24:27]
	v_mfma_f32_16x16x32_bf16 v[20:23], v[164:167], v[220:223], v[20:23]
	v_mfma_f32_16x16x32_bf16 v[8:11], v[172:175], v[220:223], v[8:11]
.Lms9_b2:
	s_setprio 0
	s_setprio 1
	s_cmp_eq_u32 s92, 0
	s_cbranch_scc1 .Lms9_b3
	v_mfma_f32_16x16x32_bf16 v[48:51], v[176:179], v[192:195], v[48:51]
	v_mfma_f32_16x16x32_bf16 v[44:47], v[184:187], v[192:195], v[44:47]
	v_mfma_f32_16x16x32_bf16 v[32:35], v[176:179], v[200:203], v[32:35]
	v_mfma_f32_16x16x32_bf16 v[28:31], v[184:187], v[200:203], v[28:31]
	v_mfma_f32_16x16x32_bf16 v[16:19], v[176:179], v[208:211], v[16:19]
	v_mfma_f32_16x16x32_bf16 v[12:15], v[184:187], v[208:211], v[12:15]
	v_mfma_f32_16x16x32_bf16 v[4:7], v[176:179], v[216:219], v[4:7]
	v_mfma_f32_16x16x32_bf16 v[0:3], v[184:187], v[216:219], v[0:3]
	v_mfma_f32_16x16x32_bf16 v[48:51], v[180:183], v[196:199], v[48:51]
	v_mfma_f32_16x16x32_bf16 v[44:47], v[188:191], v[196:199], v[44:47]
	v_mfma_f32_16x16x32_bf16 v[32:35], v[180:183], v[204:207], v[32:35]
	v_mfma_f32_16x16x32_bf16 v[28:31], v[188:191], v[204:207], v[28:31]
	v_mfma_f32_16x16x32_bf16 v[16:19], v[180:183], v[212:215], v[16:19]
	v_mfma_f32_16x16x32_bf16 v[12:15], v[188:191], v[212:215], v[12:15]
	v_mfma_f32_16x16x32_bf16 v[4:7], v[180:183], v[220:223], v[4:7]
	v_mfma_f32_16x16x32_bf16 v[0:3], v[188:191], v[220:223], v[0:3]
.Lms9_b3:
	s_setprio 0
	s_barrier
	s_add_i32 s75, 0, 0x18000
	v_add_u32_e32 v163, s75, v135
	s_add_i32 s76, 0, 0x1c000
	ds_read_b128 v[148:151], v163
	ds_read_b128 v[164:167], v163 offset:1024
	ds_read_b128 v[168:171], v163 offset:2048
	ds_read_b128 v[172:175], v163 offset:3072
	v_add_u32_e32 v163, s76, v135
	ds_read_b128 v[176:179], v163
	ds_read_b128 v[180:183], v163 offset:1024
	ds_read_b128 v[184:187], v163 offset:2048
	ds_read_b128 v[188:191], v163 offset:3072
	s_add_u32 s50, s50, 0x40000
	s_addc_u32 s51, s51, 0
	s_mov_b32 m0, s57
	v_lshl_add_u64 v[232:233], s[50:51], 0, v[142:143]
	ds_read_b128 v[192:195], v162 offset:32768
	ds_read_b128 v[196:199], v162 offset:33792
	ds_read_b128 v[200:203], v162 offset:34816
	ds_read_b128 v[204:207], v162 offset:35840
	ds_read_b128 v[208:211], v162 offset:36864
	ds_read_b128 v[212:215], v162 offset:37888
	ds_read_b128 v[216:219], v162 offset:38912
	ds_read_b128 v[220:223], v162 offset:39936
	global_load_lds_dwordx4 v[232:233], off
	v_lshl_add_u64 v[232:233], s[50:51], 0, v[138:139]
	s_mov_b32 m0, s58
	s_nop 0
	global_load_lds_dwordx4 v[232:233], off
	s_waitcnt vmcnt(8)
	s_waitcnt lgkmcnt(0)
	s_barrier
	s_setprio 1
	s_waitcnt lgkmcnt(0)
	s_cmp_eq_u32 s92, 1
	s_cbranch_scc1 .Lms9_b4
	v_mfma_f32_16x16x32_bf16 v[124:127], v[148:151], v[192:195], v[124:127]
	v_mfma_f32_16x16x32_bf16 v[120:123], v[168:171], v[192:195], v[120:123]
	v_mfma_f32_16x16x32_bf16 v[116:119], v[148:151], v[200:203], v[116:119]
	v_mfma_f32_16x16x32_bf16 v[104:107], v[168:171], v[200:203], v[104:107]
	v_mfma_f32_16x16x32_bf16 v[100:103], v[148:151], v[208:211], v[100:103]
	v_mfma_f32_16x16x32_bf16 v[88:91], v[168:171], v[208:211], v[88:91]
	v_mfma_f32_16x16x32_bf16 v[84:87], v[148:151], v[216:219], v[84:87]
	v_mfma_f32_16x16x32_bf16 v[72:75], v[168:171], v[216:219], v[72:75]
	v_mfma_f32_16x16x32_bf16 v[124:127], v[164:167], v[196:199], v[124:127]
	v_mfma_f32_16x16x32_bf16 v[120:123], v[172:175], v[196:199], v[120:123]
	v_mfma_f32_16x16x32_bf16 v[116:119], v[164:167], v[204:207], v[116:119]
	v_mfma_f32_16x16x32_bf16 v[104:107], v[172:175], v[204:207], v[104:107]
	v_mfma_f32_16x16x32_bf16 v[100:103], v[164:167], v[212:215], v[100:103]
	v_mfma_f32_16x16x32_bf16 v[88:91], v[172:175], v[212:215], v[88:91]
	v_mfma_f32_16x16x32_bf16 v[84:87], v[164:167], v[220:223], v[84:87]
	v_mfma_f32_16x16x32_bf16 v[72:75], v[172:175], v[220:223], v[72:75]

; #define PG8_STAGE(bufoff, gbase, voff) do { _Pragma("unroll") for (int _i = 0; _i < 2; ++_i) \
;         __builtin_amdgcn_global_load_lds((const unsigned*)((const char*)(gbase) + (voff)[_i]), (PG8_LAS unsigned*)(lds + (bufoff) + ldsw + _i * 8192), 16, 0, 0); } while (0)
; #define PG8_LDA(dst, b, h) do { _Pragma("unroll") for (int m = 0; m < 4; ++m) _Pragma("unroll") for (int k = 0; k < 2; ++k) dst[m][k] = *(const PG8_LAS bf16x8*)(lds + PG8_SA(b, h) + aoff + m * 2048 + k * 1024); } while (0)
; #define PG8_MMA(ai, bj, At, Bt) do { __builtin_amdgcn_s_setprio(1); _Pragma("unroll") for (int m = 0; m < 4; ++m) _Pragma("unroll") for (int n = 0; n < 2; ++n) _Pragma("unroll") for (int k = 0; k < 2; ++k) \
;         acc[ai][bj][m][n] = __builtin_amdgcn_mfma_f32_16x16x32_bf16(Bt[n][k], At[m][k], acc[ai][bj][m][n], 0, 0, 0); __builtin_amdgcn_s_setprio(0); } while (0)
; #define PG8_WAIT_V(n) asm volatile("s_waitcnt vmcnt(" #n ")" ::: "memory")
; #define PG8_WAIT_L(n) asm volatile("s_waitcnt lgkmcnt(" #n ")" ::: "memory")
; #define PG8_BAR __builtin_amdgcn_s_barrier()
; #define PG8_SCHED __builtin_amdgcn_sched_barrier(0)
; template <class Epi, class Sched, bool ALIGN_EPI = false, bool SP2 = false>
; __device__ __forceinline__ void gemm_phase(PG8_LAS unsigned char* lds, const Gemm g, const Sched& S, const Epi& E) {
;     ...
;             PG8_LDA(At, 1, 1); PG8_STAGE(PG8_SB(1, 0), b3, voffB); PG8_STAGE(PG8_SB(1, 1), b3 + hstep, voffB); PG8_STAGE(PG8_SA(1, 0), a3, voffA);
;             PG8_WAIT_V(8); PG8_WAIT_L(0); PG8_BAR; PG8_MMA(1, 0, At, B0); PG8_MMA(1, 1, At, B1); PG8_BAR; PG8_SCHED;
.Lms9_b5:
	s_setprio 0
	s_barrier
	s_add_i32 s50, s75, s56
	v_lshl_add_u64 v[224:225], v[224:225], 0, s[10:11]
	s_mov_b32 m0, s50
	ds_read_b128 v[192:195], v162 offset:49152
	ds_read_b128 v[196:199], v162 offset:50176
	ds_read_b128 v[200:203], v162 offset:51200
	ds_read_b128 v[204:207], v162 offset:52224
	ds_read_b128 v[208:211], v162 offset:53248
	ds_read_b128 v[212:215], v162 offset:54272
	ds_read_b128 v[216:219], v162 offset:55296
	ds_read_b128 v[220:223], v162 offset:56320
	global_load_lds_dwordx4 v[224:225], off
	s_add_i32 m0, s50, 0x2000
	s_add_u32 s48, s48, 0x40080
	v_lshl_add_u64 v[224:225], v[226:227], 0, s[10:11]
	s_addc_u32 s49, s49, 0
	s_add_i32 s50, s76, s56
	global_load_lds_dwordx4 v[224:225], off
	v_lshl_add_u64 v[224:225], s[48:49], 0, v[140:141]
	s_mov_b32 m0, s50
	s_nop 0
	global_load_lds_dwordx4 v[224:225], off
	v_lshl_add_u64 v[224:225], s[48:49], 0, v[136:137]
	s_add_i32 m0, s50, 0x2000
	s_nop 0
	global_load_lds_dwordx4 v[224:225], off
	v_lshl_add_u64 v[224:225], v[228:229], 0, s[10:11]
	s_mov_b32 m0, s60
	s_nop 0
	global_load_lds_dwordx4 v[224:225], off
	v_lshl_add_u64 v[224:225], v[230:231], 0, s[10:11]
	s_mov_b32 m0, s61
	s_nop 0
	global_load_lds_dwordx4 v[224:225], off
	s_waitcnt vmcnt(8)
	s_waitcnt lgkmcnt(0)
	s_barrier
	s_setprio 1
	s_waitcnt lgkmcnt(0)
	s_cmp_eq_u32 s92, 0
	s_cbranch_scc1 .Lms9_b6
	v_mfma_f32_16x16x32_bf16 v[60:63], v[148:151], v[192:195], v[60:63]
	v_mfma_f32_16x16x32_bf16 v[56:59], v[168:171], v[192:195], v[56:59]
	v_mfma_f32_16x16x32_bf16 v[52:55], v[148:151], v[200:203], v[52:55]
	v_mfma_f32_16x16x32_bf16 v[40:43], v[168:171], v[200:203], v[40:43]
	v_mfma_f32_16x16x32_bf16 v[36:39], v[148:151], v[208:211], v[36:39]
	v_mfma_f32_16x16x32_bf16 v[24:27], v[168:171], v[208:211], v[24:27]
	v_mfma_f32_16x16x32_bf16 v[20:23], v[148:151], v[216:219], v[20:23]
	v_mfma_f32_16x16x32_bf16 v[8:11], v[168:171], v[216:219], v[8:11]
	v_mfma_f32_16x16x32_bf16 v[60:63], v[164:167], v[196:199], v[60:63]
	v_mfma_f32_16x16x32_bf16 v[56:59], v[172:175], v[196:199], v[56:59]
	v_mfma_f32_16x16x32_bf16 v[52:55], v[164:167], v[204:207], v[52:55]
	v_mfma_f32_16x16x32_bf16 v[40:43], v[172:175], v[204:207], v[40:43]
	v_mfma_f32_16x16x32_bf16 v[36:39], v[164:167], v[212:215], v[36:39]
	v_mfma_f32_16x16x32_bf16 v[24:27], v[172:175], v[212:215], v[24:27]
	v_mfma_f32_16x16x32_bf16 v[20:23], v[164:167], v[220:223], v[20:23]
	v_mfma_f32_16x16x32_bf16 v[8:11], v[172:175], v[220:223], v[8:11]

;     __device__ __forceinline__ void operator()(const f32x4 (&acc)[2][2][4][2], const Unit& u, int wr, int wc, int fr, int fq) const {
; #pragma unroll
;         for (int ai = 0; ai < 2; ++ai)
; #pragma unroll
;             for (int m = 0; m < 4; ++m)
; #pragma unroll
;                 for (int bj = 0; bj < 2; ++bj) f(u, ai * 128 + wr * 64 + m * 16 + fr, bj * 128 + wc * 32 + 8 * fq, acc[ai][bj][m][0], acc[ai][bj][m][1]);
;     }
;     __device__ __forceinline__ void operator()(const pg8::Unit& u, int rl, int cl, f32x4 v0, f32x4 v1) const {
;         const int b = u.pm / 17, j = u.pm - 17 * b, col = u.pn * 256 + cl;
;         const float* src; float* dst; const float* gate;
;         if (j == 0) { const size_t off = (size_t)(b * CTXL + rl) * D + col; src = co + off; dst = cn + off; gate = modl + 4 * 3072 + 2048 + col; }
;         else { const size_t off = (size_t)(b * SEQ + (j - 1) * 256 + rl) * D + col; src = xo + off; dst = xn + off; gate = modl + b * 3072 + 2048 + col; }
;         const f32x4 a0 = *(const f32x4*)src, a1 = *(const f32x4*)(src + 4), g0 = *(const f32x4*)gate, g1 = *(const f32x4*)(gate + 4);
;         *(f32x4*)dst = a0 + g0 * v0; *(f32x4*)(dst + 4) = a1 + g1 * v1;
.Lms9_b7:
	s_setprio 0
	s_barrier
	s_add_i32 s74, s74, 2
	s_add_u32 s46, s46, 0x100
	s_addc_u32 s47, s47, 0
	s_add_u32 s72, s72, 0x100
	s_addc_u32 s73, s73, 0
	s_cmp_gt_u32 s74, 13
	s_cbranch_scc0 .LBB0_1266
	s_and_b64 vcc, exec, s[14:15]
	s_cbranch_vccz .LBB0_1269
	s_barrier
.LBB0_1269:
	s_mul_hi_i32 s17, s42, 0x78787879
	s_lshr_b32 s19, s17, 31
	s_ashr_i32 s17, s17, 3
	s_add_i32 s19, s17, s19
	s_mul_i32 s17, s19, 0xffffffef
	s_add_i32 s42, s17, s42
	v_lshl_or_b32 v148, s44, 8, v159
	s_lshl_b32 s17, s19, 12
	s_lshl_b32 s44, s42, 8
	s_mul_i32 s46, s19, 0xc00
	s_add_i32 s17, s17, s44
	s_ashr_i32 s47, s46, 31
	s_addk_i32 s17, 0xff00
	s_lshl_b32 s19, s19, 8
	s_lshl_b64 s[46:47], s[46:47], 2
	s_add_u32 s44, s26, s46
	s_addc_u32 s46, s27, s47
	s_add_u32 s44, s44, 0x11000
	s_addc_u32 s48, s46, 0
	v_add_u32_e32 v150, s17, v133
	v_add_u32_e32 v164, s19, v133
	s_cmp_eq_u32 s42, 0
	v_ashrrev_i32_e32 v151, 31, v150
	v_ashrrev_i32_e32 v165, 31, v164
	v_lshlrev_b64 v[164:165], 12, v[164:165]
	v_lshlrev_b64 v[150:151], 12, v[150:151]
	s_cselect_b64 vcc, -1, 0
	v_ashrrev_i32_e32 v149, 31, v148
	v_lshl_add_u64 v[164:165], s[8:9], 0, v[164:165]
	v_lshl_add_u64 v[150:151], s[12:13], 0, v[150:151]
	s_and_b64 s[46:47], vcc, exec
	v_cndmask_b32_e32 v165, v151, v165, vcc
	s_cselect_b32 s47, s63, s48
	s_cselect_b32 s46, s62, s44
	v_cndmask_b32_e32 v164, v150, v164, vcc
	v_lshlrev_b64 v[150:151], 2, v[148:149]
	v_lshl_add_u64 v[148:149], s[46:47], 0, v[150:151]
	v_lshl_add_u64 v[180:181], v[164:165], 0, v[150:151]
	global_load_dwordx4 v[164:167], v[148:149], off
	global_load_dwordx4 v[168:171], v[148:149], off offset:16
	global_load_dwordx4 v[176:179], v[148:149], off offset:512
	global_load_dwordx4 v[182:185], v[148:149], off offset:528
	v_add_u32_e32 v220, s19, v152
	v_add_u32_e32 v222, s17, v152
	v_ashrrev_i32_e32 v221, 31, v220
	v_ashrrev_i32_e32 v223, 31, v222
	v_lshlrev_b64 v[220:221], 12, v[220:221]
	v_lshlrev_b64 v[222:223], 12, v[222:223]
	v_lshl_add_u64 v[220:221], s[8:9], 0, v[220:221]
	v_lshl_add_u64 v[222:223], s[12:13], 0, v[222:223]
	v_cndmask_b32_e32 v221, v223, v221, vcc
	v_cndmask_b32_e32 v220, v222, v220, vcc
	v_lshl_add_u64 v[220:221], v[220:221], 0, v[150:151]
	global_load_dwordx4 v[186:189], v[180:181], off
	global_load_dwordx4 v[190:193], v[180:181], off offset:16
	global_load_dwordx4 v[194:197], v[180:181], off offset:512
	global_load_dwordx4 v[198:201], v[180:181], off offset:528
	global_load_dwordx4 v[202:205], v[220:221], off
	global_load_dwordx4 v[206:209], v[220:221], off offset:16
	global_load_dwordx4 v[210:213], v[220:221], off offset:512
	global_load_dwordx4 v[214:217], v[220:221], off offset:528
	s_waitcnt vmcnt(0)
	v_pk_fma_f32 v[186:187], v[124:125], v[164:165], v[186:187]
	v_pk_fma_f32 v[188:189], v[126:127], v[166:167], v[188:189]
	v_pk_fma_f32 v[190:191], v[120:121], v[168:169], v[190:191]
	v_pk_fma_f32 v[192:193], v[122:123], v[170:171], v[192:193]
	v_pk_fma_f32 v[194:195], v[112:113], v[176:177], v[194:195]
	v_pk_fma_f32 v[196:197], v[114:115], v[178:179], v[196:197]
	v_pk_fma_f32 v[198:199], v[108:109], v[182:183], v[198:199]
	v_pk_fma_f32 v[200:201], v[110:111], v[184:185], v[200:201]
	v_pk_fma_f32 v[202:203], v[116:117], v[164:165], v[202:203]
	v_pk_fma_f32 v[204:205], v[118:119], v[166:167], v[204:205]
	v_pk_fma_f32 v[206:207], v[104:105], v[168:169], v[206:207]
	v_pk_fma_f32 v[208:209], v[106:107], v[170:171], v[208:209]
	v_pk_fma_f32 v[210:211], v[96:97], v[176:177], v[210:211]
	v_pk_fma_f32 v[212:213], v[98:99], v[178:179], v[212:213]
	v_pk_fma_f32 v[214:215], v[92:93], v[182:183], v[214:215]
	v_pk_fma_f32 v[216:217], v[94:95], v[184:185], v[216:217]
	s_mov_b64 exec, s[88:89]
	global_store_dwordx4 v[180:181], v[186:189], off
	s_mov_b64 exec, -1
	s_mov_b64 exec, s[88:89]
	global_store_dwordx4 v[180:181], v[190:193], off offset:16
	s_mov_b64 exec, -1
	s_mov_b64 exec, s[88:89]
	global_store_dwordx4 v[180:181], v[194:197], off offset:512
	s_mov_b64 exec, -1
	s_mov_b64 exec, s[88:89]
	global_store_dwordx4 v[180:181], v[198:201], off offset:528
	s_mov_b64 exec, -1
	s_mov_b64 exec, s[88:89]
	global_store_dwordx4 v[220:221], v[202:205], off
	s_mov_b64 exec, -1
	s_mov_b64 exec, s[88:89]
	global_store_dwordx4 v[220:221], v[206:209], off offset:16
	s_mov_b64 exec, -1
	s_mov_b64 exec, s[88:89]
	global_store_dwordx4 v[220:221], v[210:213], off offset:512
	s_mov_b64 exec, -1
	s_mov_b64 exec, s[88:89]
	global_store_dwordx4 v[220:221], v[214:217], off offset:528
	s_mov_b64 exec, -1
	s_nop 1
	v_add_u32_e32 v218, s19, v153
	v_add_u32_e32 v222, s17, v153
	v_ashrrev_i32_e32 v219, 31, v218
	v_ashrrev_i32_e32 v223, 31, v222
	v_lshlrev_b64 v[218:219], 12, v[218:219]
	v_lshlrev_b64 v[222:223], 12, v[222:223]
	v_lshl_add_u64 v[218:219], s[8:9], 0, v[218:219]
	v_lshl_add_u64 v[222:223], s[12:13], 0, v[222:223]
	v_cndmask_b32_e32 v219, v223, v219, vcc
	v_cndmask_b32_e32 v218, v222, v218, vcc
	v_lshl_add_u64 v[218:219], v[218:219], 0, v[150:151]
	v_add_u32_e32 v220, s19, v154
	v_add_u32_e32 v222, s17, v154
	v_ashrrev_i32_e32 v221, 31, v220
	v_ashrrev_i32_e32 v223, 31, v222
	v_lshlrev_b64 v[220:221], 12, v[220:221]
	v_lshlrev_b64 v[222:223], 12, v[222:223]
	v_lshl_add_u64 v[220:221], s[8:9], 0, v[220:221]
	v_lshl_add_u64 v[222:223], s[12:13], 0, v[222:223]
	v_cndmask_b32_e32 v221, v223, v221, vcc
	v_cndmask_b32_e32 v220, v222, v220, vcc
	v_lshl_add_u64 v[220:221], v[220:221], 0, v[150:151]
	global_load_dwordx4 v[186:189], v[218:219], off
	global_load_dwordx4 v[190:193], v[218:219], off offset:16
	global_load_dwordx4 v[194:197], v[218:219], off offset:512
	global_load_dwordx4 v[198:201], v[218:219], off offset:528
	global_load_dwordx4 v[202:205], v[220:221], off
	global_load_dwordx4 v[206:209], v[220:221], off offset:16
	global_load_dwordx4 v[210:213], v[220:221], off offset:512
	global_load_dwordx4 v[214:217], v[220:221], off offset:528
	s_waitcnt vmcnt(0)
;     __device__ __forceinline__ void operator()(const pg8::Unit& u, int rl, int cl, f32x4 v0, f32x4 v1) const {
;         const int b = u.pm / 17, j = u.pm - 17 * b, col = u.pn * 256 + cl;
;         const float* src; float* dst; const float* gate;
;         if (j == 0) { const size_t off = (size_t)(b * CTXL + rl) * D + col; src = co + off; dst = cn + off; gate = modl + 4 * 3072 + 2048 + col; }
;         else { const size_t off = (size_t)(b * SEQ + (j - 1) * 256 + rl) * D + col; src = xo + off; dst = xn + off; gate = modl + b * 3072 + 2048 + col; }
;         const f32x4 a0 = *(const f32x4*)src, a1 = *(const f32x4*)(src + 4), g0 = *(const f32x4*)gate, g1 = *(const f32x4*)(gate + 4);
;         *(f32x4*)dst = a0 + g0 * v0; *(f32x4*)(dst + 4) = a1 + g1 * v1;
	v_pk_fma_f32 v[186:187], v[100:101], v[164:165], v[186:187]
	v_pk_fma_f32 v[188:189], v[102:103], v[166:167], v[188:189]
	v_pk_fma_f32 v[190:191], v[88:89], v[168:169], v[190:191]
	v_pk_fma_f32 v[192:193], v[90:91], v[170:171], v[192:193]
	v_pk_fma_f32 v[194:195], v[80:81], v[176:177], v[194:195]
	v_pk_fma_f32 v[196:197], v[82:83], v[178:179], v[196:197]
	v_pk_fma_f32 v[198:199], v[76:77], v[182:183], v[198:199]
	v_pk_fma_f32 v[200:201], v[78:79], v[184:185], v[200:201]
	v_pk_fma_f32 v[202:203], v[84:85], v[164:165], v[202:203]
	v_pk_fma_f32 v[204:205], v[86:87], v[166:167], v[204:205]
	v_pk_fma_f32 v[206:207], v[72:73], v[168:169], v[206:207]
	v_pk_fma_f32 v[208:209], v[74:75], v[170:171], v[208:209]
	v_pk_fma_f32 v[210:211], v[68:69], v[176:177], v[210:211]
	v_pk_fma_f32 v[212:213], v[70:71], v[178:179], v[212:213]
	v_pk_fma_f32 v[214:215], v[64:65], v[182:183], v[214:215]
	v_pk_fma_f32 v[216:217], v[66:67], v[184:185], v[216:217]
	s_mov_b64 exec, s[88:89]
	global_store_dwordx4 v[218:219], v[186:189], off
	s_mov_b64 exec, -1
	s_mov_b64 exec, s[88:89]
	global_store_dwordx4 v[218:219], v[190:193], off offset:16
	s_mov_b64 exec, -1
	s_mov_b64 exec, s[88:89]
	global_store_dwordx4 v[218:219], v[194:197], off offset:512
	s_mov_b64 exec, -1
	s_mov_b64 exec, s[88:89]
	global_store_dwordx4 v[218:219], v[198:201], off offset:528
	s_mov_b64 exec, -1
	s_mov_b64 exec, s[88:89]
	global_store_dwordx4 v[220:221], v[202:205], off
	s_mov_b64 exec, -1
	s_mov_b64 exec, s[88:89]
	global_store_dwordx4 v[220:221], v[206:209], off offset:16
	s_mov_b64 exec, -1
	s_mov_b64 exec, s[88:89]
	global_store_dwordx4 v[220:221], v[210:213], off offset:512
	s_mov_b64 exec, -1
	s_mov_b64 exec, s[88:89]
	global_store_dwordx4 v[220:221], v[214:217], off offset:528
	s_mov_b64 exec, -1
	s_nop 1
	v_add_u32_e32 v218, s19, v155
	v_add_u32_e32 v222, s17, v155
	v_ashrrev_i32_e32 v219, 31, v218
	v_ashrrev_i32_e32 v223, 31, v222
	v_lshlrev_b64 v[218:219], 12, v[218:219]
	v_lshlrev_b64 v[222:223], 12, v[222:223]
	v_lshl_add_u64 v[218:219], s[8:9], 0, v[218:219]
	v_lshl_add_u64 v[222:223], s[12:13], 0, v[222:223]
	v_cndmask_b32_e32 v219, v223, v219, vcc
	v_cndmask_b32_e32 v218, v222, v218, vcc
	v_lshl_add_u64 v[218:219], v[218:219], 0, v[150:151]
	v_add_u32_e32 v220, s19, v156
	v_add_u32_e32 v222, s17, v156
	v_ashrrev_i32_e32 v221, 31, v220
	v_ashrrev_i32_e32 v223, 31, v222
	v_lshlrev_b64 v[220:221], 12, v[220:221]
	v_lshlrev_b64 v[222:223], 12, v[222:223]
	v_lshl_add_u64 v[220:221], s[8:9], 0, v[220:221]
	v_lshl_add_u64 v[222:223], s[12:13], 0, v[222:223]
	v_cndmask_b32_e32 v221, v223, v221, vcc
	v_cndmask_b32_e32 v220, v222, v220, vcc
	v_lshl_add_u64 v[220:221], v[220:221], 0, v[150:151]
	global_load_dwordx4 v[186:189], v[218:219], off
	global_load_dwordx4 v[190:193], v[218:219], off offset:16
	global_load_dwordx4 v[194:197], v[218:219], off offset:512
	global_load_dwordx4 v[198:201], v[218:219], off offset:528
	global_load_dwordx4 v[202:205], v[220:221], off
	global_load_dwordx4 v[206:209], v[220:221], off offset:16
	global_load_dwordx4 v[210:213], v[220:221], off offset:512
	global_load_dwordx4 v[214:217], v[220:221], off offset:528
	s_waitcnt vmcnt(0)
; #define PG8_BAR __builtin_amdgcn_s_barrier()
; template <class Epi, class Sched, bool ALIGN_EPI = false, bool SP2 = false>
; __device__ __forceinline__ void gemm_phase(PG8_LAS unsigned char* lds, const Gemm g, const Sched& S, const Epi& E) {
;     ...
;         if (!has_next) break;
; #pragma unroll
;         for (int a = 0; a < 2; ++a)
; #pragma unroll
;             for (int b = 0; b < 2; ++b)
; #pragma unroll
;                 for (int m = 0; m < 4; ++m)
; #pragma unroll
;                     for (int n = 0; n < 2; ++n) acc[a][b][m][n] = (f32x4){0.f, 0.f, 0.f, 0.f};
;         cur = nxt; cA = nA; cB = nB; ++ui;
;         if constexpr (ALIGN_EPI) { if (wr == 1) PG8_BAR; }
;     __device__ __forceinline__ void operator()(const pg8::Unit& u, int rl, int cl, f32x4 v0, f32x4 v1) const {
;         const int b = u.pm / 17, j = u.pm - 17 * b, col = u.pn * 256 + cl;
;         const float* src; float* dst; const float* gate;
;         if (j == 0) { const size_t off = (size_t)(b * CTXL + rl) * D + col; src = co + off; dst = cn + off; gate = modl + 4 * 3072 + 2048 + col; }
;         else { const size_t off = (size_t)(b * SEQ + (j - 1) * 256 + rl) * D + col; src = xo + off; dst = xn + off; gate = modl + b * 3072 + 2048 + col; }
;         const f32x4 a0 = *(const f32x4*)src, a1 = *(const f32x4*)(src + 4), g0 = *(const f32x4*)gate, g1 = *(const f32x4*)(gate + 4);
;         *(f32x4*)dst = a0 + g0 * v0; *(f32x4*)(dst + 4) = a1 + g1 * v1;
	v_pk_fma_f32 v[186:187], v[60:61], v[164:165], v[186:187]
	v_pk_fma_f32 v[188:189], v[62:63], v[166:167], v[188:189]
	v_pk_fma_f32 v[190:191], v[56:57], v[168:169], v[190:191]
	v_pk_fma_f32 v[192:193], v[58:59], v[170:171], v[192:193]
	v_pk_fma_f32 v[194:195], v[48:49], v[176:177], v[194:195]
	v_pk_fma_f32 v[196:197], v[50:51], v[178:179], v[196:197]
	v_pk_fma_f32 v[198:199], v[44:45], v[182:183], v[198:199]
	v_pk_fma_f32 v[200:201], v[46:47], v[184:185], v[200:201]
	v_pk_fma_f32 v[202:203], v[52:53], v[164:165], v[202:203]
	v_pk_fma_f32 v[204:205], v[54:55], v[166:167], v[204:205]
	v_pk_fma_f32 v[206:207], v[40:41], v[168:169], v[206:207]
	v_pk_fma_f32 v[208:209], v[42:43], v[170:171], v[208:209]
	v_pk_fma_f32 v[210:211], v[32:33], v[176:177], v[210:211]
	v_pk_fma_f32 v[212:213], v[34:35], v[178:179], v[212:213]
	v_pk_fma_f32 v[214:215], v[28:29], v[182:183], v[214:215]
	v_pk_fma_f32 v[216:217], v[30:31], v[184:185], v[216:217]
	s_mov_b64 exec, s[90:91]
	global_store_dwordx4 v[218:219], v[186:189], off
	s_mov_b64 exec, -1
	s_mov_b64 exec, s[90:91]
	global_store_dwordx4 v[218:219], v[190:193], off offset:16
	s_mov_b64 exec, -1
	s_mov_b64 exec, s[90:91]
	global_store_dwordx4 v[218:219], v[194:197], off offset:512
	s_mov_b64 exec, -1
	s_mov_b64 exec, s[90:91]
	global_store_dwordx4 v[218:219], v[198:201], off offset:528
	s_mov_b64 exec, -1
	s_mov_b64 exec, s[90:91]
	global_store_dwordx4 v[220:221], v[202:205], off
	s_mov_b64 exec, -1
	s_mov_b64 exec, s[90:91]
	global_store_dwordx4 v[220:221], v[206:209], off offset:16
	s_mov_b64 exec, -1
	s_mov_b64 exec, s[90:91]
	global_store_dwordx4 v[220:221], v[210:213], off offset:512
	s_mov_b64 exec, -1
	s_mov_b64 exec, s[90:91]
	global_store_dwordx4 v[220:221], v[214:217], off offset:528
	s_mov_b64 exec, -1
	s_nop 1
	v_add_u32_e32 v218, s19, v157
	v_add_u32_e32 v222, s17, v157
	v_ashrrev_i32_e32 v219, 31, v218
	v_ashrrev_i32_e32 v223, 31, v222
	v_lshlrev_b64 v[218:219], 12, v[218:219]
	v_lshlrev_b64 v[222:223], 12, v[222:223]
	v_lshl_add_u64 v[218:219], s[8:9], 0, v[218:219]
	v_lshl_add_u64 v[222:223], s[12:13], 0, v[222:223]
	v_cndmask_b32_e32 v219, v223, v219, vcc
	v_cndmask_b32_e32 v218, v222, v218, vcc
	v_lshl_add_u64 v[218:219], v[218:219], 0, v[150:151]
	v_add_u32_e32 v220, s19, v158
	v_add_u32_e32 v222, s17, v158
	v_ashrrev_i32_e32 v221, 31, v220
	v_ashrrev_i32_e32 v223, 31, v222
	v_lshlrev_b64 v[220:221], 12, v[220:221]
	v_lshlrev_b64 v[222:223], 12, v[222:223]
	v_lshl_add_u64 v[220:221], s[8:9], 0, v[220:221]
	v_lshl_add_u64 v[222:223], s[12:13], 0, v[222:223]
	v_cndmask_b32_e32 v221, v223, v221, vcc
	v_cndmask_b32_e32 v220, v222, v220, vcc
	v_lshl_add_u64 v[220:221], v[220:221], 0, v[150:151]
	global_load_dwordx4 v[186:189], v[218:219], off
	global_load_dwordx4 v[190:193], v[218:219], off offset:16
	global_load_dwordx4 v[194:197], v[218:219], off offset:512
	global_load_dwordx4 v[198:201], v[218:219], off offset:528
	global_load_dwordx4 v[202:205], v[220:221], off
	global_load_dwordx4 v[206:209], v[220:221], off offset:16
	global_load_dwordx4 v[210:213], v[220:221], off offset:512
	global_load_dwordx4 v[214:217], v[220:221], off offset:528
	s_waitcnt vmcnt(0)
	v_pk_fma_f32 v[186:187], v[36:37], v[164:165], v[186:187]
	v_pk_fma_f32 v[188:189], v[38:39], v[166:167], v[188:189]
	v_pk_fma_f32 v[190:191], v[24:25], v[168:169], v[190:191]
	v_pk_fma_f32 v[192:193], v[26:27], v[170:171], v[192:193]
	v_pk_fma_f32 v[194:195], v[16:17], v[176:177], v[194:195]
	v_pk_fma_f32 v[196:197], v[18:19], v[178:179], v[196:197]
	v_pk_fma_f32 v[198:199], v[12:13], v[182:183], v[198:199]
	v_pk_fma_f32 v[200:201], v[14:15], v[184:185], v[200:201]
	v_pk_fma_f32 v[202:203], v[20:21], v[164:165], v[202:203]
	v_pk_fma_f32 v[204:205], v[22:23], v[166:167], v[204:205]
	v_pk_fma_f32 v[206:207], v[8:9], v[168:169], v[206:207]
	v_pk_fma_f32 v[208:209], v[10:11], v[170:171], v[208:209]
	v_pk_fma_f32 v[210:211], v[4:5], v[176:177], v[210:211]
	v_pk_fma_f32 v[212:213], v[6:7], v[178:179], v[212:213]
	v_pk_fma_f32 v[214:215], v[0:1], v[182:183], v[214:215]
	v_pk_fma_f32 v[216:217], v[2:3], v[184:185], v[216:217]
	s_mov_b64 exec, s[90:91]
	global_store_dwordx4 v[218:219], v[186:189], off
	s_mov_b64 exec, -1
	s_mov_b64 exec, s[90:91]
	global_store_dwordx4 v[218:219], v[190:193], off offset:16
	s_mov_b64 exec, -1
	s_mov_b64 exec, s[90:91]
	global_store_dwordx4 v[218:219], v[194:197], off offset:512
	s_mov_b64 exec, -1
	s_mov_b64 exec, s[90:91]
	global_store_dwordx4 v[218:219], v[198:201], off offset:528
	s_mov_b64 exec, -1
	s_mov_b64 exec, s[90:91]
	global_store_dwordx4 v[220:221], v[202:205], off
	s_mov_b64 exec, -1
	s_mov_b64 exec, s[90:91]
	global_store_dwordx4 v[220:221], v[206:209], off offset:16
	s_mov_b64 exec, -1
	s_mov_b64 exec, s[90:91]
	global_store_dwordx4 v[220:221], v[210:213], off offset:512
	s_mov_b64 exec, -1
	s_mov_b64 exec, s[90:91]
	global_store_dwordx4 v[220:221], v[214:217], off offset:528
	s_mov_b64 exec, -1
	s_nop 1
	s_andn2_b64 vcc, exec, s[22:23]
	s_mov_b64 s[22:23], -1
	s_cbranch_vccnz .LBB0_1262
	s_andn2_b64 vcc, exec, s[6:7]
	s_cbranch_vccnz .LBB0_1261
	s_barrier
	s_branch .LBB0_1261

; #define PG8_STAGE(bufoff, gbase, voff) do { _Pragma("unroll") for (int _i = 0; _i < 2; ++_i) \
;         __builtin_amdgcn_global_load_lds((const unsigned*)((const char*)(gbase) + (voff)[_i]), (PG8_LAS unsigned*)(lds + (bufoff) + ldsw + _i * 8192), 16, 0, 0); } while (0)
; #define PG8_WAIT_V(n) asm volatile("s_waitcnt vmcnt(" #n ")" ::: "memory")
; #define PG8_BAR __builtin_amdgcn_s_barrier()
;     __device__ __forceinline__ bf16* R(int i) const { return (bf16*)(ws + OFF_R0 + (size_t)i * RSZ); }
; template <class Epi, class Sched, bool ALIGN_EPI = false, bool SP2 = false>
; __device__ __forceinline__ void gemm_phase(PG8_LAS unsigned char* lds, const Gemm g, const Sched& S, const Epi& E) {
;     const int tid = threadIdx.x, wid = __builtin_amdgcn_readfirstlane(tid >> 6), lane = tid & 63, wr = wid >> 2, wc = wid & 3, fr = lane & 15, fq = lane >> 4;
;     const int K = g.K, nt = K / BK;
;     unsigned voffA[2], voffB[2];
; #pragma unroll
;     for (int i = 0; i < 2; ++i) { int R, C; stage_rc(tid * 16 + i * 8192, R, C); const int Rb = Epi::PERM ? ((R & ~31) + perm32(R & 31)) : R;
;         voffA[i] = (unsigned)(R * K + C) * 2u; voffB[i] = (unsigned)(Rb * K + C) * 2u; }
;     const size_t kstep = (size_t)(BK * 2);
;     const size_t hstep = (size_t)HALF * K * 2;
;     const size_t tstep = 2 * hstep;
;     const unsigned ldsw = (unsigned)wid * 1024u;
;     const int aoff = lds_byte(wr * 64 + fr, fq * 8), boff = lds_byte(wc * 32 + fr, fq * 8);
;     ...
;     Unit cur, nxt; int ui = 0;
;     if (!S.next(0, cur)) return;
;     f32x4 acc[2][2][4][2];
; #pragma unroll
;     for (int a = 0; a < 2; ++a)
; #pragma unroll
;         for (int b = 0; b < 2; ++b)
; #pragma unroll
;             for (int m = 0; m < 4; ++m)
; #pragma unroll
;                 for (int n = 0; n < 2; ++n) acc[a][b][m][n] = (f32x4){0.f, 0.f, 0.f, 0.f};
;     bf16x8 At[4][2], B0[2][2], B1[2][2];
;     const char* cA = (const char*)g.A + (size_t)cur.pm * tstep; const char* cB = (const char*)g.Bt + (size_t)cur.pn * tstep;
;     S.a_ready(cur);
;     if constexpr (SP2) {
;         PG8_STAGE(PG8_SB(0, 0), cB, voffB); PG8_STAGE(PG8_SB(0, 1), cB + hstep, voffB); PG8_STAGE(PG8_SA(0, 0), cA, voffA); PG8_STAGE(PG8_SA(0, 1), cA + hstep, voffA);
;         if (wr == 1) PG8_BAR;
;         PG8_WAIT_V(2); PG8_BAR;
.LBB0_1876:
	s_mov_b32 s92, 2
	s_mov_b64 s[88:89], -1
	s_mov_b64 s[90:91], -1
	s_or_b64 exec, exec, s[6:7]
	v_cmp_gt_i32_e32 vcc, 20, v2
	v_cmp_lt_i32_e64 s[6:7], 19, v3
	s_and_b64 s[8:9], vcc, s[6:7]
	s_and_saveexec_b64 s[6:7], s[8:9]
	s_cbranch_execz .LBB0_1893
	s_lshl_b32 s3, s2, 5
	s_and_b32 s3, s3, 0xe0
	s_ashr_i32 s8, s2, 3
	s_add_i32 s3, s3, s8
	s_cmpk_eq_i32 s30, 0x100
	s_cselect_b32 s3, s3, s2
	s_cmpk_gt_i32 s30, 0x110
	s_cselect_b32 s10, s2, s3
	s_movk_i32 s11, 0xe0
	s_cmpk_gt_i32 s10, 0x10f
	v_readfirstlane_b32 s20, v128
	s_cbranch_scc1 .LBB0_1893
	v_lshrrev_b32_e32 v0, 5, v128
	v_lshrrev_b32_e32 v2, 1, v128
	v_and_b32_e32 v0, 4, v0
	v_bfe_u32 v1, v128, 2, 2
	v_and_b32_e32 v11, 24, v2
	v_or3_b32 v0, v0, v1, v11
	v_lshlrev_b32_e32 v1, 4, v128
	v_add_u32_e32 v8, 0x2000, v1
	v_lshrrev_b32_e32 v2, 7, v8
	v_and_b32_e32 v4, 32, v128
	v_and_or_b32 v3, v2, s11, v0
	v_bitop3_b32 v9, v1, v4, 48 bitop3:0x6c
	v_and_b32_e32 v10, 64, v128
	v_bfe_u32 v12, v128, 2, 4
	s_movk_i32 s11, 0xf0
	s_add_u32 s8, s26, 0x1200000
	v_or_b32_e32 v1, v9, v10
	v_and_or_b32 v2, v2, s11, v12
	s_addc_u32 s9, s27, 0
	v_lshl_or_b32 v138, v2, 11, v1
	v_lshrrev_b32_e32 v2, 3, v128
	s_movk_i32 s11, 0x60
	s_add_u32 s58, s26, 0xb00000
	v_and_or_b32 v0, v2, s11, v0
	s_movk_i32 s11, 0x70
	s_addc_u32 s59, s27, 0
	v_lshl_or_b32 v140, v0, 11, v1
	v_and_or_b32 v0, v2, s11, v12
	s_ashr_i32 s11, s10, 31
	s_lshr_b32 s11, s11, 30
	s_add_i32 s11, s10, s11
	s_ashr_i32 s48, s11, 2
	s_and_b32 s11, s11, -4
	s_sub_i32 s50, s10, s11
	s_lshr_b32 s18, s20, 6
	s_ashr_i32 s49, s48, 31
	s_ashr_i32 s51, s50, 31
	s_lshr_b32 s21, s20, 8
	s_lshl_b32 s60, s18, 10
	s_lshl_b64 s[10:11], s[48:49], 19
	s_lshl_b64 s[12:13], s[50:51], 19
	s_add_u32 s54, s58, s12
	s_addc_u32 s55, s59, s13
	s_add_i32 s51, s60, 0
	s_add_i32 m0, s51, 0x10000
	v_lshl_or_b32 v136, v3, 11, v1
	global_load_lds_dwordx4 v140, s[54:55]
	s_add_i32 m0, s51, 0x12000
	s_add_u32 s12, s54, 0x40000
	global_load_lds_dwordx4 v136, s[54:55]
	s_addc_u32 s13, s55, 0
	s_add_i32 m0, s51, 0x14000
	v_lshl_or_b32 v142, v0, 11, v1
	global_load_lds_dwordx4 v140, s[12:13]
	s_add_i32 m0, s51, 0x16000
	s_add_u32 s52, s8, s10
	s_addc_u32 s53, s9, s11
	s_add_i32 s61, s51, 0x2000
	global_load_lds_dwordx4 v136, s[12:13]
	s_mov_b32 m0, s51
	s_add_u32 s10, s52, 0x40000
	global_load_lds_dwordx4 v142, s[52:53]
	s_mov_b32 m0, s61
	s_addc_u32 s11, s53, 0
	s_add_i32 s62, s51, 0x4000
	global_load_lds_dwordx4 v138, s[52:53]
	s_mov_b32 m0, s62
	s_add_i32 s63, s51, 0x6000
	global_load_lds_dwordx4 v142, s[10:11]
	s_mov_b32 m0, s63
	v_mov_b32_e32 v141, 0
	global_load_lds_dwordx4 v138, s[10:11]
	s_load_dwordx2 s[10:11], s[0:1], 0x120
	v_mov_b32_e32 v137, v141
	v_mov_b32_e32 v143, v141
	v_mov_b32_e32 v139, v141
	s_cmp_eq_u32 s21, 1
	s_mov_b32 s64, 0
	v_lshl_add_u64 v[6:7], s[54:55], 0, v[140:141]
	v_lshl_add_u64 v[4:5], s[54:55], 0, v[136:137]
	v_lshl_add_u64 v[0:1], s[52:53], 0, v[142:143]
	s_cselect_b64 s[12:13], -1, 0
	s_cmp_lg_u32 s21, 1
	v_lshl_add_u64 v[2:3], s[52:53], 0, v[138:139]
	s_cbranch_scc1 .LBB0_1880
	s_barrier

;     __device__ __forceinline__ bool next(int i, Unit& u) const {
;         const int L = i * G + (((i + 1) * G <= n) ? c : cp); if (L >= n) return false;
;         if (mode == 0) { u.pm = L / nN; u.pn = L - u.pm * nN; }
; template <class Epi, class Sched, bool ALIGN_EPI = false, bool SP2 = false>
; __device__ __forceinline__ void gemm_phase(PG8_LAS unsigned char* lds, const Gemm g, const Sched& S, const Epi& E) {
;     ...
;         const bool has_next = S.next(ui + 1, nxt);
;         const char* nA = has_next ? (const char*)g.A + (size_t)nxt.pm * tstep : cA; const char* nB = has_next ? (const char*)g.Bt + (size_t)nxt.pn * tstep : cB;
.LBB0_1882:
	s_mov_b32 s92, s93
	s_cmp_lg_u32 s92, 1
	s_cselect_b64 s[88:89], -1, 0
	s_cmp_lg_u32 s92, 0
	s_cselect_b64 s[90:91], -1, 0
	s_andn2_b64 vcc, exec, s[44:45]
	s_mov_b32 s50, s24
	s_mov_b32 s48, s22
	s_mov_b64 s[54:55], s[46:47]
	s_mov_b64 s[52:53], s[42:43]
	s_cbranch_vccz .LBB0_1892
.LBB0_1883:
	s_add_i32 s64, s64, 1
	s_mul_i32 s23, s64, s30
	s_add_i32 s25, s23, s30
	s_cmpk_gt_i32 s25, 0x110
	s_cselect_b32 s93, 1, 0
	s_cselect_b32 s25, s2, s3
	s_add_i32 s23, s25, s23
	s_cmp_eq_u32 s93, 0
	s_mov_b32 s93, 2
	s_cbranch_scc1 .Lms16_a
	s_lshr_b32 s94, s2, 4
	s_lshl_b32 s94, s94, 3
	s_and_b32 s95, s2, 7
	s_or_b32 s94, s94, s95
	s_sub_i32 s95, s23, s2
	s_add_i32 s23, s95, s94
	s_bfe_u32 s93, s2, 0x10003
.Lms16_a:
	s_cmpk_lt_i32 s23, 0x110
	s_cselect_b64 s[44:45], -1, 0
	s_cmpk_gt_i32 s23, 0x10f
	s_cbranch_scc1 .LBB0_1885
	s_ashr_i32 s22, s23, 31
	s_lshr_b32 s22, s22, 30
	s_add_i32 s24, s23, s22
	s_ashr_i32 s22, s24, 2
	s_and_b32 s24, s24, -4
	s_sub_i32 s24, s23, s24

; #define PG8_STAGE(bufoff, gbase, voff) do { _Pragma("unroll") for (int _i = 0; _i < 2; ++_i) \
;         __builtin_amdgcn_global_load_lds((const unsigned*)((const char*)(gbase) + (voff)[_i]), (PG8_LAS unsigned*)(lds + (bufoff) + ldsw + _i * 8192), 16, 0, 0); } while (0)
; #define PG8_LDA(dst, b, h) do { _Pragma("unroll") for (int m = 0; m < 4; ++m) _Pragma("unroll") for (int k = 0; k < 2; ++k) dst[m][k] = *(const PG8_LAS bf16x8*)(lds + PG8_SA(b, h) + aoff + m * 2048 + k * 1024); } while (0)
; #define PG8_LDB(dst, b, h) do { _Pragma("unroll") for (int n = 0; n < 2; ++n) _Pragma("unroll") for (int k = 0; k < 2; ++k) dst[n][k] = *(const PG8_LAS bf16x8*)(lds + PG8_SB(b, h) + boff + n * 2048 + k * 1024); } while (0)
; #define PG8_MMA(ai, bj, At, Bt) do { __builtin_amdgcn_s_setprio(1); _Pragma("unroll") for (int m = 0; m < 4; ++m) _Pragma("unroll") for (int n = 0; n < 2; ++n) _Pragma("unroll") for (int k = 0; k < 2; ++k) \
;         acc[ai][bj][m][n] = __builtin_amdgcn_mfma_f32_16x16x32_bf16(Bt[n][k], At[m][k], acc[ai][bj][m][n], 0, 0, 0); __builtin_amdgcn_s_setprio(0); } while (0)
; #define PG8_WAIT_V(n) asm volatile("s_waitcnt vmcnt(" #n ")" ::: "memory")
; #define PG8_WAIT_L(n) asm volatile("s_waitcnt lgkmcnt(" #n ")" ::: "memory")
; #define PG8_BAR __builtin_amdgcn_s_barrier()
; #define PG8_SCHED __builtin_amdgcn_sched_barrier(0)
; template <class Epi, class Sched, bool ALIGN_EPI = false, bool SP2 = false>
; __device__ __forceinline__ void gemm_phase(PG8_LAS unsigned char* lds, const Gemm g, const Sched& S, const Epi& E) {
;     ...
;             PG8_LDB(B0, 0, 0); PG8_LDB(B1, 0, 1); PG8_SCHED; PG8_LDA(At, 0, 0); PG8_STAGE(PG8_SA(1, 1), a1 + hstep, voffA);
;             PG8_WAIT_V(8); PG8_WAIT_L(0); PG8_BAR; PG8_MMA(0, 0, At, B0); PG8_MMA(0, 1, At, B1); PG8_BAR; PG8_SCHED;
.LBB0_1886:
	ds_read_b128 v[164:167], v135
	ds_read_b128 v[170:173], v135 offset:1024
	ds_read_b128 v[174:177], v135 offset:2048
	ds_read_b128 v[178:181], v135 offset:3072
	ds_read_b128 v[182:185], v168
	ds_read_b128 v[186:189], v168 offset:1024
	ds_read_b128 v[190:193], v168 offset:2048
	ds_read_b128 v[194:197], v168 offset:3072
	s_add_u32 s54, s52, 0xfffc0080
	s_addc_u32 s55, s53, -1
	s_cmp_eq_u32 s77, 12
	s_cselect_b32 s57, s23, s55
	s_cselect_b32 s56, s49, s54
	s_cselect_b32 s55, s25, s76
	s_cselect_b32 s54, s74, s75
	s_mov_b32 m0, s72
	v_lshl_add_u64 v[230:231], s[52:53], 0, v[160:161]
	ds_read_b128 v[198:201], v169
	ds_read_b128 v[202:205], v169 offset:1024
	ds_read_b128 v[206:209], v169 offset:2048
	ds_read_b128 v[210:213], v169 offset:3072
	ds_read_b128 v[214:217], v169 offset:4096
	ds_read_b128 v[218:221], v169 offset:5120
	ds_read_b128 v[222:225], v169 offset:6144
	ds_read_b128 v[226:229], v169 offset:7168
	global_load_lds_dwordx4 v[230:231], off
	v_lshl_add_u64 v[230:231], s[52:53], 0, v[162:163]
	s_mov_b32 m0, s73
	s_nop 0
	global_load_lds_dwordx4 v[230:231], off
	s_waitcnt vmcnt(8)
	s_waitcnt lgkmcnt(0)
	s_barrier
	s_setprio 1
	s_waitcnt lgkmcnt(0)
	s_cmp_eq_u32 s92, 1
	s_cbranch_scc1 .Lms16_b0
	v_mfma_f32_16x16x32_bf16 v[124:127], v[164:167], v[198:201], v[124:127]
	v_mfma_f32_16x16x32_bf16 v[120:123], v[174:177], v[198:201], v[120:123]
	v_mfma_f32_16x16x32_bf16 v[108:111], v[164:167], v[206:209], v[108:111]
	v_mfma_f32_16x16x32_bf16 v[104:107], v[174:177], v[206:209], v[104:107]
	v_mfma_f32_16x16x32_bf16 v[92:95], v[164:167], v[214:217], v[92:95]
	v_mfma_f32_16x16x32_bf16 v[88:91], v[174:177], v[214:217], v[88:91]
	v_mfma_f32_16x16x32_bf16 v[76:79], v[164:167], v[222:225], v[76:79]
	v_mfma_f32_16x16x32_bf16 v[72:75], v[174:177], v[222:225], v[72:75]
	v_mfma_f32_16x16x32_bf16 v[124:127], v[170:173], v[202:205], v[124:127]
	v_mfma_f32_16x16x32_bf16 v[120:123], v[178:181], v[202:205], v[120:123]
	v_mfma_f32_16x16x32_bf16 v[108:111], v[170:173], v[210:213], v[108:111]
	v_mfma_f32_16x16x32_bf16 v[104:107], v[178:181], v[210:213], v[104:107]
	v_mfma_f32_16x16x32_bf16 v[92:95], v[170:173], v[218:221], v[92:95]
	v_mfma_f32_16x16x32_bf16 v[88:91], v[178:181], v[218:221], v[88:91]
	v_mfma_f32_16x16x32_bf16 v[76:79], v[170:173], v[226:229], v[76:79]
	v_mfma_f32_16x16x32_bf16 v[72:75], v[178:181], v[226:229], v[72:75]
.Lms16_b0:
	s_setprio 0
	s_setprio 1
	s_cmp_eq_u32 s92, 1
	s_cbranch_scc1 .Lms16_b1
	v_mfma_f32_16x16x32_bf16 v[116:119], v[182:185], v[198:201], v[116:119]
	v_mfma_f32_16x16x32_bf16 v[112:115], v[190:193], v[198:201], v[112:115]
	v_mfma_f32_16x16x32_bf16 v[100:103], v[182:185], v[206:209], v[100:103]
	v_mfma_f32_16x16x32_bf16 v[96:99], v[190:193], v[206:209], v[96:99]
	v_mfma_f32_16x16x32_bf16 v[84:87], v[182:185], v[214:217], v[84:87]
	v_mfma_f32_16x16x32_bf16 v[80:83], v[190:193], v[214:217], v[80:83]
	v_mfma_f32_16x16x32_bf16 v[68:71], v[182:185], v[222:225], v[68:71]
	v_mfma_f32_16x16x32_bf16 v[64:67], v[190:193], v[222:225], v[64:67]
	v_mfma_f32_16x16x32_bf16 v[116:119], v[186:189], v[202:205], v[116:119]
	v_mfma_f32_16x16x32_bf16 v[112:115], v[194:197], v[202:205], v[112:115]
	v_mfma_f32_16x16x32_bf16 v[100:103], v[186:189], v[210:213], v[100:103]
	v_mfma_f32_16x16x32_bf16 v[96:99], v[194:197], v[210:213], v[96:99]
	v_mfma_f32_16x16x32_bf16 v[84:87], v[186:189], v[218:221], v[84:87]
	v_mfma_f32_16x16x32_bf16 v[80:83], v[194:197], v[218:221], v[80:83]
	v_mfma_f32_16x16x32_bf16 v[68:71], v[186:189], v[226:229], v[68:71]
	v_mfma_f32_16x16x32_bf16 v[64:67], v[194:197], v[226:229], v[64:67]
; #define PG8_STAGE(bufoff, gbase, voff) do { _Pragma("unroll") for (int _i = 0; _i < 2; ++_i) \
;         __builtin_amdgcn_global_load_lds((const unsigned*)((const char*)(gbase) + (voff)[_i]), (PG8_LAS unsigned*)(lds + (bufoff) + ldsw + _i * 8192), 16, 0, 0); } while (0)
; #define PG8_LDA(dst, b, h) do { _Pragma("unroll") for (int m = 0; m < 4; ++m) _Pragma("unroll") for (int k = 0; k < 2; ++k) dst[m][k] = *(const PG8_LAS bf16x8*)(lds + PG8_SA(b, h) + aoff + m * 2048 + k * 1024); } while (0)
; #define PG8_LDB(dst, b, h) do { _Pragma("unroll") for (int n = 0; n < 2; ++n) _Pragma("unroll") for (int k = 0; k < 2; ++k) dst[n][k] = *(const PG8_LAS bf16x8*)(lds + PG8_SB(b, h) + boff + n * 2048 + k * 1024); } while (0)
; #define PG8_MMA(ai, bj, At, Bt) do { __builtin_amdgcn_s_setprio(1); _Pragma("unroll") for (int m = 0; m < 4; ++m) _Pragma("unroll") for (int n = 0; n < 2; ++n) _Pragma("unroll") for (int k = 0; k < 2; ++k) \
;         acc[ai][bj][m][n] = __builtin_amdgcn_mfma_f32_16x16x32_bf16(Bt[n][k], At[m][k], acc[ai][bj][m][n], 0, 0, 0); __builtin_amdgcn_s_setprio(0); } while (0)
; #define PG8_WAIT_V(n) asm volatile("s_waitcnt vmcnt(" #n ")" ::: "memory")
; #define PG8_WAIT_L(n) asm volatile("s_waitcnt lgkmcnt(" #n ")" ::: "memory")
; #define PG8_BAR __builtin_amdgcn_s_barrier()
; #define PG8_SCHED __builtin_amdgcn_sched_barrier(0)
; template <class Epi, class Sched, bool ALIGN_EPI = false, bool SP2 = false>
; __device__ __forceinline__ void gemm_phase(PG8_LAS unsigned char* lds, const Gemm g, const Sched& S, const Epi& E) {
;     ...
;             PG8_LDA(At, 0, 1); PG8_STAGE(PG8_SB(0, 0), b2, voffB); PG8_STAGE(PG8_SB(0, 1), b2 + hstep, voffB); PG8_STAGE(PG8_SA(0, 0), a2, voffA);
;             PG8_WAIT_V(8); PG8_WAIT_L(0); PG8_BAR; PG8_MMA(1, 0, At, B0); PG8_MMA(1, 1, At, B1); PG8_BAR; PG8_SCHED;
;             PG8_LDB(B0, 1, 0); PG8_LDB(B1, 1, 1); PG8_SCHED; PG8_LDA(At, 1, 0); PG8_STAGE(PG8_SA(0, 1), a2 + hstep, voffA);
;             PG8_WAIT_V(8); PG8_WAIT_L(0); PG8_BAR; PG8_MMA(0, 0, At, B0); PG8_MMA(0, 1, At, B1); PG8_BAR; PG8_SCHED;
.Lms16_b1:
	s_setprio 0
	s_barrier
	s_add_i32 s78, s70, s60
	v_lshl_add_u64 v[230:231], s[54:55], 0, v[140:141]
	s_mov_b32 m0, s78
	ds_read_b128 v[198:201], v169 offset:16384
	ds_read_b128 v[202:205], v169 offset:17408
	ds_read_b128 v[206:209], v169 offset:18432
	ds_read_b128 v[210:213], v169 offset:19456
	ds_read_b128 v[214:217], v169 offset:20480
	ds_read_b128 v[218:221], v169 offset:21504
	ds_read_b128 v[222:225], v169 offset:22528
	ds_read_b128 v[226:229], v169 offset:23552
	global_load_lds_dwordx4 v[230:231], off
	s_add_i32 m0, s78, 0x2000
	s_add_u32 s78, s54, 0x40000
	v_lshl_add_u64 v[232:233], s[54:55], 0, v[136:137]
	s_addc_u32 s79, s55, 0
	s_add_i32 s80, s71, s60
	global_load_lds_dwordx4 v[232:233], off
	v_lshl_add_u64 v[234:235], s[78:79], 0, v[140:141]
	s_mov_b32 m0, s80
	v_lshl_add_u64 v[236:237], s[56:57], 0, v[138:139]
	global_load_lds_dwordx4 v[234:235], off
	v_lshl_add_u64 v[234:235], s[78:79], 0, v[136:137]
	s_add_i32 m0, s80, 0x2000
	s_nop 0
	global_load_lds_dwordx4 v[234:235], off
	v_lshl_add_u64 v[234:235], s[56:57], 0, v[142:143]
	s_mov_b32 m0, s51
	s_nop 0
	global_load_lds_dwordx4 v[234:235], off
	s_mov_b32 m0, s61
	s_nop 0
	global_load_lds_dwordx4 v[236:237], off
	s_waitcnt vmcnt(8)
	s_waitcnt lgkmcnt(0)
	s_barrier
	s_setprio 1
	s_waitcnt lgkmcnt(0)
	s_cmp_eq_u32 s92, 0
	s_cbranch_scc1 .Lms16_b2
	v_mfma_f32_16x16x32_bf16 v[60:63], v[164:167], v[198:201], v[60:63]
	v_mfma_f32_16x16x32_bf16 v[56:59], v[174:177], v[198:201], v[56:59]
	v_mfma_f32_16x16x32_bf16 v[44:47], v[164:167], v[206:209], v[44:47]
	v_mfma_f32_16x16x32_bf16 v[40:43], v[174:177], v[206:209], v[40:43]
	v_mfma_f32_16x16x32_bf16 v[28:31], v[164:167], v[214:217], v[28:31]
	v_mfma_f32_16x16x32_bf16 v[24:27], v[174:177], v[214:217], v[24:27]
	v_mfma_f32_16x16x32_bf16 v[12:15], v[164:167], v[222:225], v[12:15]
	v_mfma_f32_16x16x32_bf16 v[8:11], v[174:177], v[222:225], v[8:11]
	v_mfma_f32_16x16x32_bf16 v[60:63], v[170:173], v[202:205], v[60:63]
	v_mfma_f32_16x16x32_bf16 v[56:59], v[178:181], v[202:205], v[56:59]
	v_mfma_f32_16x16x32_bf16 v[44:47], v[170:173], v[210:213], v[44:47]
	v_mfma_f32_16x16x32_bf16 v[40:43], v[178:181], v[210:213], v[40:43]
	v_mfma_f32_16x16x32_bf16 v[28:31], v[170:173], v[218:221], v[28:31]
	v_mfma_f32_16x16x32_bf16 v[24:27], v[178:181], v[218:221], v[24:27]
	v_mfma_f32_16x16x32_bf16 v[12:15], v[170:173], v[226:229], v[12:15]
	v_mfma_f32_16x16x32_bf16 v[8:11], v[178:181], v[226:229], v[8:11]
.Lms16_b2:
	s_setprio 0
	s_setprio 1
	s_cmp_eq_u32 s92, 0
	s_cbranch_scc1 .Lms16_b3
	v_mfma_f32_16x16x32_bf16 v[52:55], v[182:185], v[198:201], v[52:55]
	v_mfma_f32_16x16x32_bf16 v[48:51], v[190:193], v[198:201], v[48:51]
	v_mfma_f32_16x16x32_bf16 v[36:39], v[182:185], v[206:209], v[36:39]
	v_mfma_f32_16x16x32_bf16 v[32:35], v[190:193], v[206:209], v[32:35]
	v_mfma_f32_16x16x32_bf16 v[20:23], v[182:185], v[214:217], v[20:23]
	v_mfma_f32_16x16x32_bf16 v[16:19], v[190:193], v[214:217], v[16:19]
	v_mfma_f32_16x16x32_bf16 v[4:7], v[182:185], v[222:225], v[4:7]
	v_mfma_f32_16x16x32_bf16 v[0:3], v[190:193], v[222:225], v[0:3]
	v_mfma_f32_16x16x32_bf16 v[52:55], v[186:189], v[202:205], v[52:55]
	v_mfma_f32_16x16x32_bf16 v[48:51], v[194:197], v[202:205], v[48:51]
	v_mfma_f32_16x16x32_bf16 v[36:39], v[186:189], v[210:213], v[36:39]
	v_mfma_f32_16x16x32_bf16 v[32:35], v[194:197], v[210:213], v[32:35]
	v_mfma_f32_16x16x32_bf16 v[20:23], v[186:189], v[218:221], v[20:23]
	v_mfma_f32_16x16x32_bf16 v[16:19], v[194:197], v[218:221], v[16:19]
	v_mfma_f32_16x16x32_bf16 v[4:7], v[186:189], v[226:229], v[4:7]
	v_mfma_f32_16x16x32_bf16 v[0:3], v[194:197], v[226:229], v[0:3]
.Lms16_b3:
	s_setprio 0
	s_barrier
	s_add_i32 s78, 0, 0x18000
	s_add_i32 s79, 0, 0x1c000
	v_add_u32_e32 v178, s78, v129
	v_add_u32_e32 v194, s79, v129
	ds_read_b128 v[164:167], v178
	ds_read_b128 v[170:173], v178 offset:1024
	ds_read_b128 v[174:177], v178 offset:2048
	ds_read_b128 v[178:181], v178 offset:3072
	ds_read_b128 v[182:185], v194
	ds_read_b128 v[186:189], v194 offset:1024
	ds_read_b128 v[190:193], v194 offset:2048
	ds_read_b128 v[194:197], v194 offset:3072
	s_add_u32 s56, s56, 0x40000
	s_addc_u32 s57, s57, 0
	s_mov_b32 m0, s62
	v_lshl_add_u64 v[238:239], s[56:57], 0, v[142:143]
	ds_read_b128 v[198:201], v169 offset:32768
	ds_read_b128 v[202:205], v169 offset:33792
	ds_read_b128 v[206:209], v169 offset:34816
	ds_read_b128 v[210:213], v169 offset:35840
	ds_read_b128 v[214:217], v169 offset:36864
	ds_read_b128 v[218:221], v169 offset:37888
	ds_read_b128 v[222:225], v169 offset:38912
	ds_read_b128 v[226:229], v169 offset:39936
	global_load_lds_dwordx4 v[238:239], off
	v_lshl_add_u64 v[238:239], s[56:57], 0, v[138:139]
	s_mov_b32 m0, s63
	s_nop 0
	global_load_lds_dwordx4 v[238:239], off
	s_waitcnt vmcnt(8)
	s_waitcnt lgkmcnt(0)
	s_barrier
	s_setprio 1
	s_waitcnt lgkmcnt(0)
	s_cmp_eq_u32 s92, 1
	s_cbranch_scc1 .Lms16_b4
	v_mfma_f32_16x16x32_bf16 v[124:127], v[164:167], v[198:201], v[124:127]
	v_mfma_f32_16x16x32_bf16 v[120:123], v[174:177], v[198:201], v[120:123]
	v_mfma_f32_16x16x32_bf16 v[108:111], v[164:167], v[206:209], v[108:111]
	v_mfma_f32_16x16x32_bf16 v[104:107], v[174:177], v[206:209], v[104:107]
	v_mfma_f32_16x16x32_bf16 v[92:95], v[164:167], v[214:217], v[92:95]
	v_mfma_f32_16x16x32_bf16 v[88:91], v[174:177], v[214:217], v[88:91]
	v_mfma_f32_16x16x32_bf16 v[76:79], v[164:167], v[222:225], v[76:79]
	v_mfma_f32_16x16x32_bf16 v[72:75], v[174:177], v[222:225], v[72:75]
	v_mfma_f32_16x16x32_bf16 v[124:127], v[170:173], v[202:205], v[124:127]
	v_mfma_f32_16x16x32_bf16 v[120:123], v[178:181], v[202:205], v[120:123]
	v_mfma_f32_16x16x32_bf16 v[108:111], v[170:173], v[210:213], v[108:111]
	v_mfma_f32_16x16x32_bf16 v[104:107], v[178:181], v[210:213], v[104:107]
	v_mfma_f32_16x16x32_bf16 v[92:95], v[170:173], v[218:221], v[92:95]
	v_mfma_f32_16x16x32_bf16 v[88:91], v[178:181], v[218:221], v[88:91]
	v_mfma_f32_16x16x32_bf16 v[76:79], v[170:173], v[226:229], v[76:79]
	v_mfma_f32_16x16x32_bf16 v[72:75], v[178:181], v[226:229], v[72:75]

; #define PG8_STAGE(bufoff, gbase, voff) do { _Pragma("unroll") for (int _i = 0; _i < 2; ++_i) \
;         __builtin_amdgcn_global_load_lds((const unsigned*)((const char*)(gbase) + (voff)[_i]), (PG8_LAS unsigned*)(lds + (bufoff) + ldsw + _i * 8192), 16, 0, 0); } while (0)
; #define PG8_LDA(dst, b, h) do { _Pragma("unroll") for (int m = 0; m < 4; ++m) _Pragma("unroll") for (int k = 0; k < 2; ++k) dst[m][k] = *(const PG8_LAS bf16x8*)(lds + PG8_SA(b, h) + aoff + m * 2048 + k * 1024); } while (0)
; #define PG8_MMA(ai, bj, At, Bt) do { __builtin_amdgcn_s_setprio(1); _Pragma("unroll") for (int m = 0; m < 4; ++m) _Pragma("unroll") for (int n = 0; n < 2; ++n) _Pragma("unroll") for (int k = 0; k < 2; ++k) \
;         acc[ai][bj][m][n] = __builtin_amdgcn_mfma_f32_16x16x32_bf16(Bt[n][k], At[m][k], acc[ai][bj][m][n], 0, 0, 0); __builtin_amdgcn_s_setprio(0); } while (0)
; #define PG8_WAIT_V(n) asm volatile("s_waitcnt vmcnt(" #n ")" ::: "memory")
; #define PG8_WAIT_L(n) asm volatile("s_waitcnt lgkmcnt(" #n ")" ::: "memory")
; #define PG8_BAR __builtin_amdgcn_s_barrier()
; #define PG8_SCHED __builtin_amdgcn_sched_barrier(0)
; template <class Epi, class Sched, bool ALIGN_EPI = false, bool SP2 = false>
; __device__ __forceinline__ void gemm_phase(PG8_LAS unsigned char* lds, const Gemm g, const Sched& S, const Epi& E) {
;     ...
;             PG8_LDA(At, 1, 1); PG8_STAGE(PG8_SB(1, 0), b3, voffB); PG8_STAGE(PG8_SB(1, 1), b3 + hstep, voffB); PG8_STAGE(PG8_SA(1, 0), a3, voffA);
;             PG8_WAIT_V(8); PG8_WAIT_L(0); PG8_BAR; PG8_MMA(1, 0, At, B0); PG8_MMA(1, 1, At, B1); PG8_BAR; PG8_SCHED;
.Lms16_b5:
	s_setprio 0
	s_barrier
	s_add_i32 s56, s78, s60
	v_lshl_add_u64 v[230:231], v[230:231], 0, s[18:19]
	s_mov_b32 m0, s56
	ds_read_b128 v[198:201], v169 offset:49152
	ds_read_b128 v[202:205], v169 offset:50176
	ds_read_b128 v[206:209], v169 offset:51200
	ds_read_b128 v[210:213], v169 offset:52224
	ds_read_b128 v[214:217], v169 offset:53248
	ds_read_b128 v[218:221], v169 offset:54272
	ds_read_b128 v[222:225], v169 offset:55296
	ds_read_b128 v[226:229], v169 offset:56320
	global_load_lds_dwordx4 v[230:231], off
	s_add_i32 m0, s56, 0x2000
	s_add_u32 s54, s54, 0x40080
	v_lshl_add_u64 v[230:231], v[232:233], 0, s[18:19]
	s_addc_u32 s55, s55, 0
	s_add_i32 s56, s79, s60
	global_load_lds_dwordx4 v[230:231], off
	v_lshl_add_u64 v[230:231], s[54:55], 0, v[140:141]
	s_mov_b32 m0, s56
	s_nop 0
	global_load_lds_dwordx4 v[230:231], off
	v_lshl_add_u64 v[230:231], s[54:55], 0, v[136:137]
	s_add_i32 m0, s56, 0x2000
	s_nop 0
	global_load_lds_dwordx4 v[230:231], off
	v_lshl_add_u64 v[230:231], v[234:235], 0, s[18:19]
	s_mov_b32 m0, s65
	s_nop 0
	global_load_lds_dwordx4 v[230:231], off
	v_lshl_add_u64 v[230:231], v[236:237], 0, s[18:19]
	s_mov_b32 m0, s69
	s_nop 0
	global_load_lds_dwordx4 v[230:231], off
	s_waitcnt vmcnt(8)
	s_waitcnt lgkmcnt(0)
	s_barrier
	s_setprio 1
	s_waitcnt lgkmcnt(0)
	s_cmp_eq_u32 s92, 0
	s_cbranch_scc1 .Lms16_b6
	v_mfma_f32_16x16x32_bf16 v[60:63], v[164:167], v[198:201], v[60:63]
	v_mfma_f32_16x16x32_bf16 v[56:59], v[174:177], v[198:201], v[56:59]
	v_mfma_f32_16x16x32_bf16 v[44:47], v[164:167], v[206:209], v[44:47]
	v_mfma_f32_16x16x32_bf16 v[40:43], v[174:177], v[206:209], v[40:43]
	v_mfma_f32_16x16x32_bf16 v[28:31], v[164:167], v[214:217], v[28:31]
	v_mfma_f32_16x16x32_bf16 v[24:27], v[174:177], v[214:217], v[24:27]
	v_mfma_f32_16x16x32_bf16 v[12:15], v[164:167], v[222:225], v[12:15]
	v_mfma_f32_16x16x32_bf16 v[8:11], v[174:177], v[222:225], v[8:11]
	v_mfma_f32_16x16x32_bf16 v[60:63], v[170:173], v[202:205], v[60:63]
	v_mfma_f32_16x16x32_bf16 v[56:59], v[178:181], v[202:205], v[56:59]
	v_mfma_f32_16x16x32_bf16 v[44:47], v[170:173], v[210:213], v[44:47]
	v_mfma_f32_16x16x32_bf16 v[40:43], v[178:181], v[210:213], v[40:43]
	v_mfma_f32_16x16x32_bf16 v[28:31], v[170:173], v[218:221], v[28:31]
	v_mfma_f32_16x16x32_bf16 v[24:27], v[178:181], v[218:221], v[24:27]
	v_mfma_f32_16x16x32_bf16 v[12:15], v[170:173], v[226:229], v[12:15]
	v_mfma_f32_16x16x32_bf16 v[8:11], v[178:181], v[226:229], v[8:11]

; __device__ __forceinline__ void store8(bf16* p, f32x4 a, f32x4 b) { u32x4 w; w.x = pk2(a.x, a.y); w.y = pk2(a.z, a.w); w.z = pk2(b.x, b.y); w.w = pk2(b.z, b.w); *(u32x4*)p = w; }
; __device__ __forceinline__ float sigm(float x) { return __builtin_amdgcn_rcpf(1.f + __expf(-x)); }
; __device__ __forceinline__ float silu(float x) { return x * __builtin_amdgcn_rcpf(1.f + __expf(-x)); }
;     __device__ __forceinline__ void operator()(const f32x4 (&acc)[2][2][4][2], const Unit& u, int wr, int wc, int fr, int fq) const {
; #pragma unroll
;         for (int ai = 0; ai < 2; ++ai)
; #pragma unroll
;             for (int m = 0; m < 4; ++m)
; #pragma unroll
;                 for (int bj = 0; bj < 2; ++bj) f(u, ai * 128 + wr * 64 + m * 16 + fr, bj * 128 + wc * 32 + 8 * fq, acc[ai][bj][m][0], acc[ai][bj][m][1]);
;     }
;     __device__ __forceinline__ void operator()(const pg8::Unit& u, int rl, int cl, f32x4 v0, f32x4 v1) const {
;         const int col = u.pn * 256 + cl; const size_t off = ((size_t)u.pm * 256 + rl) * D + col;
;         const u32x4 yw = *(const u32x4*)(y + off), zw = *(const u32x4*)(z + off);
;         const f32x4 b0 = *(const f32x4*)(bias + col), b1 = *(const f32x4*)(bias + col + 4);
;         f32x4 r0, r1;
;         r0.x = lo_bf(yw.x) * sigm(v0.x + b0.x) * silu(lo_bf(zw.x)); r0.y = hi_bf(yw.x) * sigm(v0.y + b0.y) * silu(hi_bf(zw.x));
;         r0.z = lo_bf(yw.y) * sigm(v0.z + b0.z) * silu(lo_bf(zw.y)); r0.w = hi_bf(yw.y) * sigm(v0.w + b0.w) * silu(hi_bf(zw.y));
;         r1.x = lo_bf(yw.z) * sigm(v1.x + b1.x) * silu(lo_bf(zw.z)); r1.y = hi_bf(yw.z) * sigm(v1.y + b1.y) * silu(hi_bf(zw.z));
;         r1.z = lo_bf(yw.w) * sigm(v1.z + b1.z) * silu(lo_bf(zw.w)); r1.w = hi_bf(yw.w) * sigm(v1.w + b1.w) * silu(hi_bf(zw.w));
;         store8(o + off, r0, r1);
.Lms16_b7:
	s_setprio 0
	s_barrier
	s_add_i32 s77, s77, 2
	s_add_u32 s52, s52, 0x100
	s_addc_u32 s53, s53, 0
	s_add_u32 s75, s75, 0x100
	s_addc_u32 s76, s76, 0
	s_cmp_gt_u32 s77, 13
	s_cbranch_scc0 .LBB0_1886
	s_and_b64 vcc, exec, s[20:21]
	s_cbranch_vccz .LBB0_1889
	s_barrier
.LBB0_1889:
	s_ashr_i32 s49, s48, 31
	v_lshl_or_b32 v166, s50, 8, v133
	s_lshl_b64 s[48:49], s[48:49], 18
	v_ashrrev_i32_e32 v167, 31, v166
	v_lshl_add_u64 v[186:187], s[48:49], 0, v[144:145]
	v_lshl_add_u64 v[164:165], v[166:167], 2, s[10:11]
	v_lshl_add_u64 v[178:179], v[186:187], 0, v[166:167]
	global_load_dwordx4 v[170:173], v[164:165], off
	global_load_dwordx4 v[174:177], v[164:165], off offset:16
	v_lshlrev_b64 v[188:189], 1, v[178:179]
	v_lshl_add_u64 v[178:179], s[8:9], 0, v[188:189]
	v_lshl_add_u64 v[182:183], s[14:15], 0, v[188:189]
	global_load_dwordx4 v[178:181], v[178:179], off
	s_nop 0
	global_load_dwordx4 v[182:185], v[182:183], off
	s_andn2_b64 vcc, exec, s[44:45]
	s_mov_b64 s[44:45], -1
	s_waitcnt vmcnt(0)
	v_add_f32_e32 v124, v124, v170
	v_add_f32_e32 v120, v120, v174
	v_add_f32_e32 v126, v126, v172
	v_add_f32_e32 v127, v127, v173
	v_mul_f32_e32 v120, 0xbfb8aa3b, v120
	v_mul_f32_e32 v124, 0xbfb8aa3b, v124
	v_mul_f32_e32 v126, 0xbfb8aa3b, v126
	v_mul_f32_e32 v127, 0xbfb8aa3b, v127
	v_exp_f32_e32 v193, v120
	v_lshlrev_b32_e32 v120, 16, v182
	v_add_f32_e32 v125, v125, v171
	v_add_f32_e32 v122, v122, v176
	v_exp_f32_e32 v176, v124
	v_exp_f32_e32 v191, v126
	v_exp_f32_e32 v192, v127
	v_and_b32_e32 v124, 0xffff0000, v182
	v_lshlrev_b32_e32 v127, 16, v179
	v_lshlrev_b32_e32 v126, 16, v183
	v_and_b32_e32 v171, 0xffff0000, v179
	v_mul_f32_e32 v179, 0xbfb8aa3b, v120
	v_add_f32_e32 v121, v121, v175
	v_lshlrev_b32_e32 v173, 16, v180
	v_and_b32_e32 v175, 0xffff0000, v180
	v_mul_f32_e32 v180, 0xbfb8aa3b, v124
	v_mul_f32_e32 v182, 0xbfb8aa3b, v126
	v_exp_f32_e32 v179, v179
	v_exp_f32_e32 v180, v180
	v_exp_f32_e32 v182, v182
	v_mul_f32_e32 v125, 0xbfb8aa3b, v125
	v_and_b32_e32 v170, 0xffff0000, v183
	v_exp_f32_e32 v190, v125
	v_mul_f32_e32 v183, 0xbfb8aa3b, v170
	v_add_f32_e32 v176, 1.0, v176
	v_mul_f32_e32 v122, 0xbfb8aa3b, v122
	v_exp_f32_e32 v198, v183
	v_rcp_f32_e32 v183, v176
	v_add_f32_e32 v176, 1.0, v179
	v_exp_f32_e32 v122, v122
	v_add_f32_e32 v179, 1.0, v180
	v_add_f32_e32 v180, 1.0, v182
	v_rcp_f32_e32 v182, v176
	v_and_b32_e32 v174, 0xffff0000, v184
	v_mul_f32_e32 v121, 0xbfb8aa3b, v121
	v_mul_f32_e32 v195, 0xbfb8aa3b, v174
	v_add_f32_e32 v190, 1.0, v190
	v_exp_f32_e32 v194, v121
	v_lshlrev_b32_e32 v121, 16, v178
	v_exp_f32_e32 v200, v195
	v_add_f32_e32 v195, 1.0, v191
	v_rcp_f32_e32 v191, v190
	v_rcp_f32_e32 v190, v179
	v_add_f32_e32 v122, 1.0, v122
	v_pk_mul_f32 v[120:121], v[182:183], v[120:121]
	v_and_b32_e32 v125, 0xffff0000, v178
	v_mul_f32_e32 v176, v120, v121
	v_rcp_f32_e32 v121, v122
	v_add_f32_e32 v122, v123, v177
	v_lshlrev_b32_e32 v172, 16, v184
	v_lshlrev_b32_e32 v178, 16, v185
	v_mul_f32_e32 v122, 0xbfb8aa3b, v122
	v_mul_f32_e32 v184, 0xbfb8aa3b, v172
	v_mul_f32_e32 v196, 0xbfb8aa3b, v178
	v_add_f32_e32 v192, 1.0, v192
	v_pk_mul_f32 v[124:125], v[190:191], v[124:125]
	v_exp_f32_e32 v123, v122
	v_and_b32_e32 v122, 0xffff0000, v185
	v_exp_f32_e32 v184, v184
	v_exp_f32_e32 v201, v196
	v_add_f32_e32 v196, 1.0, v193
	v_rcp_f32_e32 v193, v195
	v_rcp_f32_e32 v195, v192
	v_rcp_f32_e32 v192, v180
	v_mul_f32_e32 v180, v124, v125
	v_mul_f32_e32 v124, 0xbfb8aa3b, v122
	v_exp_f32_e32 v124, v124
	v_add_f32_e32 v194, 1.0, v194
	v_rcp_f32_e32 v199, v194
	v_add_f32_e32 v194, 1.0, v198
	v_add_f32_e32 v184, 1.0, v184
	v_add_f32_e32 v120, 1.0, v201
	v_add_f32_e32 v123, 1.0, v123
	v_rcp_f32_e32 v197, v196
	v_rcp_f32_e32 v194, v194
	v_rcp_f32_e32 v196, v184
	v_rcp_f32_e32 v120, v120
	v_rcp_f32_e32 v125, v123
	v_add_f32_e32 v123, 1.0, v124
	v_add_f32_e32 v198, 1.0, v200
	v_rcp_f32_e32 v124, v123
	v_rcp_f32_e32 v198, v198
	v_lshlrev_b32_e32 v179, 16, v181
	v_pk_mul_f32 v[126:127], v[192:193], v[126:127]
	v_pk_mul_f32 v[170:171], v[194:195], v[170:171]
	v_pk_mul_f32 v[172:173], v[196:197], v[172:173]
	v_pk_mul_f32 v[120:121], v[120:121], v[178:179]
	v_and_b32_e32 v123, 0xffff0000, v181
	v_mul_f32_e32 v126, v126, v127
	v_mul_f32_e32 v127, v170, v171
	v_mul_f32_e32 v170, v172, v173
	v_mul_f32_e32 v172, v120, v121
	v_pk_mul_f32 v[120:121], v[124:125], v[122:123]
	v_pk_mul_f32 v[174:175], v[198:199], v[174:175]
	v_mul_f32_e32 v123, v120, v121
	v_lshl_add_u64 v[124:125], s[16:17], 0, v[188:189]
	v_cvt_pk_bf16_f32 v120, v176, v180
	v_mul_f32_e32 v171, v174, v175
	v_cvt_pk_bf16_f32 v121, v126, v127
	v_cvt_pk_bf16_f32 v122, v170, v171
	v_cvt_pk_bf16_f32 v123, v172, v123
	s_mov_b64 exec, s[88:89]
	global_store_dwordx4 v[124:125], v[120:123], off
	s_mov_b64 exec, -1
	s_nop 1
	v_or_b32_e32 v120, 0x80, v166
	v_ashrrev_i32_e32 v121, 31, v120
	v_lshl_add_u64 v[122:123], v[186:187], 0, v[120:121]
	v_lshlrev_b64 v[126:127], 1, v[122:123]
	v_lshl_add_u64 v[170:171], s[8:9], 0, v[126:127]
	v_lshl_add_u64 v[174:175], s[14:15], 0, v[126:127]
	global_load_dwordx4 v[122:125], v[164:165], off offset:512
	s_nop 0
	global_load_dwordx4 v[170:173], v[170:171], off
	s_nop 0
	global_load_dwordx4 v[174:177], v[174:175], off
	s_nop 0
	global_load_dwordx4 v[178:181], v[164:165], off offset:528
	s_waitcnt vmcnt(3)
	v_add_f32_e32 v184, v116, v122
	v_add_f32_e32 v185, v117, v123
	s_waitcnt vmcnt(1)
	v_lshlrev_b32_e32 v182, 16, v174
	v_and_b32_e32 v116, 0xffff0000, v174
	v_lshlrev_b32_e32 v183, 16, v170
	v_and_b32_e32 v117, 0xffff0000, v170
	v_add_f32_e32 v170, v118, v124
	v_lshlrev_b32_e32 v123, 16, v171
	v_lshlrev_b32_e32 v122, 16, v175
	v_add_f32_e32 v125, v119, v125
	v_and_b32_e32 v119, 0xffff0000, v171
	v_and_b32_e32 v118, 0xffff0000, v175
	s_waitcnt vmcnt(0)
; __device__ __forceinline__ void store8(bf16* p, f32x4 a, f32x4 b) { u32x4 w; w.x = pk2(a.x, a.y); w.y = pk2(a.z, a.w); w.z = pk2(b.x, b.y); w.w = pk2(b.z, b.w); *(u32x4*)p = w; }
; __device__ __forceinline__ float sigm(float x) { return __builtin_amdgcn_rcpf(1.f + __expf(-x)); }
; __device__ __forceinline__ float silu(float x) { return x * __builtin_amdgcn_rcpf(1.f + __expf(-x)); }
;     __device__ __forceinline__ void operator()(const pg8::Unit& u, int rl, int cl, f32x4 v0, f32x4 v1) const {
;         const int col = u.pn * 256 + cl; const size_t off = ((size_t)u.pm * 256 + rl) * D + col;
;         const u32x4 yw = *(const u32x4*)(y + off), zw = *(const u32x4*)(z + off);
;         const f32x4 b0 = *(const f32x4*)(bias + col), b1 = *(const f32x4*)(bias + col + 4);
;         f32x4 r0, r1;
;         r0.x = lo_bf(yw.x) * sigm(v0.x + b0.x) * silu(lo_bf(zw.x)); r0.y = hi_bf(yw.x) * sigm(v0.y + b0.y) * silu(hi_bf(zw.x));
;         r0.z = lo_bf(yw.y) * sigm(v0.z + b0.z) * silu(lo_bf(zw.y)); r0.w = hi_bf(yw.y) * sigm(v0.w + b0.w) * silu(hi_bf(zw.y));
;         r1.x = lo_bf(yw.z) * sigm(v1.x + b1.x) * silu(lo_bf(zw.z)); r1.y = hi_bf(yw.z) * sigm(v1.y + b1.y) * silu(hi_bf(zw.z));
;         r1.z = lo_bf(yw.w) * sigm(v1.z + b1.z) * silu(lo_bf(zw.w)); r1.w = hi_bf(yw.w) * sigm(v1.w + b1.w) * silu(hi_bf(zw.w));
;         store8(o + off, r0, r1);
	v_add_f32_e32 v112, v112, v178
	v_mul_f32_e32 v171, 0xbfb8aa3b, v184
	v_mul_f32_e32 v174, 0xbfb8aa3b, v182
	v_mul_f32_e32 v175, 0xbfb8aa3b, v185
	v_mul_f32_e32 v178, 0xbfb8aa3b, v116
	v_mul_f32_e32 v170, 0xbfb8aa3b, v170
	v_mul_f32_e32 v184, 0xbfb8aa3b, v122
	v_mul_f32_e32 v125, 0xbfb8aa3b, v125
	v_mul_f32_e32 v185, 0xbfb8aa3b, v118
	v_exp_f32_e32 v171, v171
	v_exp_f32_e32 v174, v174
	v_exp_f32_e32 v175, v175
	v_exp_f32_e32 v178, v178
	v_mul_f32_e32 v112, 0xbfb8aa3b, v112
	v_exp_f32_e32 v170, v170
	v_exp_f32_e32 v184, v184
	v_exp_f32_e32 v125, v125
	v_exp_f32_e32 v185, v185
	v_exp_f32_e32 v112, v112
	v_lshlrev_b32_e32 v124, 16, v176
	v_mul_f32_e32 v186, 0xbfb8aa3b, v124
	v_add_f32_e32 v171, 1.0, v171
	v_add_f32_e32 v174, 1.0, v174
	v_add_f32_e32 v175, 1.0, v175
	v_add_f32_e32 v178, 1.0, v178
	v_exp_f32_e32 v188, v186
	v_add_f32_e32 v186, 1.0, v170
	v_add_f32_e32 v184, 1.0, v184
	v_add_f32_e32 v125, 1.0, v125
	v_add_f32_e32 v189, 1.0, v185
	v_rcp_f32_e32 v171, v171
	v_rcp_f32_e32 v170, v174
	v_rcp_f32_e32 v175, v175
	v_rcp_f32_e32 v174, v178
	v_add_f32_e32 v112, 1.0, v112
	v_rcp_f32_e32 v185, v186
	v_rcp_f32_e32 v184, v184
	v_rcp_f32_e32 v187, v125
	v_rcp_f32_e32 v186, v189
	v_rcp_f32_e32 v189, v112
	v_add_f32_e32 v112, v113, v179
	v_mul_f32_e32 v112, 0xbfb8aa3b, v112
	v_pk_mul_f32 v[170:171], v[170:171], v[182:183]
	v_pk_mul_f32 v[116:117], v[174:175], v[116:117]
	v_exp_f32_e32 v113, v112
	v_and_b32_e32 v112, 0xffff0000, v176
	v_pk_mul_f32 v[122:123], v[184:185], v[122:123]
	v_pk_mul_f32 v[118:119], v[186:187], v[118:119]
	v_mul_f32_e32 v170, v170, v171
	v_mul_f32_e32 v171, v116, v117
	v_mul_f32_e32 v117, 0xbfb8aa3b, v112
	v_mul_f32_e32 v122, v122, v123
	v_mul_f32_e32 v123, v118, v119
	v_exp_f32_e32 v118, v117
	v_add_f32_e32 v113, 1.0, v113
	v_add_f32_e32 v116, 1.0, v188
	v_rcp_f32_e32 v117, v113
	v_add_f32_e32 v113, 1.0, v118
	v_rcp_f32_e32 v188, v116
	v_rcp_f32_e32 v116, v113
	v_and_b32_e32 v113, 0xffff0000, v172
	v_lshlrev_b32_e32 v125, 16, v172
	v_pk_mul_f32 v[118:119], v[188:189], v[124:125]
	v_pk_mul_f32 v[112:113], v[116:117], v[112:113]
	v_mul_f32_e32 v124, v118, v119
	v_mul_f32_e32 v125, v112, v113
	v_add_f32_e32 v112, v114, v180
	v_mul_f32_e32 v112, 0xbfb8aa3b, v112
	v_exp_f32_e32 v113, v112
	v_lshlrev_b32_e32 v112, 16, v177
	v_mul_f32_e32 v114, 0xbfb8aa3b, v112
	v_exp_f32_e32 v114, v114
	v_add_f32_e32 v113, 1.0, v113
	v_rcp_f32_e32 v117, v113
	v_lshlrev_b32_e32 v113, 16, v173
	v_add_f32_e32 v116, 1.0, v114
	v_add_f32_e32 v114, v115, v181
	v_mul_f32_e32 v114, 0xbfb8aa3b, v114
	v_exp_f32_e32 v115, v114
	v_and_b32_e32 v114, 0xffff0000, v177
	v_mul_f32_e32 v118, 0xbfb8aa3b, v114
	v_exp_f32_e32 v118, v118
	v_add_f32_e32 v115, 1.0, v115
	v_rcp_f32_e32 v116, v116
	v_rcp_f32_e32 v119, v115
	v_add_f32_e32 v115, 1.0, v118
	v_rcp_f32_e32 v118, v115
	v_pk_mul_f32 v[112:113], v[116:117], v[112:113]
	v_and_b32_e32 v115, 0xffff0000, v173
	v_mul_f32_e32 v172, v112, v113
	v_pk_mul_f32 v[112:113], v[118:119], v[114:115]
	v_lshl_add_u64 v[116:117], s[16:17], 0, v[126:127]
	v_mul_f32_e32 v115, v112, v113
	v_cvt_pk_bf16_f32 v112, v170, v171
	v_cvt_pk_bf16_f32 v113, v122, v123
	v_lshl_add_u64 v[126:127], s[48:49], 0, v[146:147]
	v_cvt_pk_bf16_f32 v114, v124, v125
	v_cvt_pk_bf16_f32 v115, v172, v115
	s_mov_b64 exec, s[88:89]
	global_store_dwordx4 v[116:117], v[112:115], off
	s_mov_b64 exec, -1
	s_nop 1
	v_lshl_add_u64 v[112:113], v[126:127], 0, v[166:167]
	v_lshlrev_b64 v[174:175], 1, v[112:113]
	v_lshl_add_u64 v[116:117], s[8:9], 0, v[174:175]
	v_lshl_add_u64 v[122:123], s[14:15], 0, v[174:175]
	global_load_dwordx4 v[112:115], v[164:165], off
	s_nop 0
	global_load_dwordx4 v[116:119], v[116:117], off
	s_nop 0
	global_load_dwordx4 v[122:125], v[122:123], off
	s_nop 0
	global_load_dwordx4 v[170:173], v[164:165], off offset:16
	s_waitcnt vmcnt(3)
	v_add_f32_e32 v178, v108, v112
	v_add_f32_e32 v179, v109, v113
	s_waitcnt vmcnt(1)
	v_and_b32_e32 v108, 0xffff0000, v122
	v_lshlrev_b32_e32 v176, 16, v122
	v_add_f32_e32 v110, v110, v114
	v_mul_f32_e32 v114, 0xbfb8aa3b, v178
	v_mul_f32_e32 v122, 0xbfb8aa3b, v179
	v_mul_f32_e32 v178, 0xbfb8aa3b, v108
	v_exp_f32_e32 v122, v122
	v_exp_f32_e32 v178, v178
	v_mul_f32_e32 v110, 0xbfb8aa3b, v110
	v_and_b32_e32 v109, 0xffff0000, v116
	v_add_f32_e32 v122, 1.0, v122
	v_add_f32_e32 v180, 1.0, v178
	v_rcp_f32_e32 v181, v122
	v_rcp_f32_e32 v180, v180
	v_exp_f32_e32 v110, v110
	v_lshlrev_b32_e32 v112, 16, v123
	v_mul_f32_e32 v179, 0xbfb8aa3b, v112
	v_pk_mul_f32 v[108:109], v[180:181], v[108:109]
	v_add_f32_e32 v110, 1.0, v110
	v_mul_f32_e32 v122, v108, v109
	v_add_f32_e32 v108, v111, v115
	v_mul_f32_e32 v108, 0xbfb8aa3b, v108
	v_exp_f32_e32 v109, v108
	v_and_b32_e32 v108, 0xffff0000, v123
	v_rcp_f32_e32 v183, v110
	v_mul_f32_e32 v110, 0xbfb8aa3b, v108
	v_exp_f32_e32 v110, v110
	v_exp_f32_e32 v114, v114
	v_exp_f32_e32 v182, v179
	s_waitcnt vmcnt(0)
; __device__ __forceinline__ void store8(bf16* p, f32x4 a, f32x4 b) { u32x4 w; w.x = pk2(a.x, a.y); w.y = pk2(a.z, a.w); w.z = pk2(b.x, b.y); w.w = pk2(b.z, b.w); *(u32x4*)p = w; }
; __device__ __forceinline__ float sigm(float x) { return __builtin_amdgcn_rcpf(1.f + __expf(-x)); }
; __device__ __forceinline__ float silu(float x) { return x * __builtin_amdgcn_rcpf(1.f + __expf(-x)); }
;     __device__ __forceinline__ void operator()(const pg8::Unit& u, int rl, int cl, f32x4 v0, f32x4 v1) const {
;         const int col = u.pn * 256 + cl; const size_t off = ((size_t)u.pm * 256 + rl) * D + col;
;         const u32x4 yw = *(const u32x4*)(y + off), zw = *(const u32x4*)(z + off);
;         const f32x4 b0 = *(const f32x4*)(bias + col), b1 = *(const f32x4*)(bias + col + 4);
;         f32x4 r0, r1;
;         r0.x = lo_bf(yw.x) * sigm(v0.x + b0.x) * silu(lo_bf(zw.x)); r0.y = hi_bf(yw.x) * sigm(v0.y + b0.y) * silu(hi_bf(zw.x));
;         r0.z = lo_bf(yw.y) * sigm(v0.z + b0.z) * silu(lo_bf(zw.y)); r0.w = hi_bf(yw.y) * sigm(v0.w + b0.w) * silu(hi_bf(zw.y));
;         r1.x = lo_bf(yw.z) * sigm(v1.x + b1.x) * silu(lo_bf(zw.z)); r1.y = hi_bf(yw.z) * sigm(v1.y + b1.y) * silu(hi_bf(zw.z));
;         r1.z = lo_bf(yw.w) * sigm(v1.z + b1.z) * silu(lo_bf(zw.w)); r1.w = hi_bf(yw.w) * sigm(v1.w + b1.w) * silu(hi_bf(zw.w));
;         store8(o + off, r0, r1);
	v_add_f32_e32 v104, v104, v170
	v_add_f32_e32 v109, 1.0, v109
	v_mul_f32_e32 v104, 0xbfb8aa3b, v104
	v_rcp_f32_e32 v111, v109
	v_add_f32_e32 v109, 1.0, v110
	v_exp_f32_e32 v104, v104
	v_add_f32_e32 v114, 1.0, v114
	v_rcp_f32_e32 v110, v109
	v_rcp_f32_e32 v179, v114
	v_add_f32_e32 v114, 1.0, v182
	v_rcp_f32_e32 v182, v114
	v_and_b32_e32 v109, 0xffff0000, v117
	v_add_f32_e32 v104, 1.0, v104
	v_pk_mul_f32 v[108:109], v[110:111], v[108:109]
	v_rcp_f32_e32 v111, v104
	v_add_f32_e32 v104, v105, v171
	v_lshlrev_b32_e32 v113, 16, v117
	v_mul_f32_e32 v104, 0xbfb8aa3b, v104
	v_pk_mul_f32 v[112:113], v[182:183], v[112:113]
	v_exp_f32_e32 v105, v104
	v_and_b32_e32 v104, 0xffff0000, v124
	v_mul_f32_e32 v114, v112, v113
	v_mul_f32_e32 v112, 0xbfb8aa3b, v104
	v_exp_f32_e32 v112, v112
	v_add_f32_e32 v105, 1.0, v105
	v_rcp_f32_e32 v113, v105
	v_mul_f32_e32 v115, v108, v109
	v_add_f32_e32 v105, 1.0, v112
	v_rcp_f32_e32 v112, v105
	v_lshlrev_b32_e32 v108, 16, v124
	v_mul_f32_e32 v109, 0xbfb8aa3b, v108
	v_exp_f32_e32 v110, v109
	v_and_b32_e32 v105, 0xffff0000, v118
	v_pk_mul_f32 v[104:105], v[112:113], v[104:105]
	v_lshlrev_b32_e32 v109, 16, v118
	v_mul_f32_e32 v112, v104, v105
	v_add_f32_e32 v104, v106, v172
	v_mul_f32_e32 v104, 0xbfb8aa3b, v104
	v_add_f32_e32 v110, 1.0, v110
	v_exp_f32_e32 v105, v104
	v_lshlrev_b32_e32 v104, 16, v125
	v_rcp_f32_e32 v110, v110
	v_mul_f32_e32 v106, 0xbfb8aa3b, v104
	v_exp_f32_e32 v106, v106
	v_lshlrev_b32_e32 v177, 16, v116
	v_pk_mul_f32 v[108:109], v[110:111], v[108:109]
	v_mul_f32_e32 v116, 0xbfb8aa3b, v176
	v_mul_f32_e32 v117, v108, v109
	v_add_f32_e32 v108, 1.0, v106
	v_add_f32_e32 v106, v107, v173
	v_mul_f32_e32 v106, 0xbfb8aa3b, v106
	v_exp_f32_e32 v107, v106
	v_and_b32_e32 v106, 0xffff0000, v125
	v_mul_f32_e32 v110, 0xbfb8aa3b, v106
	v_exp_f32_e32 v110, v110
	v_exp_f32_e32 v116, v116
	v_add_f32_e32 v105, 1.0, v105
	v_add_f32_e32 v107, 1.0, v107
	v_rcp_f32_e32 v109, v105
	v_rcp_f32_e32 v108, v108
	v_rcp_f32_e32 v111, v107
	v_add_f32_e32 v107, 1.0, v110
	v_add_f32_e32 v116, 1.0, v116
	v_rcp_f32_e32 v110, v107
	v_rcp_f32_e32 v178, v116
	v_lshlrev_b32_e32 v105, 16, v119
	v_pk_mul_f32 v[104:105], v[108:109], v[104:105]
	v_and_b32_e32 v107, 0xffff0000, v119
	v_mul_f32_e32 v113, v104, v105
	v_pk_mul_f32 v[104:105], v[110:111], v[106:107]
	v_pk_mul_f32 v[176:177], v[178:179], v[176:177]
	v_mul_f32_e32 v107, v104, v105
	v_lshl_add_u64 v[108:109], s[16:17], 0, v[174:175]
	v_mul_f32_e32 v116, v176, v177
	v_cvt_pk_bf16_f32 v104, v116, v122
	v_cvt_pk_bf16_f32 v105, v114, v115
	v_cvt_pk_bf16_f32 v106, v117, v112
	v_cvt_pk_bf16_f32 v107, v113, v107
	s_mov_b64 exec, s[88:89]
	global_store_dwordx4 v[108:109], v[104:107], off
	s_mov_b64 exec, -1
	global_load_dwordx4 v[104:107], v[164:165], off offset:512
	v_lshl_add_u64 v[108:109], v[126:127], 0, v[120:121]
	v_lshlrev_b64 v[122:123], 1, v[108:109]
	v_lshl_add_u64 v[108:109], s[14:15], 0, v[122:123]
	global_load_dwordx4 v[108:111], v[108:109], off
	v_lshl_add_u64 v[112:113], s[8:9], 0, v[122:123]
	global_load_dwordx4 v[112:115], v[112:113], off
	s_nop 0
	global_load_dwordx4 v[116:119], v[164:165], off offset:528
	s_waitcnt vmcnt(3)
	v_add_f32_e32 v100, v100, v104
	v_mul_f32_e32 v100, 0xbfb8aa3b, v100
	v_exp_f32_e32 v100, v100
	s_waitcnt vmcnt(2)
	v_lshlrev_b32_e32 v124, 16, v108
	v_mul_f32_e32 v104, 0xbfb8aa3b, v124
	v_add_f32_e32 v100, 1.0, v100
	v_rcp_f32_e32 v127, v100
	v_add_f32_e32 v100, v101, v105
	v_mul_f32_e32 v100, 0xbfb8aa3b, v100
	v_exp_f32_e32 v101, v100
	v_and_b32_e32 v100, 0xffff0000, v108
	v_mul_f32_e32 v105, 0xbfb8aa3b, v100
	v_exp_f32_e32 v104, v104
	v_exp_f32_e32 v108, v105
	v_add_f32_e32 v101, 1.0, v101
	v_rcp_f32_e32 v105, v101
	v_add_f32_e32 v104, 1.0, v104
	v_add_f32_e32 v101, 1.0, v108
	v_rcp_f32_e32 v126, v104
	v_rcp_f32_e32 v104, v101
	s_waitcnt vmcnt(1)
	v_and_b32_e32 v101, 0xffff0000, v112
	v_lshlrev_b32_e32 v125, 16, v112
	s_waitcnt vmcnt(0)
	v_add_f32_e32 v96, v96, v116
	v_pk_mul_f32 v[100:101], v[104:105], v[100:101]
	v_mul_f32_e32 v96, 0xbfb8aa3b, v96
	v_mul_f32_e32 v112, v100, v101
	v_add_f32_e32 v100, v102, v106
	v_mul_f32_e32 v100, 0xbfb8aa3b, v100
	v_exp_f32_e32 v101, v100
	v_lshlrev_b32_e32 v100, 16, v109
	v_mul_f32_e32 v102, 0xbfb8aa3b, v100
	v_exp_f32_e32 v102, v102
	v_add_f32_e32 v101, 1.0, v101
	v_rcp_f32_e32 v105, v101
	v_exp_f32_e32 v96, v96
	v_add_f32_e32 v104, 1.0, v102
	v_add_f32_e32 v102, v103, v107
	v_mul_f32_e32 v102, 0xbfb8aa3b, v102
	v_exp_f32_e32 v103, v102
	v_and_b32_e32 v102, 0xffff0000, v109
	v_mul_f32_e32 v106, 0xbfb8aa3b, v102
	v_exp_f32_e32 v106, v106
	v_add_f32_e32 v103, 1.0, v103
	v_rcp_f32_e32 v104, v104
	v_rcp_f32_e32 v107, v103
	v_add_f32_e32 v103, 1.0, v106
	v_rcp_f32_e32 v106, v103
	v_lshlrev_b32_e32 v101, 16, v113
	v_pk_mul_f32 v[100:101], v[104:105], v[100:101]
	v_and_b32_e32 v103, 0xffff0000, v113
	v_add_f32_e32 v96, 1.0, v96
	v_mul_f32_e32 v109, v100, v101
	v_pk_mul_f32 v[100:101], v[106:107], v[102:103]
	v_rcp_f32_e32 v103, v96
	v_add_f32_e32 v96, v97, v117
	v_mul_f32_e32 v96, 0xbfb8aa3b, v96
	v_exp_f32_e32 v97, v96
	v_and_b32_e32 v96, 0xffff0000, v110
	v_mul_f32_e32 v104, 0xbfb8aa3b, v96
	v_exp_f32_e32 v104, v104
	v_add_f32_e32 v97, 1.0, v97
	v_rcp_f32_e32 v105, v97
	v_mul_f32_e32 v106, v100, v101
	v_add_f32_e32 v97, 1.0, v104
	v_rcp_f32_e32 v104, v97
	v_lshlrev_b32_e32 v100, 16, v110
	v_mul_f32_e32 v101, 0xbfb8aa3b, v100
	v_exp_f32_e32 v102, v101
	v_and_b32_e32 v97, 0xffff0000, v114
	v_pk_mul_f32 v[96:97], v[104:105], v[96:97]
	v_lshlrev_b32_e32 v101, 16, v114
	v_mul_f32_e32 v104, v96, v97
	v_add_f32_e32 v96, v98, v118
	v_mul_f32_e32 v96, 0xbfb8aa3b, v96
	v_add_f32_e32 v102, 1.0, v102
	v_exp_f32_e32 v97, v96
; __device__ __forceinline__ void store8(bf16* p, f32x4 a, f32x4 b) { u32x4 w; w.x = pk2(a.x, a.y); w.y = pk2(a.z, a.w); w.z = pk2(b.x, b.y); w.w = pk2(b.z, b.w); *(u32x4*)p = w; }
; __device__ __forceinline__ float sigm(float x) { return __builtin_amdgcn_rcpf(1.f + __expf(-x)); }
; __device__ __forceinline__ float silu(float x) { return x * __builtin_amdgcn_rcpf(1.f + __expf(-x)); }
;     __device__ __forceinline__ void operator()(const pg8::Unit& u, int rl, int cl, f32x4 v0, f32x4 v1) const {
;         const int col = u.pn * 256 + cl; const size_t off = ((size_t)u.pm * 256 + rl) * D + col;
;         const u32x4 yw = *(const u32x4*)(y + off), zw = *(const u32x4*)(z + off);
;         const f32x4 b0 = *(const f32x4*)(bias + col), b1 = *(const f32x4*)(bias + col + 4);
;         f32x4 r0, r1;
;         r0.x = lo_bf(yw.x) * sigm(v0.x + b0.x) * silu(lo_bf(zw.x)); r0.y = hi_bf(yw.x) * sigm(v0.y + b0.y) * silu(hi_bf(zw.x));
;         r0.z = lo_bf(yw.y) * sigm(v0.z + b0.z) * silu(lo_bf(zw.y)); r0.w = hi_bf(yw.y) * sigm(v0.w + b0.w) * silu(hi_bf(zw.y));
;         r1.x = lo_bf(yw.z) * sigm(v1.x + b1.x) * silu(lo_bf(zw.z)); r1.y = hi_bf(yw.z) * sigm(v1.y + b1.y) * silu(hi_bf(zw.z));
;         r1.z = lo_bf(yw.w) * sigm(v1.z + b1.z) * silu(lo_bf(zw.w)); r1.w = hi_bf(yw.w) * sigm(v1.w + b1.w) * silu(hi_bf(zw.w));
;         store8(o + off, r0, r1);
	v_lshlrev_b32_e32 v96, 16, v111
	v_rcp_f32_e32 v102, v102
	v_mul_f32_e32 v98, 0xbfb8aa3b, v96
	v_exp_f32_e32 v98, v98
	v_add_f32_e32 v97, 1.0, v97
	v_pk_mul_f32 v[100:101], v[102:103], v[100:101]
	v_pk_mul_f32 v[124:125], v[126:127], v[124:125]
	v_mul_f32_e32 v107, v100, v101
	v_add_f32_e32 v100, 1.0, v98
	v_add_f32_e32 v98, v99, v119
	v_mul_f32_e32 v98, 0xbfb8aa3b, v98
	v_exp_f32_e32 v99, v98
	v_and_b32_e32 v98, 0xffff0000, v111
	v_mul_f32_e32 v102, 0xbfb8aa3b, v98
	v_exp_f32_e32 v102, v102
	v_add_f32_e32 v99, 1.0, v99
	v_rcp_f32_e32 v101, v97
	v_rcp_f32_e32 v100, v100
	v_rcp_f32_e32 v103, v99
	v_add_f32_e32 v99, 1.0, v102
	v_rcp_f32_e32 v102, v99
	v_lshlrev_b32_e32 v97, 16, v115
	v_pk_mul_f32 v[96:97], v[100:101], v[96:97]
	v_and_b32_e32 v99, 0xffff0000, v115
	v_mul_f32_e32 v105, v96, v97
	v_pk_mul_f32 v[96:97], v[102:103], v[98:99]
	v_lshl_add_u64 v[100:101], s[16:17], 0, v[122:123]
	v_mul_f32_e32 v99, v96, v97
	v_mul_f32_e32 v108, v124, v125
	v_cvt_pk_bf16_f32 v96, v108, v112
	v_cvt_pk_bf16_f32 v97, v109, v106
	v_cvt_pk_bf16_f32 v98, v107, v104
	v_cvt_pk_bf16_f32 v99, v105, v99
	s_mov_b64 exec, s[88:89]
	global_store_dwordx4 v[100:101], v[96:99], off
	s_mov_b64 exec, -1
	global_load_dwordx4 v[96:99], v[164:165], off
	v_lshl_add_u64 v[112:113], s[48:49], 0, v[148:149]
	v_lshl_add_u64 v[100:101], v[112:113], 0, v[166:167]
	v_lshlrev_b64 v[114:115], 1, v[100:101]
	v_lshl_add_u64 v[100:101], s[14:15], 0, v[114:115]
	global_load_dwordx4 v[100:103], v[100:101], off
	v_lshl_add_u64 v[104:105], s[8:9], 0, v[114:115]
	global_load_dwordx4 v[104:107], v[104:105], off
	s_nop 0
	global_load_dwordx4 v[108:111], v[164:165], off offset:16
	s_waitcnt vmcnt(3)
	v_add_f32_e32 v92, v92, v96
	v_mul_f32_e32 v92, 0xbfb8aa3b, v92
	v_exp_f32_e32 v92, v92
	s_waitcnt vmcnt(2)
	v_lshlrev_b32_e32 v116, 16, v100
	v_add_f32_e32 v92, 1.0, v92
	v_rcp_f32_e32 v119, v92
	v_add_f32_e32 v92, v93, v97
	v_mul_f32_e32 v92, 0xbfb8aa3b, v92
	v_exp_f32_e32 v93, v92
	v_and_b32_e32 v92, 0xffff0000, v100
	v_mul_f32_e32 v96, 0xbfb8aa3b, v116
	v_mul_f32_e32 v97, 0xbfb8aa3b, v92
	v_exp_f32_e32 v96, v96
	v_exp_f32_e32 v100, v97
	v_add_f32_e32 v93, 1.0, v93
	v_rcp_f32_e32 v97, v93
	v_add_f32_e32 v96, 1.0, v96
	v_add_f32_e32 v93, 1.0, v100
	v_rcp_f32_e32 v118, v96
	v_rcp_f32_e32 v96, v93
	s_waitcnt vmcnt(1)
	v_and_b32_e32 v93, 0xffff0000, v104
	v_lshlrev_b32_e32 v117, 16, v104
	s_waitcnt vmcnt(0)
	v_add_f32_e32 v88, v88, v108
	v_pk_mul_f32 v[92:93], v[96:97], v[92:93]
	v_mul_f32_e32 v88, 0xbfb8aa3b, v88
	v_mul_f32_e32 v104, v92, v93
	v_add_f32_e32 v92, v94, v98
	v_mul_f32_e32 v92, 0xbfb8aa3b, v92
	v_exp_f32_e32 v93, v92
	v_lshlrev_b32_e32 v92, 16, v101
	v_mul_f32_e32 v94, 0xbfb8aa3b, v92
	v_exp_f32_e32 v94, v94
	v_add_f32_e32 v93, 1.0, v93
	v_rcp_f32_e32 v97, v93
	v_exp_f32_e32 v88, v88
	v_add_f32_e32 v96, 1.0, v94
	v_add_f32_e32 v94, v95, v99
	v_mul_f32_e32 v94, 0xbfb8aa3b, v94
	v_exp_f32_e32 v95, v94
	v_and_b32_e32 v94, 0xffff0000, v101
	v_mul_f32_e32 v98, 0xbfb8aa3b, v94
	v_exp_f32_e32 v98, v98
	v_add_f32_e32 v95, 1.0, v95
	v_rcp_f32_e32 v96, v96
	v_rcp_f32_e32 v99, v95
	v_add_f32_e32 v95, 1.0, v98
	v_rcp_f32_e32 v98, v95
	v_lshlrev_b32_e32 v93, 16, v105
	v_pk_mul_f32 v[92:93], v[96:97], v[92:93]
	v_and_b32_e32 v95, 0xffff0000, v105
	v_add_f32_e32 v88, 1.0, v88
	v_mul_f32_e32 v101, v92, v93
	v_pk_mul_f32 v[92:93], v[98:99], v[94:95]
	v_rcp_f32_e32 v95, v88
	v_add_f32_e32 v88, v89, v109
	v_mul_f32_e32 v88, 0xbfb8aa3b, v88
	v_exp_f32_e32 v89, v88
	v_and_b32_e32 v88, 0xffff0000, v102
	v_mul_f32_e32 v96, 0xbfb8aa3b, v88
	v_exp_f32_e32 v96, v96
	v_add_f32_e32 v89, 1.0, v89
	v_rcp_f32_e32 v97, v89
	v_mul_f32_e32 v98, v92, v93
	v_add_f32_e32 v89, 1.0, v96
	v_rcp_f32_e32 v96, v89
	v_lshlrev_b32_e32 v92, 16, v102
	v_mul_f32_e32 v93, 0xbfb8aa3b, v92
	v_exp_f32_e32 v94, v93
	v_and_b32_e32 v89, 0xffff0000, v106
	v_pk_mul_f32 v[88:89], v[96:97], v[88:89]
	v_lshlrev_b32_e32 v93, 16, v106
	v_mul_f32_e32 v96, v88, v89
	v_add_f32_e32 v88, v90, v110
	v_mul_f32_e32 v88, 0xbfb8aa3b, v88
	v_add_f32_e32 v94, 1.0, v94
	v_exp_f32_e32 v89, v88
	v_lshlrev_b32_e32 v88, 16, v103
	v_rcp_f32_e32 v94, v94
	v_mul_f32_e32 v90, 0xbfb8aa3b, v88
	v_exp_f32_e32 v90, v90
	v_add_f32_e32 v89, 1.0, v89
	v_pk_mul_f32 v[92:93], v[94:95], v[92:93]
	v_pk_mul_f32 v[116:117], v[118:119], v[116:117]
	v_mul_f32_e32 v99, v92, v93
	v_add_f32_e32 v92, 1.0, v90
	v_add_f32_e32 v90, v91, v111
	v_mul_f32_e32 v90, 0xbfb8aa3b, v90
	v_exp_f32_e32 v91, v90
	v_and_b32_e32 v90, 0xffff0000, v103
	v_mul_f32_e32 v94, 0xbfb8aa3b, v90
	v_exp_f32_e32 v94, v94
	v_add_f32_e32 v91, 1.0, v91
	v_rcp_f32_e32 v93, v89
	v_rcp_f32_e32 v92, v92
	v_rcp_f32_e32 v95, v91
	v_add_f32_e32 v91, 1.0, v94
	v_rcp_f32_e32 v94, v91
	v_lshlrev_b32_e32 v89, 16, v107
	v_pk_mul_f32 v[88:89], v[92:93], v[88:89]
	v_and_b32_e32 v91, 0xffff0000, v107
	v_mul_f32_e32 v97, v88, v89
	v_pk_mul_f32 v[88:89], v[94:95], v[90:91]
	v_lshl_add_u64 v[92:93], s[16:17], 0, v[114:115]
	v_mul_f32_e32 v91, v88, v89
	v_mul_f32_e32 v100, v116, v117
	v_cvt_pk_bf16_f32 v88, v100, v104
	v_cvt_pk_bf16_f32 v89, v101, v98
	v_cvt_pk_bf16_f32 v90, v99, v96
	v_cvt_pk_bf16_f32 v91, v97, v91
	s_mov_b64 exec, s[88:89]
	global_store_dwordx4 v[92:93], v[88:91], off
	s_mov_b64 exec, -1
	global_load_dwordx4 v[88:91], v[164:165], off offset:512
	v_lshl_add_u64 v[92:93], v[112:113], 0, v[120:121]
	v_lshlrev_b64 v[104:105], 1, v[92:93]
	v_lshl_add_u64 v[92:93], s[14:15], 0, v[104:105]
	global_load_dwordx4 v[92:95], v[92:93], off
	v_lshl_add_u64 v[96:97], s[8:9], 0, v[104:105]
	global_load_dwordx4 v[96:99], v[96:97], off
	s_nop 0
	global_load_dwordx4 v[100:103], v[164:165], off offset:528
	s_waitcnt vmcnt(3)
; __device__ __forceinline__ void store8(bf16* p, f32x4 a, f32x4 b) { u32x4 w; w.x = pk2(a.x, a.y); w.y = pk2(a.z, a.w); w.z = pk2(b.x, b.y); w.w = pk2(b.z, b.w); *(u32x4*)p = w; }
; __device__ __forceinline__ float sigm(float x) { return __builtin_amdgcn_rcpf(1.f + __expf(-x)); }
; __device__ __forceinline__ float silu(float x) { return x * __builtin_amdgcn_rcpf(1.f + __expf(-x)); }
;     __device__ __forceinline__ void operator()(const pg8::Unit& u, int rl, int cl, f32x4 v0, f32x4 v1) const {
;         const int col = u.pn * 256 + cl; const size_t off = ((size_t)u.pm * 256 + rl) * D + col;
;         const u32x4 yw = *(const u32x4*)(y + off), zw = *(const u32x4*)(z + off);
;         const f32x4 b0 = *(const f32x4*)(bias + col), b1 = *(const f32x4*)(bias + col + 4);
;         f32x4 r0, r1;
;         r0.x = lo_bf(yw.x) * sigm(v0.x + b0.x) * silu(lo_bf(zw.x)); r0.y = hi_bf(yw.x) * sigm(v0.y + b0.y) * silu(hi_bf(zw.x));
;         r0.z = lo_bf(yw.y) * sigm(v0.z + b0.z) * silu(lo_bf(zw.y)); r0.w = hi_bf(yw.y) * sigm(v0.w + b0.w) * silu(hi_bf(zw.y));
;         r1.x = lo_bf(yw.z) * sigm(v1.x + b1.x) * silu(lo_bf(zw.z)); r1.y = hi_bf(yw.z) * sigm(v1.y + b1.y) * silu(hi_bf(zw.z));
;         r1.z = lo_bf(yw.w) * sigm(v1.z + b1.z) * silu(lo_bf(zw.w)); r1.w = hi_bf(yw.w) * sigm(v1.w + b1.w) * silu(hi_bf(zw.w));
;         store8(o + off, r0, r1);
	v_add_f32_e32 v84, v84, v88
	v_mul_f32_e32 v84, 0xbfb8aa3b, v84
	v_exp_f32_e32 v84, v84
	s_waitcnt vmcnt(2)
	v_lshlrev_b32_e32 v106, 16, v92
	v_mul_f32_e32 v88, 0xbfb8aa3b, v106
	v_add_f32_e32 v84, 1.0, v84
	v_rcp_f32_e32 v109, v84
	v_add_f32_e32 v84, v85, v89
	v_mul_f32_e32 v84, 0xbfb8aa3b, v84
	v_exp_f32_e32 v85, v84
	v_and_b32_e32 v84, 0xffff0000, v92
	v_mul_f32_e32 v89, 0xbfb8aa3b, v84
	v_exp_f32_e32 v88, v88
	v_exp_f32_e32 v92, v89
	v_add_f32_e32 v85, 1.0, v85
	v_rcp_f32_e32 v89, v85
	v_add_f32_e32 v88, 1.0, v88
	v_add_f32_e32 v85, 1.0, v92
	v_rcp_f32_e32 v108, v88
	v_rcp_f32_e32 v88, v85
	s_waitcnt vmcnt(1)
	v_and_b32_e32 v85, 0xffff0000, v96
	v_lshlrev_b32_e32 v107, 16, v96
	s_waitcnt vmcnt(0)
	v_add_f32_e32 v80, v80, v100
	v_pk_mul_f32 v[84:85], v[88:89], v[84:85]
	v_mul_f32_e32 v80, 0xbfb8aa3b, v80
	v_mul_f32_e32 v96, v84, v85
	v_add_f32_e32 v84, v86, v90
	v_mul_f32_e32 v84, 0xbfb8aa3b, v84
	v_exp_f32_e32 v85, v84
	v_lshlrev_b32_e32 v84, 16, v93
	v_mul_f32_e32 v86, 0xbfb8aa3b, v84
	v_exp_f32_e32 v86, v86
	v_add_f32_e32 v85, 1.0, v85
	v_rcp_f32_e32 v89, v85
	v_exp_f32_e32 v80, v80
	v_add_f32_e32 v88, 1.0, v86
	v_add_f32_e32 v86, v87, v91
	v_mul_f32_e32 v86, 0xbfb8aa3b, v86
	v_exp_f32_e32 v87, v86
	v_and_b32_e32 v86, 0xffff0000, v93
	v_mul_f32_e32 v90, 0xbfb8aa3b, v86
	v_exp_f32_e32 v90, v90
	v_add_f32_e32 v87, 1.0, v87
	v_rcp_f32_e32 v88, v88
	v_rcp_f32_e32 v91, v87
	v_add_f32_e32 v87, 1.0, v90
	v_rcp_f32_e32 v90, v87
	v_lshlrev_b32_e32 v85, 16, v97
	v_pk_mul_f32 v[84:85], v[88:89], v[84:85]
	v_and_b32_e32 v87, 0xffff0000, v97
	v_add_f32_e32 v80, 1.0, v80
	v_mul_f32_e32 v93, v84, v85
	v_pk_mul_f32 v[84:85], v[90:91], v[86:87]
	v_rcp_f32_e32 v87, v80
	v_add_f32_e32 v80, v81, v101
	v_mul_f32_e32 v80, 0xbfb8aa3b, v80
	v_exp_f32_e32 v81, v80
	v_and_b32_e32 v80, 0xffff0000, v94
	v_mul_f32_e32 v88, 0xbfb8aa3b, v80
	v_exp_f32_e32 v88, v88
	v_add_f32_e32 v81, 1.0, v81
	v_rcp_f32_e32 v89, v81
	v_mul_f32_e32 v90, v84, v85
	v_add_f32_e32 v81, 1.0, v88
	v_rcp_f32_e32 v88, v81
	v_lshlrev_b32_e32 v84, 16, v94
	v_mul_f32_e32 v85, 0xbfb8aa3b, v84
	v_exp_f32_e32 v86, v85
	v_and_b32_e32 v81, 0xffff0000, v98
	v_pk_mul_f32 v[80:81], v[88:89], v[80:81]
	v_lshlrev_b32_e32 v85, 16, v98
	v_mul_f32_e32 v88, v80, v81
	v_add_f32_e32 v80, v82, v102
	v_mul_f32_e32 v80, 0xbfb8aa3b, v80
	v_add_f32_e32 v86, 1.0, v86
	v_exp_f32_e32 v81, v80
	v_lshlrev_b32_e32 v80, 16, v95
	v_rcp_f32_e32 v86, v86
	v_mul_f32_e32 v82, 0xbfb8aa3b, v80
	v_exp_f32_e32 v82, v82
	v_add_f32_e32 v81, 1.0, v81
	v_pk_mul_f32 v[84:85], v[86:87], v[84:85]
	v_pk_mul_f32 v[106:107], v[108:109], v[106:107]
	v_mul_f32_e32 v91, v84, v85
	v_add_f32_e32 v84, 1.0, v82
	v_add_f32_e32 v82, v83, v103
	v_mul_f32_e32 v82, 0xbfb8aa3b, v82
	v_exp_f32_e32 v83, v82
	v_and_b32_e32 v82, 0xffff0000, v95
	v_mul_f32_e32 v86, 0xbfb8aa3b, v82
	v_exp_f32_e32 v86, v86
	v_add_f32_e32 v83, 1.0, v83
	v_rcp_f32_e32 v85, v81
	v_rcp_f32_e32 v84, v84
	v_rcp_f32_e32 v87, v83
	v_add_f32_e32 v83, 1.0, v86
	v_rcp_f32_e32 v86, v83
	v_lshlrev_b32_e32 v81, 16, v99
	v_pk_mul_f32 v[80:81], v[84:85], v[80:81]
	v_and_b32_e32 v83, 0xffff0000, v99
	v_mul_f32_e32 v89, v80, v81
	v_pk_mul_f32 v[80:81], v[86:87], v[82:83]
	v_lshl_add_u64 v[84:85], s[16:17], 0, v[104:105]
	v_mul_f32_e32 v83, v80, v81
	v_mul_f32_e32 v92, v106, v107
	v_cvt_pk_bf16_f32 v80, v92, v96
	v_cvt_pk_bf16_f32 v81, v93, v90
	v_cvt_pk_bf16_f32 v82, v91, v88
	v_cvt_pk_bf16_f32 v83, v89, v83
	s_mov_b64 exec, s[88:89]
	global_store_dwordx4 v[84:85], v[80:83], off
	s_mov_b64 exec, -1
	global_load_dwordx4 v[80:83], v[164:165], off
	v_lshl_add_u64 v[96:97], s[48:49], 0, v[150:151]
	v_lshl_add_u64 v[84:85], v[96:97], 0, v[166:167]
	v_lshlrev_b64 v[98:99], 1, v[84:85]
	v_lshl_add_u64 v[84:85], s[14:15], 0, v[98:99]
	global_load_dwordx4 v[84:87], v[84:85], off
	v_lshl_add_u64 v[88:89], s[8:9], 0, v[98:99]
	global_load_dwordx4 v[88:91], v[88:89], off
	s_nop 0
	global_load_dwordx4 v[92:95], v[164:165], off offset:16
	s_waitcnt vmcnt(3)
	v_add_f32_e32 v76, v76, v80
	v_mul_f32_e32 v76, 0xbfb8aa3b, v76
	v_exp_f32_e32 v76, v76
	s_waitcnt vmcnt(2)
	v_lshlrev_b32_e32 v100, 16, v84
	v_add_f32_e32 v76, 1.0, v76
	v_rcp_f32_e32 v103, v76
	v_add_f32_e32 v76, v77, v81
	v_mul_f32_e32 v76, 0xbfb8aa3b, v76
	v_exp_f32_e32 v77, v76
	v_and_b32_e32 v76, 0xffff0000, v84
	v_mul_f32_e32 v80, 0xbfb8aa3b, v100
	v_mul_f32_e32 v81, 0xbfb8aa3b, v76
	v_exp_f32_e32 v80, v80
	v_exp_f32_e32 v84, v81
	v_add_f32_e32 v77, 1.0, v77
	v_rcp_f32_e32 v81, v77
	v_add_f32_e32 v80, 1.0, v80
	v_add_f32_e32 v77, 1.0, v84
	v_rcp_f32_e32 v102, v80
	v_rcp_f32_e32 v80, v77
	s_waitcnt vmcnt(1)
	v_and_b32_e32 v77, 0xffff0000, v88
	v_lshlrev_b32_e32 v101, 16, v88
	s_waitcnt vmcnt(0)
; __device__ __forceinline__ void store8(bf16* p, f32x4 a, f32x4 b) { u32x4 w; w.x = pk2(a.x, a.y); w.y = pk2(a.z, a.w); w.z = pk2(b.x, b.y); w.w = pk2(b.z, b.w); *(u32x4*)p = w; }
; __device__ __forceinline__ float sigm(float x) { return __builtin_amdgcn_rcpf(1.f + __expf(-x)); }
; __device__ __forceinline__ float silu(float x) { return x * __builtin_amdgcn_rcpf(1.f + __expf(-x)); }
;     __device__ __forceinline__ void operator()(const pg8::Unit& u, int rl, int cl, f32x4 v0, f32x4 v1) const {
;         const int col = u.pn * 256 + cl; const size_t off = ((size_t)u.pm * 256 + rl) * D + col;
;         const u32x4 yw = *(const u32x4*)(y + off), zw = *(const u32x4*)(z + off);
;         const f32x4 b0 = *(const f32x4*)(bias + col), b1 = *(const f32x4*)(bias + col + 4);
;         f32x4 r0, r1;
;         r0.x = lo_bf(yw.x) * sigm(v0.x + b0.x) * silu(lo_bf(zw.x)); r0.y = hi_bf(yw.x) * sigm(v0.y + b0.y) * silu(hi_bf(zw.x));
;         r0.z = lo_bf(yw.y) * sigm(v0.z + b0.z) * silu(lo_bf(zw.y)); r0.w = hi_bf(yw.y) * sigm(v0.w + b0.w) * silu(hi_bf(zw.y));
;         r1.x = lo_bf(yw.z) * sigm(v1.x + b1.x) * silu(lo_bf(zw.z)); r1.y = hi_bf(yw.z) * sigm(v1.y + b1.y) * silu(hi_bf(zw.z));
;         r1.z = lo_bf(yw.w) * sigm(v1.z + b1.z) * silu(lo_bf(zw.w)); r1.w = hi_bf(yw.w) * sigm(v1.w + b1.w) * silu(hi_bf(zw.w));
;         store8(o + off, r0, r1);
	v_add_f32_e32 v72, v72, v92
	v_pk_mul_f32 v[76:77], v[80:81], v[76:77]
	v_mul_f32_e32 v72, 0xbfb8aa3b, v72
	v_mul_f32_e32 v88, v76, v77
	v_add_f32_e32 v76, v78, v82
	v_mul_f32_e32 v76, 0xbfb8aa3b, v76
	v_exp_f32_e32 v77, v76
	v_lshlrev_b32_e32 v76, 16, v85
	v_mul_f32_e32 v78, 0xbfb8aa3b, v76
	v_exp_f32_e32 v78, v78
	v_add_f32_e32 v77, 1.0, v77
	v_rcp_f32_e32 v81, v77
	v_exp_f32_e32 v72, v72
	v_add_f32_e32 v80, 1.0, v78
	v_add_f32_e32 v78, v79, v83
	v_mul_f32_e32 v78, 0xbfb8aa3b, v78
	v_exp_f32_e32 v79, v78
	v_and_b32_e32 v78, 0xffff0000, v85
	v_mul_f32_e32 v82, 0xbfb8aa3b, v78
	v_exp_f32_e32 v82, v82
	v_add_f32_e32 v79, 1.0, v79
	v_rcp_f32_e32 v80, v80
	v_rcp_f32_e32 v83, v79
	v_add_f32_e32 v79, 1.0, v82
	v_rcp_f32_e32 v82, v79
	v_lshlrev_b32_e32 v77, 16, v89
	v_pk_mul_f32 v[76:77], v[80:81], v[76:77]
	v_and_b32_e32 v79, 0xffff0000, v89
	v_add_f32_e32 v72, 1.0, v72
	v_mul_f32_e32 v85, v76, v77
	v_pk_mul_f32 v[76:77], v[82:83], v[78:79]
	v_rcp_f32_e32 v79, v72
	v_add_f32_e32 v72, v73, v93
	v_mul_f32_e32 v72, 0xbfb8aa3b, v72
	v_exp_f32_e32 v73, v72
	v_and_b32_e32 v72, 0xffff0000, v86
	v_mul_f32_e32 v80, 0xbfb8aa3b, v72
	v_exp_f32_e32 v80, v80
	v_add_f32_e32 v73, 1.0, v73
	v_rcp_f32_e32 v81, v73
	v_mul_f32_e32 v82, v76, v77
	v_add_f32_e32 v73, 1.0, v80
	v_rcp_f32_e32 v80, v73
	v_lshlrev_b32_e32 v76, 16, v86
	v_mul_f32_e32 v77, 0xbfb8aa3b, v76
	v_exp_f32_e32 v78, v77
	v_and_b32_e32 v73, 0xffff0000, v90
	v_pk_mul_f32 v[72:73], v[80:81], v[72:73]
	v_lshlrev_b32_e32 v77, 16, v90
	v_mul_f32_e32 v80, v72, v73
	v_add_f32_e32 v72, v74, v94
	v_mul_f32_e32 v72, 0xbfb8aa3b, v72
	v_add_f32_e32 v78, 1.0, v78
	v_exp_f32_e32 v73, v72
	v_lshlrev_b32_e32 v72, 16, v87
	v_rcp_f32_e32 v78, v78
	v_mul_f32_e32 v74, 0xbfb8aa3b, v72
	v_exp_f32_e32 v74, v74
	v_add_f32_e32 v73, 1.0, v73
	v_pk_mul_f32 v[76:77], v[78:79], v[76:77]
	v_pk_mul_f32 v[100:101], v[102:103], v[100:101]
	v_mul_f32_e32 v83, v76, v77
	v_add_f32_e32 v76, 1.0, v74
	v_add_f32_e32 v74, v75, v95
	v_mul_f32_e32 v74, 0xbfb8aa3b, v74
	v_exp_f32_e32 v75, v74
	v_and_b32_e32 v74, 0xffff0000, v87
	v_mul_f32_e32 v78, 0xbfb8aa3b, v74
	v_exp_f32_e32 v78, v78
	v_add_f32_e32 v75, 1.0, v75
	v_rcp_f32_e32 v77, v73
	v_rcp_f32_e32 v76, v76
	v_rcp_f32_e32 v79, v75
	v_add_f32_e32 v75, 1.0, v78
	v_rcp_f32_e32 v78, v75
	v_lshlrev_b32_e32 v73, 16, v91
	v_pk_mul_f32 v[72:73], v[76:77], v[72:73]
	v_and_b32_e32 v75, 0xffff0000, v91
	v_mul_f32_e32 v81, v72, v73
	v_pk_mul_f32 v[72:73], v[78:79], v[74:75]
	v_lshl_add_u64 v[76:77], s[16:17], 0, v[98:99]
	v_mul_f32_e32 v75, v72, v73
	v_mul_f32_e32 v84, v100, v101
	v_cvt_pk_bf16_f32 v72, v84, v88
	v_cvt_pk_bf16_f32 v73, v85, v82
	v_cvt_pk_bf16_f32 v74, v83, v80
	v_cvt_pk_bf16_f32 v75, v81, v75
	s_mov_b64 exec, s[88:89]
	global_store_dwordx4 v[76:77], v[72:75], off
	s_mov_b64 exec, -1
	global_load_dwordx4 v[72:75], v[164:165], off offset:512
	v_lshl_add_u64 v[76:77], v[96:97], 0, v[120:121]
	v_lshlrev_b64 v[88:89], 1, v[76:77]
	v_lshl_add_u64 v[76:77], s[14:15], 0, v[88:89]
	global_load_dwordx4 v[76:79], v[76:77], off
	v_lshl_add_u64 v[80:81], s[8:9], 0, v[88:89]
	global_load_dwordx4 v[80:83], v[80:81], off
	s_nop 0
	global_load_dwordx4 v[84:87], v[164:165], off offset:528
	s_waitcnt vmcnt(3)
	v_add_f32_e32 v68, v68, v72
	v_mul_f32_e32 v68, 0xbfb8aa3b, v68
	v_exp_f32_e32 v68, v68
	s_waitcnt vmcnt(2)
	v_lshlrev_b32_e32 v90, 16, v76
	v_mul_f32_e32 v72, 0xbfb8aa3b, v90
	v_add_f32_e32 v68, 1.0, v68
	v_rcp_f32_e32 v93, v68
	v_add_f32_e32 v68, v69, v73
	v_mul_f32_e32 v68, 0xbfb8aa3b, v68
	v_exp_f32_e32 v69, v68
	v_and_b32_e32 v68, 0xffff0000, v76
	v_mul_f32_e32 v73, 0xbfb8aa3b, v68
	v_exp_f32_e32 v72, v72
	v_exp_f32_e32 v76, v73
	v_add_f32_e32 v69, 1.0, v69
	v_rcp_f32_e32 v73, v69
	v_add_f32_e32 v72, 1.0, v72
	v_add_f32_e32 v69, 1.0, v76
	v_rcp_f32_e32 v92, v72
	v_rcp_f32_e32 v72, v69
	s_waitcnt vmcnt(1)
	v_and_b32_e32 v69, 0xffff0000, v80
	v_lshlrev_b32_e32 v91, 16, v80
	s_waitcnt vmcnt(0)
	v_add_f32_e32 v64, v64, v84
	v_pk_mul_f32 v[68:69], v[72:73], v[68:69]
	v_mul_f32_e32 v64, 0xbfb8aa3b, v64
	v_mul_f32_e32 v80, v68, v69
	v_add_f32_e32 v68, v70, v74
	v_mul_f32_e32 v68, 0xbfb8aa3b, v68
	v_exp_f32_e32 v69, v68
	v_lshlrev_b32_e32 v68, 16, v77
	v_mul_f32_e32 v70, 0xbfb8aa3b, v68
	v_exp_f32_e32 v70, v70
	v_add_f32_e32 v69, 1.0, v69
	v_rcp_f32_e32 v73, v69
	v_exp_f32_e32 v64, v64
	v_add_f32_e32 v72, 1.0, v70
	v_add_f32_e32 v70, v71, v75
	v_mul_f32_e32 v70, 0xbfb8aa3b, v70
	v_exp_f32_e32 v71, v70
	v_and_b32_e32 v70, 0xffff0000, v77
	v_mul_f32_e32 v74, 0xbfb8aa3b, v70
	v_exp_f32_e32 v74, v74
	v_add_f32_e32 v71, 1.0, v71
	v_rcp_f32_e32 v72, v72
	v_rcp_f32_e32 v75, v71
	v_add_f32_e32 v71, 1.0, v74
	v_rcp_f32_e32 v74, v71
	v_lshlrev_b32_e32 v69, 16, v81
	v_pk_mul_f32 v[68:69], v[72:73], v[68:69]
	v_and_b32_e32 v71, 0xffff0000, v81
	v_add_f32_e32 v64, 1.0, v64
	v_mul_f32_e32 v77, v68, v69
	v_pk_mul_f32 v[68:69], v[74:75], v[70:71]
	v_rcp_f32_e32 v71, v64
	v_add_f32_e32 v64, v65, v85
	v_mul_f32_e32 v64, 0xbfb8aa3b, v64
	v_exp_f32_e32 v65, v64
	v_and_b32_e32 v64, 0xffff0000, v78
	v_mul_f32_e32 v72, 0xbfb8aa3b, v64
	v_exp_f32_e32 v72, v72
	v_add_f32_e32 v65, 1.0, v65
	v_rcp_f32_e32 v73, v65
	v_mul_f32_e32 v74, v68, v69
	v_add_f32_e32 v65, 1.0, v72
	v_rcp_f32_e32 v72, v65
	v_lshlrev_b32_e32 v68, 16, v78
	v_mul_f32_e32 v69, 0xbfb8aa3b, v68
	v_exp_f32_e32 v70, v69
	v_and_b32_e32 v65, 0xffff0000, v82
	v_pk_mul_f32 v[64:65], v[72:73], v[64:65]
	v_lshlrev_b32_e32 v69, 16, v82
	v_mul_f32_e32 v72, v64, v65
	v_add_f32_e32 v64, v66, v86
	v_mul_f32_e32 v64, 0xbfb8aa3b, v64
	v_add_f32_e32 v70, 1.0, v70
	v_exp_f32_e32 v65, v64
	v_lshlrev_b32_e32 v64, 16, v79
	v_rcp_f32_e32 v70, v70
	v_mul_f32_e32 v66, 0xbfb8aa3b, v64
; __device__ __forceinline__ void store8(bf16* p, f32x4 a, f32x4 b) { u32x4 w; w.x = pk2(a.x, a.y); w.y = pk2(a.z, a.w); w.z = pk2(b.x, b.y); w.w = pk2(b.z, b.w); *(u32x4*)p = w; }
; __device__ __forceinline__ float sigm(float x) { return __builtin_amdgcn_rcpf(1.f + __expf(-x)); }
; __device__ __forceinline__ float silu(float x) { return x * __builtin_amdgcn_rcpf(1.f + __expf(-x)); }
;     __device__ __forceinline__ void operator()(const pg8::Unit& u, int rl, int cl, f32x4 v0, f32x4 v1) const {
;         const int col = u.pn * 256 + cl; const size_t off = ((size_t)u.pm * 256 + rl) * D + col;
;         const u32x4 yw = *(const u32x4*)(y + off), zw = *(const u32x4*)(z + off);
;         const f32x4 b0 = *(const f32x4*)(bias + col), b1 = *(const f32x4*)(bias + col + 4);
;         f32x4 r0, r1;
;         r0.x = lo_bf(yw.x) * sigm(v0.x + b0.x) * silu(lo_bf(zw.x)); r0.y = hi_bf(yw.x) * sigm(v0.y + b0.y) * silu(hi_bf(zw.x));
;         r0.z = lo_bf(yw.y) * sigm(v0.z + b0.z) * silu(lo_bf(zw.y)); r0.w = hi_bf(yw.y) * sigm(v0.w + b0.w) * silu(hi_bf(zw.y));
;         r1.x = lo_bf(yw.z) * sigm(v1.x + b1.x) * silu(lo_bf(zw.z)); r1.y = hi_bf(yw.z) * sigm(v1.y + b1.y) * silu(hi_bf(zw.z));
;         r1.z = lo_bf(yw.w) * sigm(v1.z + b1.z) * silu(lo_bf(zw.w)); r1.w = hi_bf(yw.w) * sigm(v1.w + b1.w) * silu(hi_bf(zw.w));
;         store8(o + off, r0, r1);
	v_exp_f32_e32 v66, v66
	v_add_f32_e32 v65, 1.0, v65
	v_pk_mul_f32 v[68:69], v[70:71], v[68:69]
	v_pk_mul_f32 v[90:91], v[92:93], v[90:91]
	v_mul_f32_e32 v75, v68, v69
	v_add_f32_e32 v68, 1.0, v66
	v_add_f32_e32 v66, v67, v87
	v_mul_f32_e32 v66, 0xbfb8aa3b, v66
	v_exp_f32_e32 v67, v66
	v_and_b32_e32 v66, 0xffff0000, v79
	v_mul_f32_e32 v70, 0xbfb8aa3b, v66
	v_exp_f32_e32 v70, v70
	v_add_f32_e32 v67, 1.0, v67
	v_rcp_f32_e32 v69, v65
	v_rcp_f32_e32 v68, v68
	v_rcp_f32_e32 v71, v67
	v_add_f32_e32 v67, 1.0, v70
	v_rcp_f32_e32 v70, v67
	v_lshlrev_b32_e32 v65, 16, v83
	v_pk_mul_f32 v[64:65], v[68:69], v[64:65]
	v_and_b32_e32 v67, 0xffff0000, v83
	v_mul_f32_e32 v73, v64, v65
	v_pk_mul_f32 v[64:65], v[70:71], v[66:67]
	v_lshl_add_u64 v[68:69], s[16:17], 0, v[88:89]
	v_mul_f32_e32 v67, v64, v65
	v_mul_f32_e32 v76, v90, v91
	v_cvt_pk_bf16_f32 v64, v76, v80
	v_cvt_pk_bf16_f32 v65, v77, v74
	v_cvt_pk_bf16_f32 v66, v75, v72
	v_cvt_pk_bf16_f32 v67, v73, v67
	s_mov_b64 exec, s[88:89]
	global_store_dwordx4 v[68:69], v[64:67], off
	s_mov_b64 exec, -1
	global_load_dwordx4 v[64:67], v[164:165], off
	v_lshl_add_u64 v[80:81], s[48:49], 0, v[152:153]
	v_lshl_add_u64 v[68:69], v[80:81], 0, v[166:167]
	v_lshlrev_b64 v[82:83], 1, v[68:69]
	v_lshl_add_u64 v[68:69], s[14:15], 0, v[82:83]
	global_load_dwordx4 v[68:71], v[68:69], off
	v_lshl_add_u64 v[72:73], s[8:9], 0, v[82:83]
	global_load_dwordx4 v[72:75], v[72:73], off
	s_nop 0
	global_load_dwordx4 v[76:79], v[164:165], off offset:16
	s_waitcnt vmcnt(3)
	v_add_f32_e32 v60, v60, v64
	v_mul_f32_e32 v60, 0xbfb8aa3b, v60
	v_exp_f32_e32 v60, v60
	s_waitcnt vmcnt(2)
	v_lshlrev_b32_e32 v84, 16, v68
	v_add_f32_e32 v60, 1.0, v60
	v_rcp_f32_e32 v87, v60
	v_add_f32_e32 v60, v61, v65
	v_mul_f32_e32 v60, 0xbfb8aa3b, v60
	v_exp_f32_e32 v61, v60
	v_and_b32_e32 v60, 0xffff0000, v68
	v_mul_f32_e32 v64, 0xbfb8aa3b, v84
	v_mul_f32_e32 v65, 0xbfb8aa3b, v60
	v_exp_f32_e32 v64, v64
	v_exp_f32_e32 v68, v65
	v_add_f32_e32 v61, 1.0, v61
	v_rcp_f32_e32 v65, v61
	v_add_f32_e32 v64, 1.0, v64
	v_add_f32_e32 v61, 1.0, v68
	v_rcp_f32_e32 v86, v64
	v_rcp_f32_e32 v64, v61
	s_waitcnt vmcnt(1)
	v_and_b32_e32 v61, 0xffff0000, v72
	v_lshlrev_b32_e32 v85, 16, v72
	s_waitcnt vmcnt(0)
	v_add_f32_e32 v56, v56, v76
	v_pk_mul_f32 v[60:61], v[64:65], v[60:61]
	v_mul_f32_e32 v56, 0xbfb8aa3b, v56
	v_mul_f32_e32 v72, v60, v61
	v_add_f32_e32 v60, v62, v66
	v_mul_f32_e32 v60, 0xbfb8aa3b, v60
	v_exp_f32_e32 v61, v60
	v_lshlrev_b32_e32 v60, 16, v69
	v_mul_f32_e32 v62, 0xbfb8aa3b, v60
	v_exp_f32_e32 v62, v62
	v_add_f32_e32 v61, 1.0, v61
	v_rcp_f32_e32 v65, v61
	v_exp_f32_e32 v56, v56
	v_add_f32_e32 v64, 1.0, v62
	v_add_f32_e32 v62, v63, v67
	v_mul_f32_e32 v62, 0xbfb8aa3b, v62
	v_exp_f32_e32 v63, v62
	v_and_b32_e32 v62, 0xffff0000, v69
	v_mul_f32_e32 v66, 0xbfb8aa3b, v62
	v_exp_f32_e32 v66, v66
	v_add_f32_e32 v63, 1.0, v63
	v_rcp_f32_e32 v64, v64
	v_rcp_f32_e32 v67, v63
	v_add_f32_e32 v63, 1.0, v66
	v_rcp_f32_e32 v66, v63
	v_lshlrev_b32_e32 v61, 16, v73
	v_pk_mul_f32 v[60:61], v[64:65], v[60:61]
	v_and_b32_e32 v63, 0xffff0000, v73
	v_add_f32_e32 v56, 1.0, v56
	v_mul_f32_e32 v69, v60, v61
	v_pk_mul_f32 v[60:61], v[66:67], v[62:63]
	v_rcp_f32_e32 v63, v56
	v_add_f32_e32 v56, v57, v77
	v_mul_f32_e32 v56, 0xbfb8aa3b, v56
	v_exp_f32_e32 v57, v56
	v_and_b32_e32 v56, 0xffff0000, v70
	v_mul_f32_e32 v64, 0xbfb8aa3b, v56
	v_exp_f32_e32 v64, v64
	v_add_f32_e32 v57, 1.0, v57
	v_rcp_f32_e32 v65, v57
	v_mul_f32_e32 v66, v60, v61
	v_add_f32_e32 v57, 1.0, v64
	v_rcp_f32_e32 v64, v57
	v_lshlrev_b32_e32 v60, 16, v70
	v_mul_f32_e32 v61, 0xbfb8aa3b, v60
	v_exp_f32_e32 v62, v61
	v_and_b32_e32 v57, 0xffff0000, v74
	v_pk_mul_f32 v[56:57], v[64:65], v[56:57]
	v_lshlrev_b32_e32 v61, 16, v74
	v_mul_f32_e32 v64, v56, v57
	v_add_f32_e32 v56, v58, v78
	v_mul_f32_e32 v56, 0xbfb8aa3b, v56
	v_add_f32_e32 v62, 1.0, v62
	v_exp_f32_e32 v57, v56
	v_lshlrev_b32_e32 v56, 16, v71
	v_rcp_f32_e32 v62, v62
	v_mul_f32_e32 v58, 0xbfb8aa3b, v56
	v_exp_f32_e32 v58, v58
	v_add_f32_e32 v57, 1.0, v57
	v_pk_mul_f32 v[60:61], v[62:63], v[60:61]
	v_pk_mul_f32 v[84:85], v[86:87], v[84:85]
	v_mul_f32_e32 v67, v60, v61
	v_add_f32_e32 v60, 1.0, v58
	v_add_f32_e32 v58, v59, v79
	v_mul_f32_e32 v58, 0xbfb8aa3b, v58
	v_exp_f32_e32 v59, v58
	v_and_b32_e32 v58, 0xffff0000, v71
	v_mul_f32_e32 v62, 0xbfb8aa3b, v58
	v_exp_f32_e32 v62, v62
	v_add_f32_e32 v59, 1.0, v59
	v_rcp_f32_e32 v61, v57
	v_rcp_f32_e32 v60, v60
	v_rcp_f32_e32 v63, v59
	v_add_f32_e32 v59, 1.0, v62
	v_rcp_f32_e32 v62, v59
	v_lshlrev_b32_e32 v57, 16, v75
	v_pk_mul_f32 v[56:57], v[60:61], v[56:57]
	v_and_b32_e32 v59, 0xffff0000, v75
	v_mul_f32_e32 v65, v56, v57
	v_pk_mul_f32 v[56:57], v[62:63], v[58:59]
	v_lshl_add_u64 v[60:61], s[16:17], 0, v[82:83]
	v_mul_f32_e32 v59, v56, v57
	v_mul_f32_e32 v68, v84, v85
	v_cvt_pk_bf16_f32 v56, v68, v72
	v_cvt_pk_bf16_f32 v57, v69, v66
	v_cvt_pk_bf16_f32 v58, v67, v64
	v_cvt_pk_bf16_f32 v59, v65, v59
	s_mov_b64 exec, s[90:91]
	global_store_dwordx4 v[60:61], v[56:59], off
	s_mov_b64 exec, -1
	global_load_dwordx4 v[56:59], v[164:165], off offset:512
	v_lshl_add_u64 v[60:61], v[80:81], 0, v[120:121]
	v_lshlrev_b64 v[72:73], 1, v[60:61]
	v_lshl_add_u64 v[60:61], s[14:15], 0, v[72:73]
	global_load_dwordx4 v[60:63], v[60:61], off
	v_lshl_add_u64 v[64:65], s[8:9], 0, v[72:73]
	global_load_dwordx4 v[64:67], v[64:65], off
	s_nop 0
	global_load_dwordx4 v[68:71], v[164:165], off offset:528
	s_waitcnt vmcnt(3)
	v_add_f32_e32 v52, v52, v56
	v_mul_f32_e32 v52, 0xbfb8aa3b, v52
	v_exp_f32_e32 v52, v52
	s_waitcnt vmcnt(2)
; __device__ __forceinline__ void store8(bf16* p, f32x4 a, f32x4 b) { u32x4 w; w.x = pk2(a.x, a.y); w.y = pk2(a.z, a.w); w.z = pk2(b.x, b.y); w.w = pk2(b.z, b.w); *(u32x4*)p = w; }
; __device__ __forceinline__ float sigm(float x) { return __builtin_amdgcn_rcpf(1.f + __expf(-x)); }
; __device__ __forceinline__ float silu(float x) { return x * __builtin_amdgcn_rcpf(1.f + __expf(-x)); }
;     __device__ __forceinline__ void operator()(const pg8::Unit& u, int rl, int cl, f32x4 v0, f32x4 v1) const {
;         const int col = u.pn * 256 + cl; const size_t off = ((size_t)u.pm * 256 + rl) * D + col;
;         const u32x4 yw = *(const u32x4*)(y + off), zw = *(const u32x4*)(z + off);
;         const f32x4 b0 = *(const f32x4*)(bias + col), b1 = *(const f32x4*)(bias + col + 4);
;         f32x4 r0, r1;
;         r0.x = lo_bf(yw.x) * sigm(v0.x + b0.x) * silu(lo_bf(zw.x)); r0.y = hi_bf(yw.x) * sigm(v0.y + b0.y) * silu(hi_bf(zw.x));
;         r0.z = lo_bf(yw.y) * sigm(v0.z + b0.z) * silu(lo_bf(zw.y)); r0.w = hi_bf(yw.y) * sigm(v0.w + b0.w) * silu(hi_bf(zw.y));
;         r1.x = lo_bf(yw.z) * sigm(v1.x + b1.x) * silu(lo_bf(zw.z)); r1.y = hi_bf(yw.z) * sigm(v1.y + b1.y) * silu(hi_bf(zw.z));
;         r1.z = lo_bf(yw.w) * sigm(v1.z + b1.z) * silu(lo_bf(zw.w)); r1.w = hi_bf(yw.w) * sigm(v1.w + b1.w) * silu(hi_bf(zw.w));
;         store8(o + off, r0, r1);
	v_lshlrev_b32_e32 v74, 16, v60
	v_mul_f32_e32 v56, 0xbfb8aa3b, v74
	v_add_f32_e32 v52, 1.0, v52
	v_rcp_f32_e32 v77, v52
	v_add_f32_e32 v52, v53, v57
	v_mul_f32_e32 v52, 0xbfb8aa3b, v52
	v_exp_f32_e32 v53, v52
	v_and_b32_e32 v52, 0xffff0000, v60
	v_mul_f32_e32 v57, 0xbfb8aa3b, v52
	v_exp_f32_e32 v56, v56
	v_exp_f32_e32 v60, v57
	v_add_f32_e32 v53, 1.0, v53
	v_rcp_f32_e32 v57, v53
	v_add_f32_e32 v56, 1.0, v56
	v_add_f32_e32 v53, 1.0, v60
	v_rcp_f32_e32 v76, v56
	v_rcp_f32_e32 v56, v53
	s_waitcnt vmcnt(1)
	v_and_b32_e32 v53, 0xffff0000, v64
	v_lshlrev_b32_e32 v75, 16, v64
	s_waitcnt vmcnt(0)
	v_add_f32_e32 v48, v48, v68
	v_pk_mul_f32 v[52:53], v[56:57], v[52:53]
	v_mul_f32_e32 v48, 0xbfb8aa3b, v48
	v_mul_f32_e32 v64, v52, v53
	v_add_f32_e32 v52, v54, v58
	v_mul_f32_e32 v52, 0xbfb8aa3b, v52
	v_exp_f32_e32 v53, v52
	v_lshlrev_b32_e32 v52, 16, v61
	v_mul_f32_e32 v54, 0xbfb8aa3b, v52
	v_exp_f32_e32 v54, v54
	v_add_f32_e32 v53, 1.0, v53
	v_rcp_f32_e32 v57, v53
	v_exp_f32_e32 v48, v48
	v_add_f32_e32 v56, 1.0, v54
	v_add_f32_e32 v54, v55, v59
	v_mul_f32_e32 v54, 0xbfb8aa3b, v54
	v_exp_f32_e32 v55, v54
	v_and_b32_e32 v54, 0xffff0000, v61
	v_mul_f32_e32 v58, 0xbfb8aa3b, v54
	v_exp_f32_e32 v58, v58
	v_add_f32_e32 v55, 1.0, v55
	v_rcp_f32_e32 v56, v56
	v_rcp_f32_e32 v59, v55
	v_add_f32_e32 v55, 1.0, v58
	v_rcp_f32_e32 v58, v55
	v_lshlrev_b32_e32 v53, 16, v65
	v_pk_mul_f32 v[52:53], v[56:57], v[52:53]
	v_and_b32_e32 v55, 0xffff0000, v65
	v_add_f32_e32 v48, 1.0, v48
	v_mul_f32_e32 v61, v52, v53
	v_pk_mul_f32 v[52:53], v[58:59], v[54:55]
	v_rcp_f32_e32 v55, v48
	v_add_f32_e32 v48, v49, v69
	v_mul_f32_e32 v48, 0xbfb8aa3b, v48
	v_exp_f32_e32 v49, v48
	v_and_b32_e32 v48, 0xffff0000, v62
	v_mul_f32_e32 v56, 0xbfb8aa3b, v48
	v_exp_f32_e32 v56, v56
	v_add_f32_e32 v49, 1.0, v49
	v_rcp_f32_e32 v57, v49
	v_mul_f32_e32 v58, v52, v53
	v_add_f32_e32 v49, 1.0, v56
	v_rcp_f32_e32 v56, v49
	v_lshlrev_b32_e32 v52, 16, v62
	v_mul_f32_e32 v53, 0xbfb8aa3b, v52
	v_exp_f32_e32 v54, v53
	v_and_b32_e32 v49, 0xffff0000, v66
	v_pk_mul_f32 v[48:49], v[56:57], v[48:49]
	v_lshlrev_b32_e32 v53, 16, v66
	v_mul_f32_e32 v56, v48, v49
	v_add_f32_e32 v48, v50, v70
	v_mul_f32_e32 v48, 0xbfb8aa3b, v48
	v_add_f32_e32 v54, 1.0, v54
	v_exp_f32_e32 v49, v48
	v_lshlrev_b32_e32 v48, 16, v63
	v_rcp_f32_e32 v54, v54
	v_mul_f32_e32 v50, 0xbfb8aa3b, v48
	v_exp_f32_e32 v50, v50
	v_add_f32_e32 v49, 1.0, v49
	v_pk_mul_f32 v[52:53], v[54:55], v[52:53]
	v_pk_mul_f32 v[74:75], v[76:77], v[74:75]
	v_mul_f32_e32 v59, v52, v53
	v_add_f32_e32 v52, 1.0, v50
	v_add_f32_e32 v50, v51, v71
	v_mul_f32_e32 v50, 0xbfb8aa3b, v50
	v_exp_f32_e32 v51, v50
	v_and_b32_e32 v50, 0xffff0000, v63
	v_mul_f32_e32 v54, 0xbfb8aa3b, v50
	v_exp_f32_e32 v54, v54
	v_add_f32_e32 v51, 1.0, v51
	v_rcp_f32_e32 v53, v49
	v_rcp_f32_e32 v52, v52
	v_rcp_f32_e32 v55, v51
	v_add_f32_e32 v51, 1.0, v54
	v_rcp_f32_e32 v54, v51
	v_lshlrev_b32_e32 v49, 16, v67
	v_pk_mul_f32 v[48:49], v[52:53], v[48:49]
	v_and_b32_e32 v51, 0xffff0000, v67
	v_mul_f32_e32 v57, v48, v49
	v_pk_mul_f32 v[48:49], v[54:55], v[50:51]
	v_lshl_add_u64 v[52:53], s[16:17], 0, v[72:73]
	v_mul_f32_e32 v51, v48, v49
	v_mul_f32_e32 v60, v74, v75
	v_cvt_pk_bf16_f32 v48, v60, v64
	v_cvt_pk_bf16_f32 v49, v61, v58
	v_cvt_pk_bf16_f32 v50, v59, v56
	v_cvt_pk_bf16_f32 v51, v57, v51
	s_mov_b64 exec, s[90:91]
	global_store_dwordx4 v[52:53], v[48:51], off
	s_mov_b64 exec, -1
	global_load_dwordx4 v[48:51], v[164:165], off
	v_lshl_add_u64 v[64:65], s[48:49], 0, v[154:155]
	v_lshl_add_u64 v[52:53], v[64:65], 0, v[166:167]
	v_lshlrev_b64 v[66:67], 1, v[52:53]
	v_lshl_add_u64 v[52:53], s[14:15], 0, v[66:67]
	global_load_dwordx4 v[52:55], v[52:53], off
	v_lshl_add_u64 v[56:57], s[8:9], 0, v[66:67]
	global_load_dwordx4 v[56:59], v[56:57], off
	s_nop 0
	global_load_dwordx4 v[60:63], v[164:165], off offset:16
	s_waitcnt vmcnt(3)
	v_add_f32_e32 v44, v44, v48
	v_mul_f32_e32 v44, 0xbfb8aa3b, v44
	v_exp_f32_e32 v44, v44
	s_waitcnt vmcnt(2)
	v_lshlrev_b32_e32 v68, 16, v52
	v_add_f32_e32 v44, 1.0, v44
	v_rcp_f32_e32 v71, v44
	v_add_f32_e32 v44, v45, v49
	v_mul_f32_e32 v44, 0xbfb8aa3b, v44
	v_exp_f32_e32 v45, v44
	v_and_b32_e32 v44, 0xffff0000, v52
	v_mul_f32_e32 v48, 0xbfb8aa3b, v68
	v_mul_f32_e32 v49, 0xbfb8aa3b, v44
	v_exp_f32_e32 v48, v48
	v_exp_f32_e32 v52, v49
	v_add_f32_e32 v45, 1.0, v45
	v_rcp_f32_e32 v49, v45
	v_add_f32_e32 v48, 1.0, v48
	v_add_f32_e32 v45, 1.0, v52
	v_rcp_f32_e32 v70, v48
	v_rcp_f32_e32 v48, v45
	s_waitcnt vmcnt(1)
	v_and_b32_e32 v45, 0xffff0000, v56
	v_lshlrev_b32_e32 v69, 16, v56
	s_waitcnt vmcnt(0)
; __device__ __forceinline__ void store8(bf16* p, f32x4 a, f32x4 b) { u32x4 w; w.x = pk2(a.x, a.y); w.y = pk2(a.z, a.w); w.z = pk2(b.x, b.y); w.w = pk2(b.z, b.w); *(u32x4*)p = w; }
; __device__ __forceinline__ float sigm(float x) { return __builtin_amdgcn_rcpf(1.f + __expf(-x)); }
; __device__ __forceinline__ float silu(float x) { return x * __builtin_amdgcn_rcpf(1.f + __expf(-x)); }
;     __device__ __forceinline__ void operator()(const pg8::Unit& u, int rl, int cl, f32x4 v0, f32x4 v1) const {
;         const int col = u.pn * 256 + cl; const size_t off = ((size_t)u.pm * 256 + rl) * D + col;
;         const u32x4 yw = *(const u32x4*)(y + off), zw = *(const u32x4*)(z + off);
;         const f32x4 b0 = *(const f32x4*)(bias + col), b1 = *(const f32x4*)(bias + col + 4);
;         f32x4 r0, r1;
;         r0.x = lo_bf(yw.x) * sigm(v0.x + b0.x) * silu(lo_bf(zw.x)); r0.y = hi_bf(yw.x) * sigm(v0.y + b0.y) * silu(hi_bf(zw.x));
;         r0.z = lo_bf(yw.y) * sigm(v0.z + b0.z) * silu(lo_bf(zw.y)); r0.w = hi_bf(yw.y) * sigm(v0.w + b0.w) * silu(hi_bf(zw.y));
;         r1.x = lo_bf(yw.z) * sigm(v1.x + b1.x) * silu(lo_bf(zw.z)); r1.y = hi_bf(yw.z) * sigm(v1.y + b1.y) * silu(hi_bf(zw.z));
;         r1.z = lo_bf(yw.w) * sigm(v1.z + b1.z) * silu(lo_bf(zw.w)); r1.w = hi_bf(yw.w) * sigm(v1.w + b1.w) * silu(hi_bf(zw.w));
;         store8(o + off, r0, r1);
	v_add_f32_e32 v40, v40, v60
	v_pk_mul_f32 v[44:45], v[48:49], v[44:45]
	v_mul_f32_e32 v40, 0xbfb8aa3b, v40
	v_mul_f32_e32 v56, v44, v45
	v_add_f32_e32 v44, v46, v50
	v_mul_f32_e32 v44, 0xbfb8aa3b, v44
	v_exp_f32_e32 v45, v44
	v_lshlrev_b32_e32 v44, 16, v53
	v_mul_f32_e32 v46, 0xbfb8aa3b, v44
	v_exp_f32_e32 v46, v46
	v_add_f32_e32 v45, 1.0, v45
	v_rcp_f32_e32 v49, v45
	v_exp_f32_e32 v40, v40
	v_add_f32_e32 v48, 1.0, v46
	v_add_f32_e32 v46, v47, v51
	v_mul_f32_e32 v46, 0xbfb8aa3b, v46
	v_exp_f32_e32 v47, v46
	v_and_b32_e32 v46, 0xffff0000, v53
	v_mul_f32_e32 v50, 0xbfb8aa3b, v46
	v_exp_f32_e32 v50, v50
	v_add_f32_e32 v47, 1.0, v47
	v_rcp_f32_e32 v48, v48
	v_rcp_f32_e32 v51, v47
	v_add_f32_e32 v47, 1.0, v50
	v_rcp_f32_e32 v50, v47
	v_lshlrev_b32_e32 v45, 16, v57
	v_pk_mul_f32 v[44:45], v[48:49], v[44:45]
	v_and_b32_e32 v47, 0xffff0000, v57
	v_add_f32_e32 v40, 1.0, v40
	v_mul_f32_e32 v53, v44, v45
	v_pk_mul_f32 v[44:45], v[50:51], v[46:47]
	v_rcp_f32_e32 v47, v40
	v_add_f32_e32 v40, v41, v61
	v_mul_f32_e32 v40, 0xbfb8aa3b, v40
	v_exp_f32_e32 v41, v40
	v_and_b32_e32 v40, 0xffff0000, v54
	v_mul_f32_e32 v48, 0xbfb8aa3b, v40
	v_exp_f32_e32 v48, v48
	v_add_f32_e32 v41, 1.0, v41
	v_rcp_f32_e32 v49, v41
	v_mul_f32_e32 v50, v44, v45
	v_add_f32_e32 v41, 1.0, v48
	v_rcp_f32_e32 v48, v41
	v_lshlrev_b32_e32 v44, 16, v54
	v_mul_f32_e32 v45, 0xbfb8aa3b, v44
	v_exp_f32_e32 v46, v45
	v_and_b32_e32 v41, 0xffff0000, v58
	v_pk_mul_f32 v[40:41], v[48:49], v[40:41]
	v_lshlrev_b32_e32 v45, 16, v58
	v_mul_f32_e32 v48, v40, v41
	v_add_f32_e32 v40, v42, v62
	v_mul_f32_e32 v40, 0xbfb8aa3b, v40
	v_add_f32_e32 v46, 1.0, v46
	v_exp_f32_e32 v41, v40
	v_lshlrev_b32_e32 v40, 16, v55
	v_rcp_f32_e32 v46, v46
	v_mul_f32_e32 v42, 0xbfb8aa3b, v40
	v_exp_f32_e32 v42, v42
	v_add_f32_e32 v41, 1.0, v41
	v_pk_mul_f32 v[44:45], v[46:47], v[44:45]
	v_pk_mul_f32 v[68:69], v[70:71], v[68:69]
	v_mul_f32_e32 v51, v44, v45
	v_add_f32_e32 v44, 1.0, v42
	v_add_f32_e32 v42, v43, v63
	v_mul_f32_e32 v42, 0xbfb8aa3b, v42
	v_exp_f32_e32 v43, v42
	v_and_b32_e32 v42, 0xffff0000, v55
	v_mul_f32_e32 v46, 0xbfb8aa3b, v42
	v_exp_f32_e32 v46, v46
	v_add_f32_e32 v43, 1.0, v43
	v_rcp_f32_e32 v45, v41
	v_rcp_f32_e32 v44, v44
	v_rcp_f32_e32 v47, v43
	v_add_f32_e32 v43, 1.0, v46
	v_rcp_f32_e32 v46, v43
	v_lshlrev_b32_e32 v41, 16, v59
	v_pk_mul_f32 v[40:41], v[44:45], v[40:41]
	v_and_b32_e32 v43, 0xffff0000, v59
	v_mul_f32_e32 v49, v40, v41
	v_pk_mul_f32 v[40:41], v[46:47], v[42:43]
	v_lshl_add_u64 v[44:45], s[16:17], 0, v[66:67]
	v_mul_f32_e32 v43, v40, v41
	v_mul_f32_e32 v52, v68, v69
	v_cvt_pk_bf16_f32 v40, v52, v56
	v_cvt_pk_bf16_f32 v41, v53, v50
	v_cvt_pk_bf16_f32 v42, v51, v48
	v_cvt_pk_bf16_f32 v43, v49, v43
	s_mov_b64 exec, s[90:91]
	global_store_dwordx4 v[44:45], v[40:43], off
	s_mov_b64 exec, -1
	global_load_dwordx4 v[40:43], v[164:165], off offset:512
	v_lshl_add_u64 v[44:45], v[64:65], 0, v[120:121]
	v_lshlrev_b64 v[56:57], 1, v[44:45]
	v_lshl_add_u64 v[44:45], s[14:15], 0, v[56:57]
	global_load_dwordx4 v[44:47], v[44:45], off
	v_lshl_add_u64 v[48:49], s[8:9], 0, v[56:57]
	global_load_dwordx4 v[48:51], v[48:49], off
	s_nop 0
	global_load_dwordx4 v[52:55], v[164:165], off offset:528
	s_waitcnt vmcnt(3)
	v_add_f32_e32 v36, v36, v40
	v_mul_f32_e32 v36, 0xbfb8aa3b, v36
	v_exp_f32_e32 v36, v36
	s_waitcnt vmcnt(2)
	v_lshlrev_b32_e32 v58, 16, v44
	v_mul_f32_e32 v40, 0xbfb8aa3b, v58
	v_add_f32_e32 v36, 1.0, v36
	v_rcp_f32_e32 v61, v36
	v_add_f32_e32 v36, v37, v41
	v_mul_f32_e32 v36, 0xbfb8aa3b, v36
	v_exp_f32_e32 v37, v36
	v_and_b32_e32 v36, 0xffff0000, v44
	v_mul_f32_e32 v41, 0xbfb8aa3b, v36
	v_exp_f32_e32 v40, v40
	v_exp_f32_e32 v44, v41
	v_add_f32_e32 v37, 1.0, v37
	v_rcp_f32_e32 v41, v37
	v_add_f32_e32 v40, 1.0, v40
	v_add_f32_e32 v37, 1.0, v44
	v_rcp_f32_e32 v60, v40
	v_rcp_f32_e32 v40, v37
	s_waitcnt vmcnt(1)
	v_and_b32_e32 v37, 0xffff0000, v48
	v_lshlrev_b32_e32 v59, 16, v48
	s_waitcnt vmcnt(0)
	v_add_f32_e32 v32, v32, v52
	v_pk_mul_f32 v[36:37], v[40:41], v[36:37]
	v_mul_f32_e32 v32, 0xbfb8aa3b, v32
	v_mul_f32_e32 v48, v36, v37
	v_add_f32_e32 v36, v38, v42
	v_mul_f32_e32 v36, 0xbfb8aa3b, v36
	v_exp_f32_e32 v37, v36
	v_lshlrev_b32_e32 v36, 16, v45
	v_mul_f32_e32 v38, 0xbfb8aa3b, v36
	v_exp_f32_e32 v38, v38
	v_add_f32_e32 v37, 1.0, v37
	v_rcp_f32_e32 v41, v37
	v_exp_f32_e32 v32, v32
	v_add_f32_e32 v40, 1.0, v38
	v_add_f32_e32 v38, v39, v43
	v_mul_f32_e32 v38, 0xbfb8aa3b, v38
	v_exp_f32_e32 v39, v38
	v_and_b32_e32 v38, 0xffff0000, v45
	v_mul_f32_e32 v42, 0xbfb8aa3b, v38
	v_exp_f32_e32 v42, v42
	v_add_f32_e32 v39, 1.0, v39
	v_rcp_f32_e32 v40, v40
	v_rcp_f32_e32 v43, v39
	v_add_f32_e32 v39, 1.0, v42
	v_rcp_f32_e32 v42, v39
	v_lshlrev_b32_e32 v37, 16, v49
	v_pk_mul_f32 v[36:37], v[40:41], v[36:37]
	v_and_b32_e32 v39, 0xffff0000, v49
	v_add_f32_e32 v32, 1.0, v32
	v_mul_f32_e32 v45, v36, v37
	v_pk_mul_f32 v[36:37], v[42:43], v[38:39]
	v_rcp_f32_e32 v39, v32
	v_add_f32_e32 v32, v33, v53
	v_mul_f32_e32 v32, 0xbfb8aa3b, v32
	v_exp_f32_e32 v33, v32
	v_and_b32_e32 v32, 0xffff0000, v46
	v_mul_f32_e32 v40, 0xbfb8aa3b, v32
	v_exp_f32_e32 v40, v40
	v_add_f32_e32 v33, 1.0, v33
	v_rcp_f32_e32 v41, v33
	v_mul_f32_e32 v42, v36, v37
	v_add_f32_e32 v33, 1.0, v40
	v_rcp_f32_e32 v40, v33
	v_lshlrev_b32_e32 v36, 16, v46
	v_mul_f32_e32 v37, 0xbfb8aa3b, v36
	v_exp_f32_e32 v38, v37
	v_and_b32_e32 v33, 0xffff0000, v50
	v_pk_mul_f32 v[32:33], v[40:41], v[32:33]
	v_lshlrev_b32_e32 v37, 16, v50
	v_mul_f32_e32 v40, v32, v33
	v_add_f32_e32 v32, v34, v54
	v_mul_f32_e32 v32, 0xbfb8aa3b, v32
	v_add_f32_e32 v38, 1.0, v38
	v_exp_f32_e32 v33, v32
	v_lshlrev_b32_e32 v32, 16, v47
	v_rcp_f32_e32 v38, v38
	v_mul_f32_e32 v34, 0xbfb8aa3b, v32
; __device__ __forceinline__ void store8(bf16* p, f32x4 a, f32x4 b) { u32x4 w; w.x = pk2(a.x, a.y); w.y = pk2(a.z, a.w); w.z = pk2(b.x, b.y); w.w = pk2(b.z, b.w); *(u32x4*)p = w; }
; __device__ __forceinline__ float sigm(float x) { return __builtin_amdgcn_rcpf(1.f + __expf(-x)); }
; __device__ __forceinline__ float silu(float x) { return x * __builtin_amdgcn_rcpf(1.f + __expf(-x)); }
;     __device__ __forceinline__ void operator()(const pg8::Unit& u, int rl, int cl, f32x4 v0, f32x4 v1) const {
;         const int col = u.pn * 256 + cl; const size_t off = ((size_t)u.pm * 256 + rl) * D + col;
;         const u32x4 yw = *(const u32x4*)(y + off), zw = *(const u32x4*)(z + off);
;         const f32x4 b0 = *(const f32x4*)(bias + col), b1 = *(const f32x4*)(bias + col + 4);
;         f32x4 r0, r1;
;         r0.x = lo_bf(yw.x) * sigm(v0.x + b0.x) * silu(lo_bf(zw.x)); r0.y = hi_bf(yw.x) * sigm(v0.y + b0.y) * silu(hi_bf(zw.x));
;         r0.z = lo_bf(yw.y) * sigm(v0.z + b0.z) * silu(lo_bf(zw.y)); r0.w = hi_bf(yw.y) * sigm(v0.w + b0.w) * silu(hi_bf(zw.y));
;         r1.x = lo_bf(yw.z) * sigm(v1.x + b1.x) * silu(lo_bf(zw.z)); r1.y = hi_bf(yw.z) * sigm(v1.y + b1.y) * silu(hi_bf(zw.z));
;         r1.z = lo_bf(yw.w) * sigm(v1.z + b1.z) * silu(lo_bf(zw.w)); r1.w = hi_bf(yw.w) * sigm(v1.w + b1.w) * silu(hi_bf(zw.w));
;         store8(o + off, r0, r1);
	v_exp_f32_e32 v34, v34
	v_add_f32_e32 v33, 1.0, v33
	v_pk_mul_f32 v[36:37], v[38:39], v[36:37]
	v_pk_mul_f32 v[58:59], v[60:61], v[58:59]
	v_mul_f32_e32 v43, v36, v37
	v_add_f32_e32 v36, 1.0, v34
	v_add_f32_e32 v34, v35, v55
	v_mul_f32_e32 v34, 0xbfb8aa3b, v34
	v_exp_f32_e32 v35, v34
	v_and_b32_e32 v34, 0xffff0000, v47
	v_mul_f32_e32 v38, 0xbfb8aa3b, v34
	v_exp_f32_e32 v38, v38
	v_add_f32_e32 v35, 1.0, v35
	v_rcp_f32_e32 v37, v33
	v_rcp_f32_e32 v36, v36
	v_rcp_f32_e32 v39, v35
	v_add_f32_e32 v35, 1.0, v38
	v_rcp_f32_e32 v38, v35
	v_lshlrev_b32_e32 v33, 16, v51
	v_pk_mul_f32 v[32:33], v[36:37], v[32:33]
	v_and_b32_e32 v35, 0xffff0000, v51
	v_mul_f32_e32 v41, v32, v33
	v_pk_mul_f32 v[32:33], v[38:39], v[34:35]
	v_lshl_add_u64 v[36:37], s[16:17], 0, v[56:57]
	v_mul_f32_e32 v35, v32, v33
	v_mul_f32_e32 v44, v58, v59
	v_cvt_pk_bf16_f32 v32, v44, v48
	v_cvt_pk_bf16_f32 v33, v45, v42
	v_cvt_pk_bf16_f32 v34, v43, v40
	v_cvt_pk_bf16_f32 v35, v41, v35
	s_mov_b64 exec, s[90:91]
	global_store_dwordx4 v[36:37], v[32:35], off
	s_mov_b64 exec, -1
	global_load_dwordx4 v[32:35], v[164:165], off
	v_lshl_add_u64 v[48:49], s[48:49], 0, v[156:157]
	v_lshl_add_u64 v[36:37], v[48:49], 0, v[166:167]
	v_lshlrev_b64 v[50:51], 1, v[36:37]
	v_lshl_add_u64 v[36:37], s[14:15], 0, v[50:51]
	global_load_dwordx4 v[36:39], v[36:37], off
	v_lshl_add_u64 v[40:41], s[8:9], 0, v[50:51]
	global_load_dwordx4 v[40:43], v[40:41], off
	s_nop 0
	global_load_dwordx4 v[44:47], v[164:165], off offset:16
	s_waitcnt vmcnt(3)
	v_add_f32_e32 v28, v28, v32
	v_mul_f32_e32 v28, 0xbfb8aa3b, v28
	v_exp_f32_e32 v28, v28
	s_waitcnt vmcnt(2)
	v_lshlrev_b32_e32 v52, 16, v36
	v_add_f32_e32 v28, 1.0, v28
	v_rcp_f32_e32 v55, v28
	v_add_f32_e32 v28, v29, v33
	v_mul_f32_e32 v28, 0xbfb8aa3b, v28
	v_exp_f32_e32 v29, v28
	v_and_b32_e32 v28, 0xffff0000, v36
	v_mul_f32_e32 v32, 0xbfb8aa3b, v52
	v_mul_f32_e32 v33, 0xbfb8aa3b, v28
	v_exp_f32_e32 v32, v32
	v_exp_f32_e32 v36, v33
	v_add_f32_e32 v29, 1.0, v29
	v_rcp_f32_e32 v33, v29
	v_add_f32_e32 v32, 1.0, v32
	v_add_f32_e32 v29, 1.0, v36
	v_rcp_f32_e32 v54, v32
	v_rcp_f32_e32 v32, v29
	s_waitcnt vmcnt(1)
	v_and_b32_e32 v29, 0xffff0000, v40
	v_lshlrev_b32_e32 v53, 16, v40
	s_waitcnt vmcnt(0)
	v_add_f32_e32 v24, v24, v44
	v_pk_mul_f32 v[28:29], v[32:33], v[28:29]
	v_mul_f32_e32 v24, 0xbfb8aa3b, v24
	v_mul_f32_e32 v40, v28, v29
	v_add_f32_e32 v28, v30, v34
	v_mul_f32_e32 v28, 0xbfb8aa3b, v28
	v_exp_f32_e32 v29, v28
	v_lshlrev_b32_e32 v28, 16, v37
	v_mul_f32_e32 v30, 0xbfb8aa3b, v28
	v_exp_f32_e32 v30, v30
	v_add_f32_e32 v29, 1.0, v29
	v_rcp_f32_e32 v33, v29
	v_exp_f32_e32 v24, v24
	v_add_f32_e32 v32, 1.0, v30
	v_add_f32_e32 v30, v31, v35
	v_mul_f32_e32 v30, 0xbfb8aa3b, v30
	v_exp_f32_e32 v31, v30
	v_and_b32_e32 v30, 0xffff0000, v37
	v_mul_f32_e32 v34, 0xbfb8aa3b, v30
	v_exp_f32_e32 v34, v34
	v_add_f32_e32 v31, 1.0, v31
	v_rcp_f32_e32 v32, v32
	v_rcp_f32_e32 v35, v31
	v_add_f32_e32 v31, 1.0, v34
	v_rcp_f32_e32 v34, v31
	v_lshlrev_b32_e32 v29, 16, v41
	v_pk_mul_f32 v[28:29], v[32:33], v[28:29]
	v_and_b32_e32 v31, 0xffff0000, v41
	v_add_f32_e32 v24, 1.0, v24
	v_mul_f32_e32 v37, v28, v29
	v_pk_mul_f32 v[28:29], v[34:35], v[30:31]
	v_rcp_f32_e32 v31, v24
	v_add_f32_e32 v24, v25, v45
	v_mul_f32_e32 v24, 0xbfb8aa3b, v24
	v_exp_f32_e32 v25, v24
	v_and_b32_e32 v24, 0xffff0000, v38
	v_mul_f32_e32 v32, 0xbfb8aa3b, v24
	v_exp_f32_e32 v32, v32
	v_add_f32_e32 v25, 1.0, v25
	v_rcp_f32_e32 v33, v25
	v_mul_f32_e32 v34, v28, v29
	v_add_f32_e32 v25, 1.0, v32
	v_rcp_f32_e32 v32, v25
	v_lshlrev_b32_e32 v28, 16, v38
	v_mul_f32_e32 v29, 0xbfb8aa3b, v28
	v_exp_f32_e32 v30, v29
	v_and_b32_e32 v25, 0xffff0000, v42
	v_pk_mul_f32 v[24:25], v[32:33], v[24:25]
	v_lshlrev_b32_e32 v29, 16, v42
	v_mul_f32_e32 v32, v24, v25
	v_add_f32_e32 v24, v26, v46
	v_mul_f32_e32 v24, 0xbfb8aa3b, v24
	v_add_f32_e32 v30, 1.0, v30
	v_exp_f32_e32 v25, v24
	v_lshlrev_b32_e32 v24, 16, v39
	v_rcp_f32_e32 v30, v30
	v_mul_f32_e32 v26, 0xbfb8aa3b, v24
	v_exp_f32_e32 v26, v26
	v_add_f32_e32 v25, 1.0, v25
	v_pk_mul_f32 v[28:29], v[30:31], v[28:29]
	v_pk_mul_f32 v[52:53], v[54:55], v[52:53]
	v_mul_f32_e32 v35, v28, v29
	v_add_f32_e32 v28, 1.0, v26
	v_add_f32_e32 v26, v27, v47
	v_mul_f32_e32 v26, 0xbfb8aa3b, v26
	v_exp_f32_e32 v27, v26
	v_and_b32_e32 v26, 0xffff0000, v39
	v_mul_f32_e32 v30, 0xbfb8aa3b, v26
	v_exp_f32_e32 v30, v30
	v_add_f32_e32 v27, 1.0, v27
	v_rcp_f32_e32 v29, v25
	v_rcp_f32_e32 v28, v28
	v_rcp_f32_e32 v31, v27
	v_add_f32_e32 v27, 1.0, v30
	v_rcp_f32_e32 v30, v27
	v_lshlrev_b32_e32 v25, 16, v43
	v_pk_mul_f32 v[24:25], v[28:29], v[24:25]
	v_and_b32_e32 v27, 0xffff0000, v43
	v_mul_f32_e32 v33, v24, v25
	v_pk_mul_f32 v[24:25], v[30:31], v[26:27]
	v_lshl_add_u64 v[28:29], s[16:17], 0, v[50:51]
	v_mul_f32_e32 v27, v24, v25
	v_mul_f32_e32 v36, v52, v53
	v_cvt_pk_bf16_f32 v24, v36, v40
	v_cvt_pk_bf16_f32 v25, v37, v34
	v_cvt_pk_bf16_f32 v26, v35, v32
	v_cvt_pk_bf16_f32 v27, v33, v27
	s_mov_b64 exec, s[90:91]
	global_store_dwordx4 v[28:29], v[24:27], off
	s_mov_b64 exec, -1
	global_load_dwordx4 v[24:27], v[164:165], off offset:512
	v_lshl_add_u64 v[28:29], v[48:49], 0, v[120:121]
	v_lshlrev_b64 v[40:41], 1, v[28:29]
	v_lshl_add_u64 v[28:29], s[14:15], 0, v[40:41]
	global_load_dwordx4 v[28:31], v[28:29], off
	v_lshl_add_u64 v[32:33], s[8:9], 0, v[40:41]
	global_load_dwordx4 v[32:35], v[32:33], off
	s_nop 0
	global_load_dwordx4 v[36:39], v[164:165], off offset:528
	s_waitcnt vmcnt(3)
	v_add_f32_e32 v20, v20, v24
	v_mul_f32_e32 v20, 0xbfb8aa3b, v20
	v_exp_f32_e32 v20, v20
	s_waitcnt vmcnt(2)
; __device__ __forceinline__ void store8(bf16* p, f32x4 a, f32x4 b) { u32x4 w; w.x = pk2(a.x, a.y); w.y = pk2(a.z, a.w); w.z = pk2(b.x, b.y); w.w = pk2(b.z, b.w); *(u32x4*)p = w; }
; __device__ __forceinline__ float sigm(float x) { return __builtin_amdgcn_rcpf(1.f + __expf(-x)); }
; __device__ __forceinline__ float silu(float x) { return x * __builtin_amdgcn_rcpf(1.f + __expf(-x)); }
;     __device__ __forceinline__ void operator()(const pg8::Unit& u, int rl, int cl, f32x4 v0, f32x4 v1) const {
;         const int col = u.pn * 256 + cl; const size_t off = ((size_t)u.pm * 256 + rl) * D + col;
;         const u32x4 yw = *(const u32x4*)(y + off), zw = *(const u32x4*)(z + off);
;         const f32x4 b0 = *(const f32x4*)(bias + col), b1 = *(const f32x4*)(bias + col + 4);
;         f32x4 r0, r1;
;         r0.x = lo_bf(yw.x) * sigm(v0.x + b0.x) * silu(lo_bf(zw.x)); r0.y = hi_bf(yw.x) * sigm(v0.y + b0.y) * silu(hi_bf(zw.x));
;         r0.z = lo_bf(yw.y) * sigm(v0.z + b0.z) * silu(lo_bf(zw.y)); r0.w = hi_bf(yw.y) * sigm(v0.w + b0.w) * silu(hi_bf(zw.y));
;         r1.x = lo_bf(yw.z) * sigm(v1.x + b1.x) * silu(lo_bf(zw.z)); r1.y = hi_bf(yw.z) * sigm(v1.y + b1.y) * silu(hi_bf(zw.z));
;         r1.z = lo_bf(yw.w) * sigm(v1.z + b1.z) * silu(lo_bf(zw.w)); r1.w = hi_bf(yw.w) * sigm(v1.w + b1.w) * silu(hi_bf(zw.w));
;         store8(o + off, r0, r1);
	v_lshlrev_b32_e32 v42, 16, v28
	v_mul_f32_e32 v24, 0xbfb8aa3b, v42
	v_add_f32_e32 v20, 1.0, v20
	v_rcp_f32_e32 v45, v20
	v_add_f32_e32 v20, v21, v25
	v_mul_f32_e32 v20, 0xbfb8aa3b, v20
	v_exp_f32_e32 v21, v20
	v_and_b32_e32 v20, 0xffff0000, v28
	v_mul_f32_e32 v25, 0xbfb8aa3b, v20
	v_exp_f32_e32 v24, v24
	v_exp_f32_e32 v28, v25
	v_add_f32_e32 v21, 1.0, v21
	v_rcp_f32_e32 v25, v21
	v_add_f32_e32 v24, 1.0, v24
	v_add_f32_e32 v21, 1.0, v28
	v_rcp_f32_e32 v44, v24
	v_rcp_f32_e32 v24, v21
	s_waitcnt vmcnt(1)
	v_and_b32_e32 v21, 0xffff0000, v32
	v_lshlrev_b32_e32 v43, 16, v32
	s_waitcnt vmcnt(0)
	v_add_f32_e32 v16, v16, v36
	v_pk_mul_f32 v[20:21], v[24:25], v[20:21]
	v_mul_f32_e32 v16, 0xbfb8aa3b, v16
	v_mul_f32_e32 v32, v20, v21
	v_add_f32_e32 v20, v22, v26
	v_mul_f32_e32 v20, 0xbfb8aa3b, v20
	v_exp_f32_e32 v21, v20
	v_lshlrev_b32_e32 v20, 16, v29
	v_mul_f32_e32 v22, 0xbfb8aa3b, v20
	v_exp_f32_e32 v22, v22
	v_add_f32_e32 v21, 1.0, v21
	v_rcp_f32_e32 v25, v21
	v_exp_f32_e32 v16, v16
	v_add_f32_e32 v24, 1.0, v22
	v_add_f32_e32 v22, v23, v27
	v_mul_f32_e32 v22, 0xbfb8aa3b, v22
	v_exp_f32_e32 v23, v22
	v_and_b32_e32 v22, 0xffff0000, v29
	v_mul_f32_e32 v26, 0xbfb8aa3b, v22
	v_exp_f32_e32 v26, v26
	v_add_f32_e32 v23, 1.0, v23
	v_rcp_f32_e32 v24, v24
	v_rcp_f32_e32 v27, v23
	v_add_f32_e32 v23, 1.0, v26
	v_rcp_f32_e32 v26, v23
	v_lshlrev_b32_e32 v21, 16, v33
	v_pk_mul_f32 v[20:21], v[24:25], v[20:21]
	v_and_b32_e32 v23, 0xffff0000, v33
	v_add_f32_e32 v16, 1.0, v16
	v_mul_f32_e32 v29, v20, v21
	v_pk_mul_f32 v[20:21], v[26:27], v[22:23]
	v_rcp_f32_e32 v23, v16
	v_add_f32_e32 v16, v17, v37
	v_mul_f32_e32 v16, 0xbfb8aa3b, v16
	v_exp_f32_e32 v17, v16
	v_and_b32_e32 v16, 0xffff0000, v30
	v_mul_f32_e32 v24, 0xbfb8aa3b, v16
	v_exp_f32_e32 v24, v24
	v_add_f32_e32 v17, 1.0, v17
	v_rcp_f32_e32 v25, v17
	v_mul_f32_e32 v26, v20, v21
	v_add_f32_e32 v17, 1.0, v24
	v_rcp_f32_e32 v24, v17
	v_lshlrev_b32_e32 v20, 16, v30
	v_mul_f32_e32 v21, 0xbfb8aa3b, v20
	v_exp_f32_e32 v22, v21
	v_and_b32_e32 v17, 0xffff0000, v34
	v_pk_mul_f32 v[16:17], v[24:25], v[16:17]
	v_lshlrev_b32_e32 v21, 16, v34
	v_mul_f32_e32 v24, v16, v17
	v_add_f32_e32 v16, v18, v38
	v_mul_f32_e32 v16, 0xbfb8aa3b, v16
	v_add_f32_e32 v22, 1.0, v22
	v_exp_f32_e32 v17, v16
	v_lshlrev_b32_e32 v16, 16, v31
	v_rcp_f32_e32 v22, v22
	v_mul_f32_e32 v18, 0xbfb8aa3b, v16
	v_exp_f32_e32 v18, v18
	v_add_f32_e32 v17, 1.0, v17
	v_pk_mul_f32 v[20:21], v[22:23], v[20:21]
	v_pk_mul_f32 v[42:43], v[44:45], v[42:43]
	v_mul_f32_e32 v27, v20, v21
	v_add_f32_e32 v20, 1.0, v18
	v_add_f32_e32 v18, v19, v39
	v_mul_f32_e32 v18, 0xbfb8aa3b, v18
	v_exp_f32_e32 v19, v18
	v_and_b32_e32 v18, 0xffff0000, v31
	v_mul_f32_e32 v22, 0xbfb8aa3b, v18
	v_exp_f32_e32 v22, v22
	v_add_f32_e32 v19, 1.0, v19
	v_rcp_f32_e32 v21, v17
	v_rcp_f32_e32 v20, v20
	v_rcp_f32_e32 v23, v19
	v_add_f32_e32 v19, 1.0, v22
	v_rcp_f32_e32 v22, v19
	v_lshlrev_b32_e32 v17, 16, v35
	v_pk_mul_f32 v[16:17], v[20:21], v[16:17]
	v_and_b32_e32 v19, 0xffff0000, v35
	v_mul_f32_e32 v25, v16, v17
	v_pk_mul_f32 v[16:17], v[22:23], v[18:19]
	v_lshl_add_u64 v[20:21], s[16:17], 0, v[40:41]
	v_mul_f32_e32 v19, v16, v17
	v_mul_f32_e32 v28, v42, v43
	v_cvt_pk_bf16_f32 v16, v28, v32
	v_cvt_pk_bf16_f32 v17, v29, v26
	v_cvt_pk_bf16_f32 v18, v27, v24
	v_cvt_pk_bf16_f32 v19, v25, v19
	s_mov_b64 exec, s[90:91]
	global_store_dwordx4 v[20:21], v[16:19], off
	s_mov_b64 exec, -1
	global_load_dwordx4 v[16:19], v[164:165], off
	v_lshl_add_u64 v[32:33], s[48:49], 0, v[158:159]
	v_lshl_add_u64 v[20:21], v[32:33], 0, v[166:167]
	v_lshlrev_b64 v[34:35], 1, v[20:21]
	v_lshl_add_u64 v[20:21], s[14:15], 0, v[34:35]
	global_load_dwordx4 v[20:23], v[20:21], off
	v_lshl_add_u64 v[24:25], s[8:9], 0, v[34:35]
	global_load_dwordx4 v[24:27], v[24:25], off
	s_nop 0
	global_load_dwordx4 v[28:31], v[164:165], off offset:16
	s_waitcnt vmcnt(3)
	v_add_f32_e32 v12, v12, v16
	v_mul_f32_e32 v12, 0xbfb8aa3b, v12
	v_exp_f32_e32 v12, v12
	s_waitcnt vmcnt(2)
	v_lshlrev_b32_e32 v36, 16, v20
	v_add_f32_e32 v12, 1.0, v12
	v_rcp_f32_e32 v39, v12
	v_add_f32_e32 v12, v13, v17
	v_mul_f32_e32 v12, 0xbfb8aa3b, v12
	v_exp_f32_e32 v13, v12
	v_and_b32_e32 v12, 0xffff0000, v20
	v_mul_f32_e32 v16, 0xbfb8aa3b, v36
	v_mul_f32_e32 v17, 0xbfb8aa3b, v12
	v_exp_f32_e32 v16, v16
	v_exp_f32_e32 v20, v17
	v_add_f32_e32 v13, 1.0, v13
	v_rcp_f32_e32 v17, v13
	v_add_f32_e32 v16, 1.0, v16
	v_add_f32_e32 v13, 1.0, v20
	v_rcp_f32_e32 v38, v16
	v_rcp_f32_e32 v16, v13
	s_waitcnt vmcnt(1)
	v_and_b32_e32 v13, 0xffff0000, v24
	v_lshlrev_b32_e32 v37, 16, v24
	s_waitcnt vmcnt(0)
; #define PG8_BAR __builtin_amdgcn_s_barrier()
; __device__ __forceinline__ void store8(bf16* p, f32x4 a, f32x4 b) { u32x4 w; w.x = pk2(a.x, a.y); w.y = pk2(a.z, a.w); w.z = pk2(b.x, b.y); w.w = pk2(b.z, b.w); *(u32x4*)p = w; }
; __device__ __forceinline__ float sigm(float x) { return __builtin_amdgcn_rcpf(1.f + __expf(-x)); }
; __device__ __forceinline__ float silu(float x) { return x * __builtin_amdgcn_rcpf(1.f + __expf(-x)); }
; template <class Epi, class Sched, bool ALIGN_EPI = false, bool SP2 = false>
; __device__ __forceinline__ void gemm_phase(PG8_LAS unsigned char* lds, const Gemm g, const Sched& S, const Epi& E) {
;     ...
;         if (!has_next) break;
; #pragma unroll
;         for (int a = 0; a < 2; ++a)
; #pragma unroll
;             for (int b = 0; b < 2; ++b)
; #pragma unroll
;                 for (int m = 0; m < 4; ++m)
; #pragma unroll
;                     for (int n = 0; n < 2; ++n) acc[a][b][m][n] = (f32x4){0.f, 0.f, 0.f, 0.f};
;         cur = nxt; cA = nA; cB = nB; ++ui;
;         if constexpr (ALIGN_EPI) { if (wr == 1) PG8_BAR; }
;     __device__ __forceinline__ void operator()(const pg8::Unit& u, int rl, int cl, f32x4 v0, f32x4 v1) const {
;         const int col = u.pn * 256 + cl; const size_t off = ((size_t)u.pm * 256 + rl) * D + col;
;         const u32x4 yw = *(const u32x4*)(y + off), zw = *(const u32x4*)(z + off);
;         const f32x4 b0 = *(const f32x4*)(bias + col), b1 = *(const f32x4*)(bias + col + 4);
;         f32x4 r0, r1;
;         r0.x = lo_bf(yw.x) * sigm(v0.x + b0.x) * silu(lo_bf(zw.x)); r0.y = hi_bf(yw.x) * sigm(v0.y + b0.y) * silu(hi_bf(zw.x));
;         r0.z = lo_bf(yw.y) * sigm(v0.z + b0.z) * silu(lo_bf(zw.y)); r0.w = hi_bf(yw.y) * sigm(v0.w + b0.w) * silu(hi_bf(zw.y));
;         r1.x = lo_bf(yw.z) * sigm(v1.x + b1.x) * silu(lo_bf(zw.z)); r1.y = hi_bf(yw.z) * sigm(v1.y + b1.y) * silu(hi_bf(zw.z));
;         r1.z = lo_bf(yw.w) * sigm(v1.z + b1.z) * silu(lo_bf(zw.w)); r1.w = hi_bf(yw.w) * sigm(v1.w + b1.w) * silu(hi_bf(zw.w));
;         store8(o + off, r0, r1);
	v_add_f32_e32 v8, v8, v28
	v_pk_mul_f32 v[12:13], v[16:17], v[12:13]
	v_mul_f32_e32 v8, 0xbfb8aa3b, v8
	v_mul_f32_e32 v24, v12, v13
	v_add_f32_e32 v12, v14, v18
	v_mul_f32_e32 v12, 0xbfb8aa3b, v12
	v_exp_f32_e32 v13, v12
	v_lshlrev_b32_e32 v12, 16, v21
	v_mul_f32_e32 v14, 0xbfb8aa3b, v12
	v_exp_f32_e32 v14, v14
	v_add_f32_e32 v13, 1.0, v13
	v_rcp_f32_e32 v17, v13
	v_exp_f32_e32 v8, v8
	v_add_f32_e32 v16, 1.0, v14
	v_add_f32_e32 v14, v15, v19
	v_mul_f32_e32 v14, 0xbfb8aa3b, v14
	v_exp_f32_e32 v15, v14
	v_and_b32_e32 v14, 0xffff0000, v21
	v_mul_f32_e32 v18, 0xbfb8aa3b, v14
	v_exp_f32_e32 v18, v18
	v_add_f32_e32 v15, 1.0, v15
	v_rcp_f32_e32 v16, v16
	v_rcp_f32_e32 v19, v15
	v_add_f32_e32 v15, 1.0, v18
	v_rcp_f32_e32 v18, v15
	v_lshlrev_b32_e32 v13, 16, v25
	v_pk_mul_f32 v[12:13], v[16:17], v[12:13]
	v_and_b32_e32 v15, 0xffff0000, v25
	v_add_f32_e32 v8, 1.0, v8
	v_mul_f32_e32 v21, v12, v13
	v_pk_mul_f32 v[12:13], v[18:19], v[14:15]
	v_rcp_f32_e32 v15, v8
	v_add_f32_e32 v8, v9, v29
	v_mul_f32_e32 v8, 0xbfb8aa3b, v8
	v_exp_f32_e32 v9, v8
	v_and_b32_e32 v8, 0xffff0000, v22
	v_mul_f32_e32 v16, 0xbfb8aa3b, v8
	v_exp_f32_e32 v16, v16
	v_add_f32_e32 v9, 1.0, v9
	v_rcp_f32_e32 v17, v9
	v_mul_f32_e32 v18, v12, v13
	v_add_f32_e32 v9, 1.0, v16
	v_rcp_f32_e32 v16, v9
	v_lshlrev_b32_e32 v12, 16, v22
	v_mul_f32_e32 v13, 0xbfb8aa3b, v12
	v_exp_f32_e32 v14, v13
	v_and_b32_e32 v9, 0xffff0000, v26
	v_pk_mul_f32 v[8:9], v[16:17], v[8:9]
	v_lshlrev_b32_e32 v13, 16, v26
	v_mul_f32_e32 v16, v8, v9
	v_add_f32_e32 v8, v10, v30
	v_mul_f32_e32 v8, 0xbfb8aa3b, v8
	v_add_f32_e32 v14, 1.0, v14
	v_exp_f32_e32 v9, v8
	v_lshlrev_b32_e32 v8, 16, v23
	v_rcp_f32_e32 v14, v14
	v_mul_f32_e32 v10, 0xbfb8aa3b, v8
	v_exp_f32_e32 v10, v10
	v_add_f32_e32 v9, 1.0, v9
	v_pk_mul_f32 v[12:13], v[14:15], v[12:13]
	v_pk_mul_f32 v[36:37], v[38:39], v[36:37]
	v_mul_f32_e32 v19, v12, v13
	v_add_f32_e32 v12, 1.0, v10
	v_add_f32_e32 v10, v11, v31
	v_mul_f32_e32 v10, 0xbfb8aa3b, v10
	v_exp_f32_e32 v11, v10
	v_and_b32_e32 v10, 0xffff0000, v23
	v_mul_f32_e32 v14, 0xbfb8aa3b, v10
	v_exp_f32_e32 v14, v14
	v_add_f32_e32 v11, 1.0, v11
	v_rcp_f32_e32 v13, v9
	v_rcp_f32_e32 v12, v12
	v_rcp_f32_e32 v15, v11
	v_add_f32_e32 v11, 1.0, v14
	v_rcp_f32_e32 v14, v11
	v_lshlrev_b32_e32 v9, 16, v27
	v_pk_mul_f32 v[8:9], v[12:13], v[8:9]
	v_and_b32_e32 v11, 0xffff0000, v27
	v_mul_f32_e32 v17, v8, v9
	v_pk_mul_f32 v[8:9], v[14:15], v[10:11]
	v_lshl_add_u64 v[12:13], s[16:17], 0, v[34:35]
	v_mul_f32_e32 v11, v8, v9
	v_mul_f32_e32 v20, v36, v37
	v_cvt_pk_bf16_f32 v8, v20, v24
	v_cvt_pk_bf16_f32 v9, v21, v18
	v_cvt_pk_bf16_f32 v10, v19, v16
	v_cvt_pk_bf16_f32 v11, v17, v11
	s_mov_b64 exec, s[90:91]
	global_store_dwordx4 v[12:13], v[8:11], off
	s_mov_b64 exec, -1
	global_load_dwordx4 v[8:11], v[164:165], off offset:512
	v_lshl_add_u64 v[12:13], v[32:33], 0, v[120:121]
	v_lshlrev_b64 v[24:25], 1, v[12:13]
	v_lshl_add_u64 v[12:13], s[14:15], 0, v[24:25]
	global_load_dwordx4 v[12:15], v[12:13], off
	v_lshl_add_u64 v[16:17], s[8:9], 0, v[24:25]
	global_load_dwordx4 v[16:19], v[16:17], off
	s_nop 0
	global_load_dwordx4 v[20:23], v[164:165], off offset:528
	s_waitcnt vmcnt(3)
	v_add_f32_e32 v4, v4, v8
	v_mul_f32_e32 v4, 0xbfb8aa3b, v4
	v_exp_f32_e32 v4, v4
	s_waitcnt vmcnt(2)
	v_lshlrev_b32_e32 v26, 16, v12
	v_mul_f32_e32 v8, 0xbfb8aa3b, v26
	v_add_f32_e32 v4, 1.0, v4
	v_rcp_f32_e32 v29, v4
	v_add_f32_e32 v4, v5, v9
	v_mul_f32_e32 v4, 0xbfb8aa3b, v4
	v_exp_f32_e32 v5, v4
	v_and_b32_e32 v4, 0xffff0000, v12
	v_mul_f32_e32 v9, 0xbfb8aa3b, v4
	v_exp_f32_e32 v8, v8
	v_exp_f32_e32 v12, v9
	v_add_f32_e32 v5, 1.0, v5
	v_rcp_f32_e32 v9, v5
	v_add_f32_e32 v8, 1.0, v8
	v_add_f32_e32 v5, 1.0, v12
	v_rcp_f32_e32 v28, v8
	v_rcp_f32_e32 v8, v5
	s_waitcnt vmcnt(1)
	v_and_b32_e32 v5, 0xffff0000, v16
	v_lshlrev_b32_e32 v27, 16, v16
	s_waitcnt vmcnt(0)
	v_add_f32_e32 v0, v0, v20
	v_pk_mul_f32 v[4:5], v[8:9], v[4:5]
	v_mul_f32_e32 v0, 0xbfb8aa3b, v0
	v_mul_f32_e32 v16, v4, v5
	v_add_f32_e32 v4, v6, v10
	v_mul_f32_e32 v4, 0xbfb8aa3b, v4
	v_exp_f32_e32 v5, v4
	v_lshlrev_b32_e32 v4, 16, v13
	v_mul_f32_e32 v6, 0xbfb8aa3b, v4
	v_exp_f32_e32 v6, v6
	v_add_f32_e32 v5, 1.0, v5
	v_rcp_f32_e32 v9, v5
	v_exp_f32_e32 v0, v0
	v_add_f32_e32 v8, 1.0, v6
	v_add_f32_e32 v6, v7, v11
	v_mul_f32_e32 v6, 0xbfb8aa3b, v6
	v_exp_f32_e32 v7, v6
	v_and_b32_e32 v6, 0xffff0000, v13
	v_mul_f32_e32 v10, 0xbfb8aa3b, v6
	v_exp_f32_e32 v10, v10
	v_add_f32_e32 v7, 1.0, v7
	v_rcp_f32_e32 v8, v8
	v_rcp_f32_e32 v11, v7
	v_add_f32_e32 v7, 1.0, v10
	v_rcp_f32_e32 v10, v7
	v_lshlrev_b32_e32 v5, 16, v17
	v_pk_mul_f32 v[4:5], v[8:9], v[4:5]
	v_and_b32_e32 v7, 0xffff0000, v17
	v_add_f32_e32 v0, 1.0, v0
	v_mul_f32_e32 v13, v4, v5
	v_pk_mul_f32 v[4:5], v[10:11], v[6:7]
	v_rcp_f32_e32 v7, v0
	v_add_f32_e32 v0, v1, v21
	v_mul_f32_e32 v0, 0xbfb8aa3b, v0
	v_exp_f32_e32 v1, v0
	v_and_b32_e32 v0, 0xffff0000, v14
	v_mul_f32_e32 v8, 0xbfb8aa3b, v0
	v_exp_f32_e32 v8, v8
	v_add_f32_e32 v1, 1.0, v1
	v_rcp_f32_e32 v9, v1
	v_mul_f32_e32 v10, v4, v5
	v_add_f32_e32 v1, 1.0, v8
	v_rcp_f32_e32 v8, v1
	v_lshlrev_b32_e32 v4, 16, v14
	v_mul_f32_e32 v5, 0xbfb8aa3b, v4
	v_exp_f32_e32 v6, v5
	v_and_b32_e32 v1, 0xffff0000, v18
	v_pk_mul_f32 v[0:1], v[8:9], v[0:1]
	v_lshlrev_b32_e32 v5, 16, v18
	v_mul_f32_e32 v8, v0, v1
	v_add_f32_e32 v0, v2, v22
	v_mul_f32_e32 v0, 0xbfb8aa3b, v0
	v_add_f32_e32 v6, 1.0, v6
	v_exp_f32_e32 v1, v0
	v_lshlrev_b32_e32 v0, 16, v15
	v_rcp_f32_e32 v6, v6
	v_mul_f32_e32 v2, 0xbfb8aa3b, v0
	v_exp_f32_e32 v2, v2
	v_add_f32_e32 v1, 1.0, v1
	v_pk_mul_f32 v[4:5], v[6:7], v[4:5]
	v_pk_mul_f32 v[26:27], v[28:29], v[26:27]
	v_mul_f32_e32 v11, v4, v5
	v_add_f32_e32 v4, 1.0, v2
	v_add_f32_e32 v2, v3, v23
	v_mul_f32_e32 v2, 0xbfb8aa3b, v2
	v_exp_f32_e32 v3, v2
	v_and_b32_e32 v2, 0xffff0000, v15
	v_mul_f32_e32 v6, 0xbfb8aa3b, v2
	v_exp_f32_e32 v6, v6
	v_add_f32_e32 v3, 1.0, v3
	v_rcp_f32_e32 v5, v1
	v_rcp_f32_e32 v4, v4
	v_rcp_f32_e32 v7, v3
	v_add_f32_e32 v3, 1.0, v6
	v_rcp_f32_e32 v6, v3
	v_lshlrev_b32_e32 v1, 16, v19
	v_pk_mul_f32 v[0:1], v[4:5], v[0:1]
	v_and_b32_e32 v3, 0xffff0000, v19
	v_mul_f32_e32 v9, v0, v1
	v_pk_mul_f32 v[0:1], v[6:7], v[2:3]
	v_lshl_add_u64 v[4:5], s[16:17], 0, v[24:25]
	v_mul_f32_e32 v3, v0, v1
	v_mul_f32_e32 v12, v26, v27
	v_cvt_pk_bf16_f32 v0, v12, v16
	v_cvt_pk_bf16_f32 v1, v13, v10
	v_cvt_pk_bf16_f32 v2, v11, v8
	v_cvt_pk_bf16_f32 v3, v9, v3
	s_mov_b64 exec, s[90:91]
	global_store_dwordx4 v[4:5], v[0:3], off
	s_mov_b64 exec, -1
	s_cbranch_vccnz .LBB0_1882
	s_andn2_b64 vcc, exec, s[12:13]
	s_cbranch_vccnz .LBB0_1881
	s_barrier
	s_branch .LBB0_1881

; #define PG8_STAGE(bufoff, gbase, voff) do { _Pragma("unroll") for (int _i = 0; _i < 2; ++_i) \
;         __builtin_amdgcn_global_load_lds((const unsigned*)((const char*)(gbase) + (voff)[_i]), (PG8_LAS unsigned*)(lds + (bufoff) + ldsw + _i * 8192), 16, 0, 0); } while (0)
; #define PG8_BAR __builtin_amdgcn_s_barrier()
;     __device__ __forceinline__ bf16* R(int i) const { return (bf16*)(ws + OFF_R0 + (size_t)i * RSZ); }
; template <class Epi, class Sched, bool ALIGN_EPI = false, bool SP2 = false>
; __device__ __forceinline__ void gemm_phase(PG8_LAS unsigned char* lds, const Gemm g, const Sched& S, const Epi& E) {
;     const int tid = threadIdx.x, wid = __builtin_amdgcn_readfirstlane(tid >> 6), lane = tid & 63, wr = wid >> 2, wc = wid & 3, fr = lane & 15, fq = lane >> 4;
;     const int K = g.K, nt = K / BK;
;     unsigned voffA[2], voffB[2];
; #pragma unroll
;     for (int i = 0; i < 2; ++i) { int R, C; stage_rc(tid * 16 + i * 8192, R, C); const int Rb = Epi::PERM ? ((R & ~31) + perm32(R & 31)) : R;
;         voffA[i] = (unsigned)(R * K + C) * 2u; voffB[i] = (unsigned)(Rb * K + C) * 2u; }
;     const size_t kstep = (size_t)(BK * 2);
;     const size_t hstep = (size_t)HALF * K * 2;
;     const size_t tstep = 2 * hstep;
;     const unsigned ldsw = (unsigned)wid * 1024u;
;     const int aoff = lds_byte(wr * 64 + fr, fq * 8), boff = lds_byte(wc * 32 + fr, fq * 8);
;     ...
;     Unit cur, nxt; int ui = 0;
;     if (!S.next(0, cur)) return;
;     f32x4 acc[2][2][4][2];
; #pragma unroll
;     for (int a = 0; a < 2; ++a)
; #pragma unroll
;         for (int b = 0; b < 2; ++b)
; #pragma unroll
;             for (int m = 0; m < 4; ++m)
; #pragma unroll
;                 for (int n = 0; n < 2; ++n) acc[a][b][m][n] = (f32x4){0.f, 0.f, 0.f, 0.f};
;     bf16x8 At[4][2], B0[2][2], B1[2][2];
;     const char* cA = (const char*)g.A + (size_t)cur.pm * tstep; const char* cB = (const char*)g.Bt + (size_t)cur.pn * tstep;
;     S.a_ready(cur);
;     if constexpr (SP2) {
;         PG8_STAGE(PG8_SB(0, 0), cB, voffB); PG8_STAGE(PG8_SB(0, 1), cB + hstep, voffB); PG8_STAGE(PG8_SA(0, 0), cA, voffA); PG8_STAGE(PG8_SA(0, 1), cA + hstep, voffA);
;         if (wr == 1) PG8_BAR;
.LBB0_1947:
	s_mov_b32 s92, 2
	s_mov_b64 s[88:89], -1
	s_mov_b64 s[90:91], -1
	s_or_b64 exec, exec, s[6:7]
	v_cmp_gt_i32_e32 vcc, 21, v2
	v_cmp_lt_i32_e64 s[6:7], 20, v3
	s_and_b64 s[6:7], vcc, s[6:7]
	s_and_saveexec_b64 s[12:13], s[6:7]
	s_cbranch_execz .LBB0_1974
	s_lshl_b32 s3, s2, 5
	s_and_b32 s3, s3, 0xe0
	s_ashr_i32 s6, s2, 3
	s_add_i32 s3, s3, s6
	s_cmpk_eq_i32 s30, 0x100
	s_cselect_b32 s3, s3, s2
	s_cmpk_gt_i32 s30, 0x110
	s_cselect_b32 s6, s2, s3
	s_movk_i32 s7, 0xe0
	v_readfirstlane_b32 s16, v128
	s_cmpk_gt_i32 s6, 0x10f
	v_lshlrev_b32_e32 v129, 2, v128
	s_cbranch_scc1 .LBB0_1964
	v_lshrrev_b32_e32 v0, 5, v128
	v_lshrrev_b32_e32 v2, 1, v128
	v_and_b32_e32 v0, 4, v0
	v_bfe_u32 v1, v128, 2, 2
	v_and_b32_e32 v11, 24, v2
	v_or3_b32 v0, v0, v1, v11
	v_lshlrev_b32_e32 v1, 4, v128
	v_add_u32_e32 v8, 0x2000, v1
	v_lshrrev_b32_e32 v2, 7, v8
	v_and_b32_e32 v4, 32, v128
	v_and_or_b32 v3, v2, s7, v0
	v_bitop3_b32 v9, v1, v4, 48 bitop3:0x6c
	v_and_b32_e32 v10, 64, v128
	v_bfe_u32 v12, v128, 2, 4
	s_movk_i32 s7, 0xf0
	s_add_u32 s54, s26, 0x9a00000
	v_or_b32_e32 v1, v9, v10
	v_and_or_b32 v2, v2, s7, v12
	s_addc_u32 s55, s27, 0
	v_lshl_or_b32 v138, v2, 11, v1
	v_lshrrev_b32_e32 v2, 3, v128
	s_movk_i32 s7, 0x60
	s_add_u32 s56, s26, 0xd00000
	v_and_or_b32 v0, v2, s7, v0
	s_movk_i32 s7, 0x70
	s_addc_u32 s57, s27, 0
	v_lshl_or_b32 v140, v0, 11, v1
	v_and_or_b32 v0, v2, s7, v12
	s_ashr_i32 s7, s6, 31
	s_lshr_b32 s7, s7, 30
	s_add_i32 s7, s6, s7
	s_ashr_i32 s44, s7, 2
	s_and_b32 s7, s7, -4
	s_sub_i32 s46, s6, s7
	s_lshr_b32 s10, s16, 6
	s_ashr_i32 s45, s44, 31
	s_ashr_i32 s47, s46, 31
	s_lshr_b32 s17, s16, 8
	s_lshl_b32 s58, s10, 10
	s_lshl_b64 s[6:7], s[44:45], 19
	s_lshl_b64 s[8:9], s[46:47], 19
	s_add_u32 s50, s56, s8
	s_addc_u32 s51, s57, s9
	s_add_i32 s45, s58, 0
	s_add_i32 m0, s45, 0x10000
	v_lshl_or_b32 v136, v3, 11, v1
	global_load_lds_dwordx4 v140, s[50:51]
	s_add_i32 m0, s45, 0x12000
	s_add_u32 s8, s50, 0x40000
	global_load_lds_dwordx4 v136, s[50:51]
	s_addc_u32 s9, s51, 0
	s_add_i32 m0, s45, 0x14000
	v_lshl_or_b32 v142, v0, 11, v1
	global_load_lds_dwordx4 v140, s[8:9]
	s_add_i32 m0, s45, 0x16000
	s_add_u32 s48, s54, s6
	s_addc_u32 s49, s55, s7
	s_add_i32 s47, s45, 0x2000
	global_load_lds_dwordx4 v136, s[8:9]
	s_mov_b32 m0, s45
	s_add_u32 s6, s48, 0x40000
	global_load_lds_dwordx4 v142, s[48:49]
	s_mov_b32 m0, s47
	s_addc_u32 s7, s49, 0
	s_add_i32 s59, s45, 0x4000
	global_load_lds_dwordx4 v138, s[48:49]
	s_mov_b32 m0, s59
	s_add_i32 s60, s45, 0x6000
	global_load_lds_dwordx4 v142, s[6:7]
	s_mov_b32 m0, s60
	v_mov_b32_e32 v141, 0
	global_load_lds_dwordx4 v138, s[6:7]
	v_mov_b32_e32 v137, v141
	v_mov_b32_e32 v143, v141
	v_mov_b32_e32 v139, v141
	s_cmp_eq_u32 s17, 1
	s_mov_b32 s61, 0
	v_lshl_add_u64 v[6:7], s[50:51], 0, v[140:141]
	v_lshl_add_u64 v[4:5], s[50:51], 0, v[136:137]
	v_lshl_add_u64 v[0:1], s[48:49], 0, v[142:143]
	s_cselect_b64 s[6:7], -1, 0
	s_cmp_lg_u32 s17, 1
	v_lshl_add_u64 v[2:3], s[48:49], 0, v[138:139]
	s_cbranch_scc1 .LBB0_1951
	s_barrier

;     __device__ __forceinline__ bool next(int i, Unit& u) const {
;         const int L = i * G + (((i + 1) * G <= n) ? c : cp); if (L >= n) return false;
;         if (mode == 0) { u.pm = L / nN; u.pn = L - u.pm * nN; }
; template <class Epi, class Sched, bool ALIGN_EPI = false, bool SP2 = false>
; __device__ __forceinline__ void gemm_phase(PG8_LAS unsigned char* lds, const Gemm g, const Sched& S, const Epi& E) {
;     ...
;         const bool has_next = S.next(ui + 1, nxt);
;         const char* nA = has_next ? (const char*)g.A + (size_t)nxt.pm * tstep : cA; const char* nB = has_next ? (const char*)g.Bt + (size_t)nxt.pn * tstep : cB;
.LBB0_1953:
	s_mov_b32 s92, s93
	s_cmp_lg_u32 s92, 1
	s_cselect_b64 s[88:89], -1, 0
	s_cmp_lg_u32 s92, 0
	s_cselect_b64 s[90:91], -1, 0
	s_andn2_b64 vcc, exec, s[24:25]
	s_mov_b32 s46, s20
	s_mov_b32 s44, s18
	s_mov_b64 s[50:51], s[42:43]
	s_mov_b64 s[48:49], s[22:23]
	s_cbranch_vccz .LBB0_1963
.LBB0_1954:
	s_add_i32 s61, s61, 1
	s_mul_i32 s19, s61, s30
	s_add_i32 s21, s19, s30
	s_cmpk_gt_i32 s21, 0x110
	s_cselect_b32 s93, 1, 0
	s_cselect_b32 s21, s2, s3
	s_add_i32 s19, s21, s19
	s_cmp_eq_u32 s93, 0
	s_mov_b32 s93, 2
	s_cbranch_scc1 .Lms17_a
	s_lshr_b32 s94, s2, 4
	s_lshl_b32 s94, s94, 3
	s_and_b32 s95, s2, 7
	s_or_b32 s94, s94, s95
	s_sub_i32 s95, s19, s2
	s_add_i32 s19, s95, s94
	s_bfe_u32 s93, s2, 0x10003
.Lms17_a:
	s_cmpk_lt_i32 s19, 0x110
	s_cselect_b64 s[24:25], -1, 0
	s_cmpk_gt_i32 s19, 0x10f
	s_cbranch_scc1 .LBB0_1956
	s_ashr_i32 s18, s19, 31
	s_lshr_b32 s18, s18, 30
	s_add_i32 s20, s19, s18
	s_ashr_i32 s18, s20, 2
	s_and_b32 s20, s20, -4
	s_sub_i32 s20, s19, s20

; #define PG8_STAGE(bufoff, gbase, voff) do { _Pragma("unroll") for (int _i = 0; _i < 2; ++_i) \
;         __builtin_amdgcn_global_load_lds((const unsigned*)((const char*)(gbase) + (voff)[_i]), (PG8_LAS unsigned*)(lds + (bufoff) + ldsw + _i * 8192), 16, 0, 0); } while (0)
; #define PG8_LDA(dst, b, h) do { _Pragma("unroll") for (int m = 0; m < 4; ++m) _Pragma("unroll") for (int k = 0; k < 2; ++k) dst[m][k] = *(const PG8_LAS bf16x8*)(lds + PG8_SA(b, h) + aoff + m * 2048 + k * 1024); } while (0)
; #define PG8_LDB(dst, b, h) do { _Pragma("unroll") for (int n = 0; n < 2; ++n) _Pragma("unroll") for (int k = 0; k < 2; ++k) dst[n][k] = *(const PG8_LAS bf16x8*)(lds + PG8_SB(b, h) + boff + n * 2048 + k * 1024); } while (0)
; #define PG8_MMA(ai, bj, At, Bt) do { __builtin_amdgcn_s_setprio(1); _Pragma("unroll") for (int m = 0; m < 4; ++m) _Pragma("unroll") for (int n = 0; n < 2; ++n) _Pragma("unroll") for (int k = 0; k < 2; ++k) \
;         acc[ai][bj][m][n] = __builtin_amdgcn_mfma_f32_16x16x32_bf16(Bt[n][k], At[m][k], acc[ai][bj][m][n], 0, 0, 0); __builtin_amdgcn_s_setprio(0); } while (0)
; #define PG8_WAIT_V(n) asm volatile("s_waitcnt vmcnt(" #n ")" ::: "memory")
; #define PG8_WAIT_L(n) asm volatile("s_waitcnt lgkmcnt(" #n ")" ::: "memory")
; #define PG8_BAR __builtin_amdgcn_s_barrier()
; #define PG8_SCHED __builtin_amdgcn_sched_barrier(0)
; template <class Epi, class Sched, bool ALIGN_EPI = false, bool SP2 = false>
; __device__ __forceinline__ void gemm_phase(PG8_LAS unsigned char* lds, const Gemm g, const Sched& S, const Epi& E) {
;     ...
;             PG8_LDB(B0, 0, 0); PG8_LDB(B1, 0, 1); PG8_SCHED; PG8_LDA(At, 0, 0); PG8_STAGE(PG8_SA(1, 1), a1 + hstep, voffA);
;             PG8_WAIT_V(8); PG8_WAIT_L(0); PG8_BAR; PG8_MMA(0, 0, At, B0); PG8_MMA(0, 1, At, B1); PG8_BAR; PG8_SCHED;
.LBB0_1957:
	ds_read_b128 v[148:151], v160
	ds_read_b128 v[164:167], v160 offset:1024
	ds_read_b128 v[168:171], v160 offset:2048
	ds_read_b128 v[172:175], v160 offset:3072
	ds_read_b128 v[176:179], v161
	ds_read_b128 v[180:183], v161 offset:1024
	ds_read_b128 v[184:187], v161 offset:2048
	ds_read_b128 v[188:191], v161 offset:3072
	s_add_u32 s50, s48, 0xfffc0080
	s_addc_u32 s51, s49, -1
	s_cmp_eq_u32 s76, 12
	s_cselect_b32 s53, s19, s51
	s_cselect_b32 s52, s72, s50
	s_cselect_b32 s51, s21, s75
	s_cselect_b32 s50, s73, s74
	s_mov_b32 m0, s71
	v_lshl_add_u64 v[224:225], s[48:49], 0, v[144:145]
	ds_read_b128 v[192:195], v162
	ds_read_b128 v[196:199], v162 offset:1024
	ds_read_b128 v[200:203], v162 offset:2048
	ds_read_b128 v[204:207], v162 offset:3072
	ds_read_b128 v[208:211], v162 offset:4096
	ds_read_b128 v[212:215], v162 offset:5120
	ds_read_b128 v[216:219], v162 offset:6144
	ds_read_b128 v[220:223], v162 offset:7168
	global_load_lds_dwordx4 v[224:225], off
	v_lshl_add_u64 v[224:225], s[48:49], 0, v[146:147]
	s_add_i32 m0, s45, 0xe000
	s_nop 0
	global_load_lds_dwordx4 v[224:225], off
	s_waitcnt vmcnt(8)
	s_waitcnt lgkmcnt(0)
	s_barrier
	s_setprio 1
	s_waitcnt lgkmcnt(0)
	s_cmp_eq_u32 s92, 1
	s_cbranch_scc1 .Lms17_b0
	v_mfma_f32_16x16x32_bf16 v[124:127], v[148:151], v[192:195], v[124:127]
	v_mfma_f32_16x16x32_bf16 v[120:123], v[168:171], v[192:195], v[120:123]
	v_mfma_f32_16x16x32_bf16 v[116:119], v[148:151], v[200:203], v[116:119]
	v_mfma_f32_16x16x32_bf16 v[104:107], v[168:171], v[200:203], v[104:107]
	v_mfma_f32_16x16x32_bf16 v[100:103], v[148:151], v[208:211], v[100:103]
	v_mfma_f32_16x16x32_bf16 v[88:91], v[168:171], v[208:211], v[88:91]
	v_mfma_f32_16x16x32_bf16 v[84:87], v[148:151], v[216:219], v[84:87]
	v_mfma_f32_16x16x32_bf16 v[72:75], v[168:171], v[216:219], v[72:75]
	v_mfma_f32_16x16x32_bf16 v[124:127], v[164:167], v[196:199], v[124:127]
	v_mfma_f32_16x16x32_bf16 v[120:123], v[172:175], v[196:199], v[120:123]
	v_mfma_f32_16x16x32_bf16 v[116:119], v[164:167], v[204:207], v[116:119]
	v_mfma_f32_16x16x32_bf16 v[104:107], v[172:175], v[204:207], v[104:107]
	v_mfma_f32_16x16x32_bf16 v[100:103], v[164:167], v[212:215], v[100:103]
	v_mfma_f32_16x16x32_bf16 v[88:91], v[172:175], v[212:215], v[88:91]
	v_mfma_f32_16x16x32_bf16 v[84:87], v[164:167], v[220:223], v[84:87]
	v_mfma_f32_16x16x32_bf16 v[72:75], v[172:175], v[220:223], v[72:75]

; #define PG8_STAGE(bufoff, gbase, voff) do { _Pragma("unroll") for (int _i = 0; _i < 2; ++_i) \
;         __builtin_amdgcn_global_load_lds((const unsigned*)((const char*)(gbase) + (voff)[_i]), (PG8_LAS unsigned*)(lds + (bufoff) + ldsw + _i * 8192), 16, 0, 0); } while (0)
; #define PG8_LDA(dst, b, h) do { _Pragma("unroll") for (int m = 0; m < 4; ++m) _Pragma("unroll") for (int k = 0; k < 2; ++k) dst[m][k] = *(const PG8_LAS bf16x8*)(lds + PG8_SA(b, h) + aoff + m * 2048 + k * 1024); } while (0)
; #define PG8_MMA(ai, bj, At, Bt) do { __builtin_amdgcn_s_setprio(1); _Pragma("unroll") for (int m = 0; m < 4; ++m) _Pragma("unroll") for (int n = 0; n < 2; ++n) _Pragma("unroll") for (int k = 0; k < 2; ++k) \
;         acc[ai][bj][m][n] = __builtin_amdgcn_mfma_f32_16x16x32_bf16(Bt[n][k], At[m][k], acc[ai][bj][m][n], 0, 0, 0); __builtin_amdgcn_s_setprio(0); } while (0)
; #define PG8_WAIT_V(n) asm volatile("s_waitcnt vmcnt(" #n ")" ::: "memory")
; #define PG8_WAIT_L(n) asm volatile("s_waitcnt lgkmcnt(" #n ")" ::: "memory")
; #define PG8_BAR __builtin_amdgcn_s_barrier()
; #define PG8_SCHED __builtin_amdgcn_sched_barrier(0)
; template <class Epi, class Sched, bool ALIGN_EPI = false, bool SP2 = false>
; __device__ __forceinline__ void gemm_phase(PG8_LAS unsigned char* lds, const Gemm g, const Sched& S, const Epi& E) {
;     ...
;             PG8_LDA(At, 0, 1); PG8_STAGE(PG8_SB(0, 0), b2, voffB); PG8_STAGE(PG8_SB(0, 1), b2 + hstep, voffB); PG8_STAGE(PG8_SA(0, 0), a2, voffA);
;             PG8_WAIT_V(8); PG8_WAIT_L(0); PG8_BAR; PG8_MMA(1, 0, At, B0); PG8_MMA(1, 1, At, B1); PG8_BAR; PG8_SCHED;
.Lms17_b1:
	s_setprio 0
	s_barrier
	s_add_i32 s77, s69, s58
	v_lshl_add_u64 v[224:225], s[50:51], 0, v[140:141]
	s_mov_b32 m0, s77
	ds_read_b128 v[192:195], v162 offset:16384
	ds_read_b128 v[196:199], v162 offset:17408
	ds_read_b128 v[200:203], v162 offset:18432
	ds_read_b128 v[204:207], v162 offset:19456
	ds_read_b128 v[208:211], v162 offset:20480
	ds_read_b128 v[212:215], v162 offset:21504
	ds_read_b128 v[216:219], v162 offset:22528
	ds_read_b128 v[220:223], v162 offset:23552
	global_load_lds_dwordx4 v[224:225], off
	s_add_i32 m0, s77, 0x2000
	s_add_u32 s78, s50, 0x40000
	v_lshl_add_u64 v[226:227], s[50:51], 0, v[136:137]
	s_addc_u32 s79, s51, 0
	s_add_i32 s77, s70, s58
	global_load_lds_dwordx4 v[226:227], off
	v_lshl_add_u64 v[228:229], s[78:79], 0, v[140:141]
	s_mov_b32 m0, s77
	v_lshl_add_u64 v[230:231], s[52:53], 0, v[138:139]
	global_load_lds_dwordx4 v[228:229], off
	v_lshl_add_u64 v[228:229], s[78:79], 0, v[136:137]
	s_add_i32 m0, s77, 0x2000
	s_nop 0
	global_load_lds_dwordx4 v[228:229], off
	v_lshl_add_u64 v[228:229], s[52:53], 0, v[142:143]
	s_mov_b32 m0, s45
	s_nop 0
	global_load_lds_dwordx4 v[228:229], off
	s_mov_b32 m0, s47
	s_nop 0
	global_load_lds_dwordx4 v[230:231], off
	s_waitcnt vmcnt(8)
	s_waitcnt lgkmcnt(0)
	s_barrier
	s_setprio 1
	s_waitcnt lgkmcnt(0)
	s_cmp_eq_u32 s92, 0
	s_cbranch_scc1 .Lms17_b2
	v_mfma_f32_16x16x32_bf16 v[60:63], v[148:151], v[192:195], v[60:63]
	v_mfma_f32_16x16x32_bf16 v[56:59], v[168:171], v[192:195], v[56:59]
	v_mfma_f32_16x16x32_bf16 v[52:55], v[148:151], v[200:203], v[52:55]
	v_mfma_f32_16x16x32_bf16 v[40:43], v[168:171], v[200:203], v[40:43]
	v_mfma_f32_16x16x32_bf16 v[36:39], v[148:151], v[208:211], v[36:39]
	v_mfma_f32_16x16x32_bf16 v[24:27], v[168:171], v[208:211], v[24:27]
	v_mfma_f32_16x16x32_bf16 v[20:23], v[148:151], v[216:219], v[20:23]
	v_mfma_f32_16x16x32_bf16 v[8:11], v[168:171], v[216:219], v[8:11]
	v_mfma_f32_16x16x32_bf16 v[60:63], v[164:167], v[196:199], v[60:63]
	v_mfma_f32_16x16x32_bf16 v[56:59], v[172:175], v[196:199], v[56:59]
	v_mfma_f32_16x16x32_bf16 v[52:55], v[164:167], v[204:207], v[52:55]
	v_mfma_f32_16x16x32_bf16 v[40:43], v[172:175], v[204:207], v[40:43]
	v_mfma_f32_16x16x32_bf16 v[36:39], v[164:167], v[212:215], v[36:39]
	v_mfma_f32_16x16x32_bf16 v[24:27], v[172:175], v[212:215], v[24:27]
	v_mfma_f32_16x16x32_bf16 v[20:23], v[164:167], v[220:223], v[20:23]
	v_mfma_f32_16x16x32_bf16 v[8:11], v[172:175], v[220:223], v[8:11]

; #define PG8_STAGE(bufoff, gbase, voff) do { _Pragma("unroll") for (int _i = 0; _i < 2; ++_i) \
;         __builtin_amdgcn_global_load_lds((const unsigned*)((const char*)(gbase) + (voff)[_i]), (PG8_LAS unsigned*)(lds + (bufoff) + ldsw + _i * 8192), 16, 0, 0); } while (0)
; #define PG8_LDA(dst, b, h) do { _Pragma("unroll") for (int m = 0; m < 4; ++m) _Pragma("unroll") for (int k = 0; k < 2; ++k) dst[m][k] = *(const PG8_LAS bf16x8*)(lds + PG8_SA(b, h) + aoff + m * 2048 + k * 1024); } while (0)
; #define PG8_LDB(dst, b, h) do { _Pragma("unroll") for (int n = 0; n < 2; ++n) _Pragma("unroll") for (int k = 0; k < 2; ++k) dst[n][k] = *(const PG8_LAS bf16x8*)(lds + PG8_SB(b, h) + boff + n * 2048 + k * 1024); } while (0)
; #define PG8_MMA(ai, bj, At, Bt) do { __builtin_amdgcn_s_setprio(1); _Pragma("unroll") for (int m = 0; m < 4; ++m) _Pragma("unroll") for (int n = 0; n < 2; ++n) _Pragma("unroll") for (int k = 0; k < 2; ++k) \
;         acc[ai][bj][m][n] = __builtin_amdgcn_mfma_f32_16x16x32_bf16(Bt[n][k], At[m][k], acc[ai][bj][m][n], 0, 0, 0); __builtin_amdgcn_s_setprio(0); } while (0)
; #define PG8_WAIT_V(n) asm volatile("s_waitcnt vmcnt(" #n ")" ::: "memory")
; #define PG8_WAIT_L(n) asm volatile("s_waitcnt lgkmcnt(" #n ")" ::: "memory")
; #define PG8_BAR __builtin_amdgcn_s_barrier()
; #define PG8_SCHED __builtin_amdgcn_sched_barrier(0)
; template <class Epi, class Sched, bool ALIGN_EPI = false, bool SP2 = false>
; __device__ __forceinline__ void gemm_phase(PG8_LAS unsigned char* lds, const Gemm g, const Sched& S, const Epi& E) {
;     ...
;             PG8_LDB(B0, 1, 0); PG8_LDB(B1, 1, 1); PG8_SCHED; PG8_LDA(At, 1, 0); PG8_STAGE(PG8_SA(0, 1), a2 + hstep, voffA);
;             PG8_WAIT_V(8); PG8_WAIT_L(0); PG8_BAR; PG8_MMA(0, 0, At, B0); PG8_MMA(0, 1, At, B1); PG8_BAR; PG8_SCHED;
.Lms17_b3:
	s_setprio 0
	s_barrier
	s_add_i32 s77, 0, 0x18000
	v_add_u32_e32 v163, s77, v135
	s_add_i32 s78, 0, 0x1c000
	ds_read_b128 v[148:151], v163
	ds_read_b128 v[164:167], v163 offset:1024
	ds_read_b128 v[168:171], v163 offset:2048
	ds_read_b128 v[172:175], v163 offset:3072
	v_add_u32_e32 v163, s78, v135
	ds_read_b128 v[176:179], v163
	ds_read_b128 v[180:183], v163 offset:1024
	ds_read_b128 v[184:187], v163 offset:2048
	ds_read_b128 v[188:191], v163 offset:3072
	s_add_u32 s52, s52, 0x40000
	s_addc_u32 s53, s53, 0
	s_mov_b32 m0, s59
	v_lshl_add_u64 v[232:233], s[52:53], 0, v[142:143]
	ds_read_b128 v[192:195], v162 offset:32768
	ds_read_b128 v[196:199], v162 offset:33792
	ds_read_b128 v[200:203], v162 offset:34816
	ds_read_b128 v[204:207], v162 offset:35840
	ds_read_b128 v[208:211], v162 offset:36864
	ds_read_b128 v[212:215], v162 offset:37888
	ds_read_b128 v[216:219], v162 offset:38912
	ds_read_b128 v[220:223], v162 offset:39936
	global_load_lds_dwordx4 v[232:233], off
	v_lshl_add_u64 v[232:233], s[52:53], 0, v[138:139]
	s_mov_b32 m0, s60
	s_nop 0
	global_load_lds_dwordx4 v[232:233], off
	s_waitcnt vmcnt(8)
	s_waitcnt lgkmcnt(0)
	s_barrier
	s_setprio 1
	s_waitcnt lgkmcnt(0)
	s_cmp_eq_u32 s92, 1
	s_cbranch_scc1 .Lms17_b4
	v_mfma_f32_16x16x32_bf16 v[124:127], v[148:151], v[192:195], v[124:127]
	v_mfma_f32_16x16x32_bf16 v[120:123], v[168:171], v[192:195], v[120:123]
	v_mfma_f32_16x16x32_bf16 v[116:119], v[148:151], v[200:203], v[116:119]
	v_mfma_f32_16x16x32_bf16 v[104:107], v[168:171], v[200:203], v[104:107]
	v_mfma_f32_16x16x32_bf16 v[100:103], v[148:151], v[208:211], v[100:103]
	v_mfma_f32_16x16x32_bf16 v[88:91], v[168:171], v[208:211], v[88:91]
	v_mfma_f32_16x16x32_bf16 v[84:87], v[148:151], v[216:219], v[84:87]
	v_mfma_f32_16x16x32_bf16 v[72:75], v[168:171], v[216:219], v[72:75]
	v_mfma_f32_16x16x32_bf16 v[124:127], v[164:167], v[196:199], v[124:127]
	v_mfma_f32_16x16x32_bf16 v[120:123], v[172:175], v[196:199], v[120:123]
	v_mfma_f32_16x16x32_bf16 v[116:119], v[164:167], v[204:207], v[116:119]
	v_mfma_f32_16x16x32_bf16 v[104:107], v[172:175], v[204:207], v[104:107]
	v_mfma_f32_16x16x32_bf16 v[100:103], v[164:167], v[212:215], v[100:103]
	v_mfma_f32_16x16x32_bf16 v[88:91], v[172:175], v[212:215], v[88:91]
	v_mfma_f32_16x16x32_bf16 v[84:87], v[164:167], v[220:223], v[84:87]
	v_mfma_f32_16x16x32_bf16 v[72:75], v[172:175], v[220:223], v[72:75]

; #define PG8_STAGE(bufoff, gbase, voff) do { _Pragma("unroll") for (int _i = 0; _i < 2; ++_i) \
;         __builtin_amdgcn_global_load_lds((const unsigned*)((const char*)(gbase) + (voff)[_i]), (PG8_LAS unsigned*)(lds + (bufoff) + ldsw + _i * 8192), 16, 0, 0); } while (0)
; #define PG8_LDA(dst, b, h) do { _Pragma("unroll") for (int m = 0; m < 4; ++m) _Pragma("unroll") for (int k = 0; k < 2; ++k) dst[m][k] = *(const PG8_LAS bf16x8*)(lds + PG8_SA(b, h) + aoff + m * 2048 + k * 1024); } while (0)
; #define PG8_MMA(ai, bj, At, Bt) do { __builtin_amdgcn_s_setprio(1); _Pragma("unroll") for (int m = 0; m < 4; ++m) _Pragma("unroll") for (int n = 0; n < 2; ++n) _Pragma("unroll") for (int k = 0; k < 2; ++k) \
;         acc[ai][bj][m][n] = __builtin_amdgcn_mfma_f32_16x16x32_bf16(Bt[n][k], At[m][k], acc[ai][bj][m][n], 0, 0, 0); __builtin_amdgcn_s_setprio(0); } while (0)
; #define PG8_WAIT_V(n) asm volatile("s_waitcnt vmcnt(" #n ")" ::: "memory")
; #define PG8_WAIT_L(n) asm volatile("s_waitcnt lgkmcnt(" #n ")" ::: "memory")
; #define PG8_BAR __builtin_amdgcn_s_barrier()
; #define PG8_SCHED __builtin_amdgcn_sched_barrier(0)
; template <class Epi, class Sched, bool ALIGN_EPI = false, bool SP2 = false>
; __device__ __forceinline__ void gemm_phase(PG8_LAS unsigned char* lds, const Gemm g, const Sched& S, const Epi& E) {
;     ...
;             PG8_LDA(At, 1, 1); PG8_STAGE(PG8_SB(1, 0), b3, voffB); PG8_STAGE(PG8_SB(1, 1), b3 + hstep, voffB); PG8_STAGE(PG8_SA(1, 0), a3, voffA);
;             PG8_WAIT_V(8); PG8_WAIT_L(0); PG8_BAR; PG8_MMA(1, 0, At, B0); PG8_MMA(1, 1, At, B1); PG8_BAR; PG8_SCHED;
.Lms17_b5:
	s_setprio 0
	s_barrier
	s_add_i32 s52, s77, s58
	v_lshl_add_u64 v[224:225], v[224:225], 0, s[10:11]
	s_mov_b32 m0, s52
	ds_read_b128 v[192:195], v162 offset:49152
	ds_read_b128 v[196:199], v162 offset:50176
	ds_read_b128 v[200:203], v162 offset:51200
	ds_read_b128 v[204:207], v162 offset:52224
	ds_read_b128 v[208:211], v162 offset:53248
	ds_read_b128 v[212:215], v162 offset:54272
	ds_read_b128 v[216:219], v162 offset:55296
	ds_read_b128 v[220:223], v162 offset:56320
	global_load_lds_dwordx4 v[224:225], off
	s_add_i32 m0, s52, 0x2000
	s_add_u32 s50, s50, 0x40080
	v_lshl_add_u64 v[224:225], v[226:227], 0, s[10:11]
	s_addc_u32 s51, s51, 0
	s_add_i32 s52, s78, s58
	global_load_lds_dwordx4 v[224:225], off
	v_lshl_add_u64 v[224:225], s[50:51], 0, v[140:141]
	s_mov_b32 m0, s52
	s_nop 0
	global_load_lds_dwordx4 v[224:225], off
	v_lshl_add_u64 v[224:225], s[50:51], 0, v[136:137]
	s_add_i32 m0, s52, 0x2000
	s_nop 0
	global_load_lds_dwordx4 v[224:225], off
	v_lshl_add_u64 v[224:225], v[228:229], 0, s[10:11]
	s_mov_b32 m0, s62
	s_nop 0
	global_load_lds_dwordx4 v[224:225], off
	v_lshl_add_u64 v[224:225], v[230:231], 0, s[10:11]
	s_mov_b32 m0, s63
	s_nop 0
	global_load_lds_dwordx4 v[224:225], off
	s_waitcnt vmcnt(8)
	s_waitcnt lgkmcnt(0)
	s_barrier
	s_setprio 1
	s_waitcnt lgkmcnt(0)
	s_cmp_eq_u32 s92, 0
	s_cbranch_scc1 .Lms17_b6
	v_mfma_f32_16x16x32_bf16 v[60:63], v[148:151], v[192:195], v[60:63]
	v_mfma_f32_16x16x32_bf16 v[56:59], v[168:171], v[192:195], v[56:59]
	v_mfma_f32_16x16x32_bf16 v[52:55], v[148:151], v[200:203], v[52:55]
	v_mfma_f32_16x16x32_bf16 v[40:43], v[168:171], v[200:203], v[40:43]
	v_mfma_f32_16x16x32_bf16 v[36:39], v[148:151], v[208:211], v[36:39]
	v_mfma_f32_16x16x32_bf16 v[24:27], v[168:171], v[208:211], v[24:27]
	v_mfma_f32_16x16x32_bf16 v[20:23], v[148:151], v[216:219], v[20:23]
	v_mfma_f32_16x16x32_bf16 v[8:11], v[168:171], v[216:219], v[8:11]
	v_mfma_f32_16x16x32_bf16 v[60:63], v[164:167], v[196:199], v[60:63]
	v_mfma_f32_16x16x32_bf16 v[56:59], v[172:175], v[196:199], v[56:59]
	v_mfma_f32_16x16x32_bf16 v[52:55], v[164:167], v[204:207], v[52:55]
	v_mfma_f32_16x16x32_bf16 v[40:43], v[172:175], v[204:207], v[40:43]
	v_mfma_f32_16x16x32_bf16 v[36:39], v[164:167], v[212:215], v[36:39]
	v_mfma_f32_16x16x32_bf16 v[24:27], v[172:175], v[212:215], v[24:27]
	v_mfma_f32_16x16x32_bf16 v[20:23], v[164:167], v[220:223], v[20:23]
	v_mfma_f32_16x16x32_bf16 v[8:11], v[172:175], v[220:223], v[8:11]

; #define PG8_BAR __builtin_amdgcn_s_barrier()
; template <class Epi, class Sched, bool ALIGN_EPI = false, bool SP2 = false>
; __device__ __forceinline__ void gemm_phase(PG8_LAS unsigned char* lds, const Gemm g, const Sched& S, const Epi& E) {
;     ...
;         if constexpr (ALIGN_EPI) { if (wr == 0) PG8_BAR; }
;         if constexpr (!Epi::AFTER_DRAIN) { E(acc, cur, wr, wc, fr, fq); S.done(cur); }
;     __device__ __forceinline__ void operator()(const pg8::Unit& u, int rl, int cl, f32x4 v0, f32x4 v1) const {
;         const int b = u.pm / 17, j = u.pm - 17 * b, col = u.pn * 256 + cl;
;         const float* src; float* dst; const float* gate;
;         if (j == 0) { const size_t off = (size_t)(b * CTXL + rl) * D + col; src = co + off; dst = cn + off; gate = modl + 4 * 3072 + 2048 + col; }
;         else { const size_t off = (size_t)(b * SEQ + (j - 1) * 256 + rl) * D + col; src = xo + off; dst = xn + off; gate = modl + b * 3072 + 2048 + col; }
;         const f32x4 a0 = *(const f32x4*)src, a1 = *(const f32x4*)(src + 4), g0 = *(const f32x4*)gate, g1 = *(const f32x4*)(gate + 4);
;         *(f32x4*)dst = a0 + g0 * v0; *(f32x4*)(dst + 4) = a1 + g1 * v1;
.Lms17_b7:
	s_setprio 0
	s_barrier
	s_add_i32 s76, s76, 2
	s_add_u32 s48, s48, 0x100
	s_addc_u32 s49, s49, 0
	s_add_u32 s74, s74, 0x100
	s_addc_u32 s75, s75, 0
	s_cmp_gt_u32 s76, 13
	s_cbranch_scc0 .LBB0_1957
	s_and_b64 vcc, exec, s[16:17]
	s_cbranch_vccz .LBB0_1960
	s_barrier
.LBB0_1960:
	s_mul_hi_i32 s19, s44, 0x78787879
	s_lshr_b32 s21, s19, 31
	s_ashr_i32 s19, s19, 3
	s_add_i32 s21, s19, s21
	s_mul_i32 s19, s21, 0xffffffef
	s_add_i32 s44, s19, s44
	v_lshl_or_b32 v148, s46, 8, v159
	s_lshl_b32 s19, s21, 12
	s_lshl_b32 s46, s44, 8
	s_mul_i32 s48, s21, 0xc00
	s_add_i32 s19, s19, s46
	s_ashr_i32 s49, s48, 31
	s_addk_i32 s19, 0xff00
	s_lshl_b32 s21, s21, 8
	s_lshl_b64 s[48:49], s[48:49], 2
	s_add_u32 s46, s26, s48
	s_addc_u32 s48, s27, s49
	s_add_u32 s46, s46, 0x20000
	s_addc_u32 s50, s48, 0
	v_add_u32_e32 v150, s19, v133
	v_add_u32_e32 v164, s21, v133
	s_cmp_eq_u32 s44, 0
	v_ashrrev_i32_e32 v151, 31, v150
	v_ashrrev_i32_e32 v165, 31, v164
	v_lshlrev_b64 v[164:165], 12, v[164:165]
	v_lshlrev_b64 v[150:151], 12, v[150:151]
	s_cselect_b64 vcc, -1, 0
	v_ashrrev_i32_e32 v149, 31, v148
	v_lshl_add_u64 v[164:165], s[8:9], 0, v[164:165]
	v_lshl_add_u64 v[150:151], s[14:15], 0, v[150:151]
	s_and_b64 s[48:49], vcc, exec
	v_cndmask_b32_e32 v165, v151, v165, vcc
	s_cselect_b32 s49, s65, s50
	s_cselect_b32 s48, s64, s46
	v_cndmask_b32_e32 v164, v150, v164, vcc
	v_lshlrev_b64 v[150:151], 2, v[148:149]
	v_lshl_add_u64 v[148:149], s[48:49], 0, v[150:151]
	v_lshl_add_u64 v[180:181], v[164:165], 0, v[150:151]
	global_load_dwordx4 v[164:167], v[148:149], off
	global_load_dwordx4 v[168:171], v[148:149], off offset:16
	global_load_dwordx4 v[176:179], v[148:149], off offset:512
	global_load_dwordx4 v[182:185], v[148:149], off offset:528
	v_add_u32_e32 v220, s21, v152
	v_add_u32_e32 v222, s19, v152
	v_ashrrev_i32_e32 v221, 31, v220
	v_ashrrev_i32_e32 v223, 31, v222
	v_lshlrev_b64 v[220:221], 12, v[220:221]
	v_lshlrev_b64 v[222:223], 12, v[222:223]
	v_lshl_add_u64 v[220:221], s[8:9], 0, v[220:221]
	v_lshl_add_u64 v[222:223], s[14:15], 0, v[222:223]
	v_cndmask_b32_e32 v221, v223, v221, vcc
	v_cndmask_b32_e32 v220, v222, v220, vcc
	v_lshl_add_u64 v[220:221], v[220:221], 0, v[150:151]
	global_load_dwordx4 v[186:189], v[180:181], off
	global_load_dwordx4 v[190:193], v[180:181], off offset:16
	global_load_dwordx4 v[194:197], v[180:181], off offset:512
	global_load_dwordx4 v[198:201], v[180:181], off offset:528
	global_load_dwordx4 v[202:205], v[220:221], off
	global_load_dwordx4 v[206:209], v[220:221], off offset:16
	global_load_dwordx4 v[210:213], v[220:221], off offset:512
	global_load_dwordx4 v[214:217], v[220:221], off offset:528
	s_waitcnt vmcnt(0)
	v_pk_fma_f32 v[186:187], v[124:125], v[164:165], v[186:187]
	v_pk_fma_f32 v[188:189], v[126:127], v[166:167], v[188:189]
	v_pk_fma_f32 v[190:191], v[120:121], v[168:169], v[190:191]
	v_pk_fma_f32 v[192:193], v[122:123], v[170:171], v[192:193]
	v_pk_fma_f32 v[194:195], v[112:113], v[176:177], v[194:195]
	v_pk_fma_f32 v[196:197], v[114:115], v[178:179], v[196:197]
	v_pk_fma_f32 v[198:199], v[108:109], v[182:183], v[198:199]
	v_pk_fma_f32 v[200:201], v[110:111], v[184:185], v[200:201]
	v_pk_fma_f32 v[202:203], v[116:117], v[164:165], v[202:203]
	v_pk_fma_f32 v[204:205], v[118:119], v[166:167], v[204:205]
	v_pk_fma_f32 v[206:207], v[104:105], v[168:169], v[206:207]
	v_pk_fma_f32 v[208:209], v[106:107], v[170:171], v[208:209]
	v_pk_fma_f32 v[210:211], v[96:97], v[176:177], v[210:211]
	v_pk_fma_f32 v[212:213], v[98:99], v[178:179], v[212:213]
	v_pk_fma_f32 v[214:215], v[92:93], v[182:183], v[214:215]
	v_pk_fma_f32 v[216:217], v[94:95], v[184:185], v[216:217]
	s_mov_b64 exec, s[88:89]
	global_store_dwordx4 v[180:181], v[186:189], off
	s_mov_b64 exec, -1
	s_mov_b64 exec, s[88:89]
	global_store_dwordx4 v[180:181], v[190:193], off offset:16
	s_mov_b64 exec, -1
	s_mov_b64 exec, s[88:89]
	global_store_dwordx4 v[180:181], v[194:197], off offset:512
	s_mov_b64 exec, -1
	s_mov_b64 exec, s[88:89]
	global_store_dwordx4 v[180:181], v[198:201], off offset:528
	s_mov_b64 exec, -1
	s_mov_b64 exec, s[88:89]
	global_store_dwordx4 v[220:221], v[202:205], off
	s_mov_b64 exec, -1
	s_mov_b64 exec, s[88:89]
	global_store_dwordx4 v[220:221], v[206:209], off offset:16
	s_mov_b64 exec, -1
	s_mov_b64 exec, s[88:89]
	global_store_dwordx4 v[220:221], v[210:213], off offset:512
	s_mov_b64 exec, -1
	s_mov_b64 exec, s[88:89]
	global_store_dwordx4 v[220:221], v[214:217], off offset:528
	s_mov_b64 exec, -1
	s_nop 1
	v_add_u32_e32 v218, s21, v153
	v_add_u32_e32 v222, s19, v153
	v_ashrrev_i32_e32 v219, 31, v218
	v_ashrrev_i32_e32 v223, 31, v222
	v_lshlrev_b64 v[218:219], 12, v[218:219]
	v_lshlrev_b64 v[222:223], 12, v[222:223]
	v_lshl_add_u64 v[218:219], s[8:9], 0, v[218:219]
	v_lshl_add_u64 v[222:223], s[14:15], 0, v[222:223]
	v_cndmask_b32_e32 v219, v223, v219, vcc
	v_cndmask_b32_e32 v218, v222, v218, vcc
	v_lshl_add_u64 v[218:219], v[218:219], 0, v[150:151]
	v_add_u32_e32 v220, s21, v154
	v_add_u32_e32 v222, s19, v154
	v_ashrrev_i32_e32 v221, 31, v220
	v_ashrrev_i32_e32 v223, 31, v222
	v_lshlrev_b64 v[220:221], 12, v[220:221]
	v_lshlrev_b64 v[222:223], 12, v[222:223]
	v_lshl_add_u64 v[220:221], s[8:9], 0, v[220:221]
	v_lshl_add_u64 v[222:223], s[14:15], 0, v[222:223]
	v_cndmask_b32_e32 v221, v223, v221, vcc
	v_cndmask_b32_e32 v220, v222, v220, vcc
	v_lshl_add_u64 v[220:221], v[220:221], 0, v[150:151]
	global_load_dwordx4 v[186:189], v[218:219], off
	global_load_dwordx4 v[190:193], v[218:219], off offset:16
	global_load_dwordx4 v[194:197], v[218:219], off offset:512
	global_load_dwordx4 v[198:201], v[218:219], off offset:528
	global_load_dwordx4 v[202:205], v[220:221], off
	global_load_dwordx4 v[206:209], v[220:221], off offset:16
	global_load_dwordx4 v[210:213], v[220:221], off offset:512
	global_load_dwordx4 v[214:217], v[220:221], off offset:528
	s_waitcnt vmcnt(0)
;     __device__ __forceinline__ void operator()(const pg8::Unit& u, int rl, int cl, f32x4 v0, f32x4 v1) const {
;         const int b = u.pm / 17, j = u.pm - 17 * b, col = u.pn * 256 + cl;
;         const float* src; float* dst; const float* gate;
;         if (j == 0) { const size_t off = (size_t)(b * CTXL + rl) * D + col; src = co + off; dst = cn + off; gate = modl + 4 * 3072 + 2048 + col; }
;         else { const size_t off = (size_t)(b * SEQ + (j - 1) * 256 + rl) * D + col; src = xo + off; dst = xn + off; gate = modl + b * 3072 + 2048 + col; }
;         const f32x4 a0 = *(const f32x4*)src, a1 = *(const f32x4*)(src + 4), g0 = *(const f32x4*)gate, g1 = *(const f32x4*)(gate + 4);
;         *(f32x4*)dst = a0 + g0 * v0; *(f32x4*)(dst + 4) = a1 + g1 * v1;
	v_pk_fma_f32 v[186:187], v[100:101], v[164:165], v[186:187]
	v_pk_fma_f32 v[188:189], v[102:103], v[166:167], v[188:189]
	v_pk_fma_f32 v[190:191], v[88:89], v[168:169], v[190:191]
	v_pk_fma_f32 v[192:193], v[90:91], v[170:171], v[192:193]
	v_pk_fma_f32 v[194:195], v[80:81], v[176:177], v[194:195]
	v_pk_fma_f32 v[196:197], v[82:83], v[178:179], v[196:197]
	v_pk_fma_f32 v[198:199], v[76:77], v[182:183], v[198:199]
	v_pk_fma_f32 v[200:201], v[78:79], v[184:185], v[200:201]
	v_pk_fma_f32 v[202:203], v[84:85], v[164:165], v[202:203]
	v_pk_fma_f32 v[204:205], v[86:87], v[166:167], v[204:205]
	v_pk_fma_f32 v[206:207], v[72:73], v[168:169], v[206:207]
	v_pk_fma_f32 v[208:209], v[74:75], v[170:171], v[208:209]
	v_pk_fma_f32 v[210:211], v[68:69], v[176:177], v[210:211]
	v_pk_fma_f32 v[212:213], v[70:71], v[178:179], v[212:213]
	v_pk_fma_f32 v[214:215], v[64:65], v[182:183], v[214:215]
	v_pk_fma_f32 v[216:217], v[66:67], v[184:185], v[216:217]
	s_mov_b64 exec, s[88:89]
	global_store_dwordx4 v[218:219], v[186:189], off
	s_mov_b64 exec, -1
	s_mov_b64 exec, s[88:89]
	global_store_dwordx4 v[218:219], v[190:193], off offset:16
	s_mov_b64 exec, -1
	s_mov_b64 exec, s[88:89]
	global_store_dwordx4 v[218:219], v[194:197], off offset:512
	s_mov_b64 exec, -1
	s_mov_b64 exec, s[88:89]
	global_store_dwordx4 v[218:219], v[198:201], off offset:528
	s_mov_b64 exec, -1
	s_mov_b64 exec, s[88:89]
	global_store_dwordx4 v[220:221], v[202:205], off
	s_mov_b64 exec, -1
	s_mov_b64 exec, s[88:89]
	global_store_dwordx4 v[220:221], v[206:209], off offset:16
	s_mov_b64 exec, -1
	s_mov_b64 exec, s[88:89]
	global_store_dwordx4 v[220:221], v[210:213], off offset:512
	s_mov_b64 exec, -1
	s_mov_b64 exec, s[88:89]
	global_store_dwordx4 v[220:221], v[214:217], off offset:528
	s_mov_b64 exec, -1
	s_nop 1
	v_add_u32_e32 v218, s21, v155
	v_add_u32_e32 v222, s19, v155
	v_ashrrev_i32_e32 v219, 31, v218
	v_ashrrev_i32_e32 v223, 31, v222
	v_lshlrev_b64 v[218:219], 12, v[218:219]
	v_lshlrev_b64 v[222:223], 12, v[222:223]
	v_lshl_add_u64 v[218:219], s[8:9], 0, v[218:219]
	v_lshl_add_u64 v[222:223], s[14:15], 0, v[222:223]
	v_cndmask_b32_e32 v219, v223, v219, vcc
	v_cndmask_b32_e32 v218, v222, v218, vcc
	v_lshl_add_u64 v[218:219], v[218:219], 0, v[150:151]
	v_add_u32_e32 v220, s21, v156
	v_add_u32_e32 v222, s19, v156
	v_ashrrev_i32_e32 v221, 31, v220
	v_ashrrev_i32_e32 v223, 31, v222
	v_lshlrev_b64 v[220:221], 12, v[220:221]
	v_lshlrev_b64 v[222:223], 12, v[222:223]
	v_lshl_add_u64 v[220:221], s[8:9], 0, v[220:221]
	v_lshl_add_u64 v[222:223], s[14:15], 0, v[222:223]
	v_cndmask_b32_e32 v221, v223, v221, vcc
	v_cndmask_b32_e32 v220, v222, v220, vcc
	v_lshl_add_u64 v[220:221], v[220:221], 0, v[150:151]
	global_load_dwordx4 v[186:189], v[218:219], off
	global_load_dwordx4 v[190:193], v[218:219], off offset:16
	global_load_dwordx4 v[194:197], v[218:219], off offset:512
	global_load_dwordx4 v[198:201], v[218:219], off offset:528
	global_load_dwordx4 v[202:205], v[220:221], off
	global_load_dwordx4 v[206:209], v[220:221], off offset:16
	global_load_dwordx4 v[210:213], v[220:221], off offset:512
	global_load_dwordx4 v[214:217], v[220:221], off offset:528
	s_waitcnt vmcnt(0)
;     __device__ __forceinline__ void operator()(const pg8::Unit& u, int rl, int cl, f32x4 v0, f32x4 v1) const {
;         const int b = u.pm / 17, j = u.pm - 17 * b, col = u.pn * 256 + cl;
;         const float* src; float* dst; const float* gate;
;         if (j == 0) { const size_t off = (size_t)(b * CTXL + rl) * D + col; src = co + off; dst = cn + off; gate = modl + 4 * 3072 + 2048 + col; }
;         else { const size_t off = (size_t)(b * SEQ + (j - 1) * 256 + rl) * D + col; src = xo + off; dst = xn + off; gate = modl + b * 3072 + 2048 + col; }
;         const f32x4 a0 = *(const f32x4*)src, a1 = *(const f32x4*)(src + 4), g0 = *(const f32x4*)gate, g1 = *(const f32x4*)(gate + 4);
;         *(f32x4*)dst = a0 + g0 * v0; *(f32x4*)(dst + 4) = a1 + g1 * v1;
	v_pk_fma_f32 v[186:187], v[60:61], v[164:165], v[186:187]
	v_pk_fma_f32 v[188:189], v[62:63], v[166:167], v[188:189]
	v_pk_fma_f32 v[190:191], v[56:57], v[168:169], v[190:191]
	v_pk_fma_f32 v[192:193], v[58:59], v[170:171], v[192:193]
	v_pk_fma_f32 v[194:195], v[48:49], v[176:177], v[194:195]
	v_pk_fma_f32 v[196:197], v[50:51], v[178:179], v[196:197]
	v_pk_fma_f32 v[198:199], v[44:45], v[182:183], v[198:199]
	v_pk_fma_f32 v[200:201], v[46:47], v[184:185], v[200:201]
	v_pk_fma_f32 v[202:203], v[52:53], v[164:165], v[202:203]
	v_pk_fma_f32 v[204:205], v[54:55], v[166:167], v[204:205]
	v_pk_fma_f32 v[206:207], v[40:41], v[168:169], v[206:207]
	v_pk_fma_f32 v[208:209], v[42:43], v[170:171], v[208:209]
	v_pk_fma_f32 v[210:211], v[32:33], v[176:177], v[210:211]
	v_pk_fma_f32 v[212:213], v[34:35], v[178:179], v[212:213]
	v_pk_fma_f32 v[214:215], v[28:29], v[182:183], v[214:215]
	v_pk_fma_f32 v[216:217], v[30:31], v[184:185], v[216:217]
	s_mov_b64 exec, s[90:91]
	global_store_dwordx4 v[218:219], v[186:189], off
	s_mov_b64 exec, -1
	s_mov_b64 exec, s[90:91]
	global_store_dwordx4 v[218:219], v[190:193], off offset:16
	s_mov_b64 exec, -1
	s_mov_b64 exec, s[90:91]
	global_store_dwordx4 v[218:219], v[194:197], off offset:512
	s_mov_b64 exec, -1
	s_mov_b64 exec, s[90:91]
	global_store_dwordx4 v[218:219], v[198:201], off offset:528
	s_mov_b64 exec, -1
	s_mov_b64 exec, s[90:91]
	global_store_dwordx4 v[220:221], v[202:205], off
	s_mov_b64 exec, -1
	s_mov_b64 exec, s[90:91]
	global_store_dwordx4 v[220:221], v[206:209], off offset:16
	s_mov_b64 exec, -1
	s_mov_b64 exec, s[90:91]
	global_store_dwordx4 v[220:221], v[210:213], off offset:512
	s_mov_b64 exec, -1
	s_mov_b64 exec, s[90:91]
	global_store_dwordx4 v[220:221], v[214:217], off offset:528
	s_mov_b64 exec, -1
	s_nop 1
	v_add_u32_e32 v218, s21, v157
	v_add_u32_e32 v222, s19, v157
	v_ashrrev_i32_e32 v219, 31, v218
	v_ashrrev_i32_e32 v223, 31, v222
	v_lshlrev_b64 v[218:219], 12, v[218:219]
	v_lshlrev_b64 v[222:223], 12, v[222:223]
	v_lshl_add_u64 v[218:219], s[8:9], 0, v[218:219]
	v_lshl_add_u64 v[222:223], s[14:15], 0, v[222:223]
	v_cndmask_b32_e32 v219, v223, v219, vcc
	v_cndmask_b32_e32 v218, v222, v218, vcc
	v_lshl_add_u64 v[218:219], v[218:219], 0, v[150:151]
	v_add_u32_e32 v220, s21, v158
	v_add_u32_e32 v222, s19, v158
	v_ashrrev_i32_e32 v221, 31, v220
	v_ashrrev_i32_e32 v223, 31, v222
	v_lshlrev_b64 v[220:221], 12, v[220:221]
	v_lshlrev_b64 v[222:223], 12, v[222:223]
	v_lshl_add_u64 v[220:221], s[8:9], 0, v[220:221]
	v_lshl_add_u64 v[222:223], s[14:15], 0, v[222:223]
	v_cndmask_b32_e32 v221, v223, v221, vcc
	v_cndmask_b32_e32 v220, v222, v220, vcc
	v_lshl_add_u64 v[220:221], v[220:221], 0, v[150:151]
	global_load_dwordx4 v[186:189], v[218:219], off
	global_load_dwordx4 v[190:193], v[218:219], off offset:16
	global_load_dwordx4 v[194:197], v[218:219], off offset:512
	global_load_dwordx4 v[198:201], v[218:219], off offset:528
	global_load_dwordx4 v[202:205], v[220:221], off
	global_load_dwordx4 v[206:209], v[220:221], off offset:16
	global_load_dwordx4 v[210:213], v[220:221], off offset:512
	global_load_dwordx4 v[214:217], v[220:221], off offset:528
	s_waitcnt vmcnt(0)
	v_pk_fma_f32 v[186:187], v[36:37], v[164:165], v[186:187]
	v_pk_fma_f32 v[188:189], v[38:39], v[166:167], v[188:189]
	v_pk_fma_f32 v[190:191], v[24:25], v[168:169], v[190:191]
	v_pk_fma_f32 v[192:193], v[26:27], v[170:171], v[192:193]
	v_pk_fma_f32 v[194:195], v[16:17], v[176:177], v[194:195]
	v_pk_fma_f32 v[196:197], v[18:19], v[178:179], v[196:197]
	v_pk_fma_f32 v[198:199], v[12:13], v[182:183], v[198:199]
	v_pk_fma_f32 v[200:201], v[14:15], v[184:185], v[200:201]
	v_pk_fma_f32 v[202:203], v[20:21], v[164:165], v[202:203]
	v_pk_fma_f32 v[204:205], v[22:23], v[166:167], v[204:205]
	v_pk_fma_f32 v[206:207], v[8:9], v[168:169], v[206:207]
	v_pk_fma_f32 v[208:209], v[10:11], v[170:171], v[208:209]
	v_pk_fma_f32 v[210:211], v[4:5], v[176:177], v[210:211]
	v_pk_fma_f32 v[212:213], v[6:7], v[178:179], v[212:213]
	v_pk_fma_f32 v[214:215], v[0:1], v[182:183], v[214:215]
	v_pk_fma_f32 v[216:217], v[2:3], v[184:185], v[216:217]
	s_mov_b64 exec, s[90:91]
	global_store_dwordx4 v[218:219], v[186:189], off
	s_mov_b64 exec, -1
	s_mov_b64 exec, s[90:91]
	global_store_dwordx4 v[218:219], v[190:193], off offset:16
	s_mov_b64 exec, -1
	s_mov_b64 exec, s[90:91]
	global_store_dwordx4 v[218:219], v[194:197], off offset:512
	s_mov_b64 exec, -1
	s_mov_b64 exec, s[90:91]
	global_store_dwordx4 v[218:219], v[198:201], off offset:528
	s_mov_b64 exec, -1
	s_mov_b64 exec, s[90:91]
	global_store_dwordx4 v[220:221], v[202:205], off
	s_mov_b64 exec, -1
	s_mov_b64 exec, s[90:91]
	global_store_dwordx4 v[220:221], v[206:209], off offset:16
	s_mov_b64 exec, -1
	s_mov_b64 exec, s[90:91]
	global_store_dwordx4 v[220:221], v[210:213], off offset:512
	s_mov_b64 exec, -1
	s_mov_b64 exec, s[90:91]
	global_store_dwordx4 v[220:221], v[214:217], off offset:528
	s_mov_b64 exec, -1
	s_nop 1
	s_andn2_b64 vcc, exec, s[24:25]
	s_mov_b64 s[24:25], -1
	s_cbranch_vccnz .LBB0_1953
	s_andn2_b64 vcc, exec, s[6:7]
	s_cbranch_vccnz .LBB0_1952
	s_barrier
	s_branch .LBB0_1952
